# static priority raise for the younger half: all per-burst s_setprio pairs in the GEMM loops deleted, waves 4..7 at s_setprio 1 from entry (0 inside P7)
# baseline (speedup 1.0000x reference)
; #define LAS __attribute__((address_space(3)))
; __device__ __forceinline__ unsigned xb_add(unsigned* p, unsigned v) { return __hip_atomic_fetch_add(p, v, __ATOMIC_RELAXED, __HIP_MEMORY_SCOPE_AGENT); }
; __device__ __forceinline__ unsigned xb_xcc_id() { return (unsigned)__builtin_amdgcn_s_getreg((3 << 11) | 20) & 0xFu; }
; __global__ void __launch_bounds__(NTHR, 2) mega(Args args) {
;     extern __shared__ __attribute__((aligned(16))) unsigned char lds_raw[];
;     LAS unsigned char* lds = (LAS unsigned char*)lds_raw;
;     cg::grid_group grid = cg::this_grid();
;     const int G = gridDim.x, bx = blockIdx.x;
;     const int lo = args.ph_lo, hi = args.ph_hi;
;     unsigned* const bar = (unsigned*)args.ws;
;     volatile LAS unsigned* const bst = (volatile LAS unsigned*)(lds + 131072 + 64);
;     if (threadIdx.x < 2) bst[threadIdx.x] = 0u;
;     if (threadIdx.x == 0) (void)xb_add(&bar[XB_XCNT(xb_xcc_id())], 1u);
_Z4mega4Args:
	s_load_dwordx2 s[34:35], s[0:1], 0x140
	s_load_dword s33, s[0:1], 0x150
	s_add_u32 s4, s0, 0x150
	v_and_b32_e32 v202, 0x3ff, v0
	s_mov_b32 s81, s2
	s_addc_u32 s5, s1, 0
	v_readfirstlane_b32 s98, v202
	s_nop 3
	s_bfe_u32 s98, s98, 0x40006
	s_cmp_ge_u32 s98, 4
	s_cbranch_scc0 .Lprio_static_a
	s_setprio 1
.Lprio_static_a:
	v_cmp_gt_u32_e32 vcc, 2, v202
	s_and_saveexec_b64 s[2:3], vcc
	v_lshl_add_u32 v1, v202, 2, 0
	v_add_u32_e32 v1, 0x20040, v1
	v_mov_b32_e32 v2, 0
	ds_write_b32 v1, v2
	s_or_b64 exec, exec, s[2:3]
	v_cmp_eq_u32_e64 s[94:95], 0, v202
	s_and_saveexec_b64 s[2:3], s[94:95]
	s_cbranch_execz .LBB0_5
	s_mov_b64 s[6:7], exec
	v_mbcnt_lo_u32_b32 v1, s6, 0
	v_mbcnt_hi_u32_b32 v1, s7, v1
	v_cmp_eq_u32_e32 vcc, 0, v1
	s_getreg_b32 s8, hwreg(HW_REG_XCC_ID, 0, 4)
	s_and_b64 s[10:11], exec, vcc
	s_mov_b64 exec, s[10:11]
	s_cbranch_execz .LBB0_5
	s_lshl_b32 s8, s8, 8
	s_and_b32 s8, s8, 0xf00
	s_bcnt1_i32_b64 s6, s[6:7]
	v_mov_b32_e32 v1, s8
	v_mov_b32_e32 v2, s6
	s_waitcnt lgkmcnt(0)
	global_atomic_add v1, v2, s[34:35] offset:1024

; #define PG8_STAGE(bufoff, gbase, voff) do { _Pragma("unroll") for (int _i = 0; _i < 2; ++_i) \
;         __builtin_amdgcn_global_load_lds((const unsigned*)((const char*)(gbase) + (voff)[_i]), (LAS unsigned*)(lds + (bufoff) + ldsw + _i * 8192), 16, 0, 0); } while (0)
; #define PG8_LDA(dst, b, h) do { _Pragma("unroll") for (int m = 0; m < 4; ++m) _Pragma("unroll") for (int k = 0; k < 2; ++k) dst[m][k] = *(const LAS bf16x8*)(lds + PG8_SA(b, h) + aoff + m * 2048 + k * 1024); } while (0)
; #define PG8_LDB(dst, b, h) do { _Pragma("unroll") for (int n = 0; n < 2; ++n) _Pragma("unroll") for (int k = 0; k < 2; ++k) dst[n][k] = *(const LAS bf16x8*)(lds + PG8_SB(b, h) + boff + n * 2048 + k * 1024); } while (0)
; #define PG8_MMA(ai, bj, At, Bt) do { __builtin_amdgcn_s_setprio(1); _Pragma("unroll") for (int m = 0; m < 4; ++m) _Pragma("unroll") for (int n = 0; n < 2; ++n) _Pragma("unroll") for (int k = 0; k < 2; ++k) \
;         acc[ai][bj][m][n] = __builtin_amdgcn_mfma_f32_16x16x32_bf16(Bt[n][k], At[m][k], acc[ai][bj][m][n], 0, 0, 0); __builtin_amdgcn_s_setprio(0); } while (0)
; #define PG8_WAIT_V(n) asm volatile("s_waitcnt vmcnt(" #n ")" ::: "memory")
; #define PG8_WAIT_L(n) asm volatile("s_waitcnt lgkmcnt(" #n ")" ::: "memory")
; #define PG8_BAR __builtin_amdgcn_s_barrier()
; #define PG8_SCHED __builtin_amdgcn_sched_barrier(0)
; template <class Epi>
; __device__ __forceinline__ void gemm_phase(LAS unsigned char* lds, const Gemm g, const Sched& S, const Epi& E) {
;     ...
;             PG8_LDB(B0, 0, 0); PG8_LDB(B1, 0, 1); PG8_SCHED; PG8_LDA(At, 0, 0); PG8_STAGE(PG8_SA(1, 1), a1 + hstepA, voffA);
;             PG8_WAIT_V(8); PG8_WAIT_L(0); PG8_BAR; PG8_MMA(0, 0, At, B0); PG8_MMA(0, 1, At, B1); PG8_BAR; PG8_SCHED;
;             PG8_LDA(At, 0, 1); PG8_STAGE(PG8_SB(0, 0), b2, voffB); PG8_STAGE(PG8_SB(0, 1), b2 + hstepB, voffB); PG8_STAGE(PG8_SA(0, 0), a2, voffA);
;             PG8_WAIT_V(8); PG8_WAIT_L(0); PG8_BAR; PG8_MMA(1, 0, At, B0); PG8_MMA(1, 1, At, B1); PG8_BAR; PG8_SCHED;
.LBB0_163:
	ds_read_b128 v[148:151], v145
	ds_read_b128 v[152:155], v145 offset:1024
	ds_read_b128 v[156:159], v145 offset:2048
	ds_read_b128 v[160:163], v145 offset:3072
	ds_read_b128 v[164:167], v146
	ds_read_b128 v[168:171], v146 offset:1024
	ds_read_b128 v[172:175], v146 offset:2048
	ds_read_b128 v[176:179], v146 offset:3072
	s_add_u32 s44, s40, 0xfffc0080
	s_addc_u32 s45, s41, -1
	s_cmp_eq_u32 s67, 12
	s_cselect_b32 s47, s21, s45
	s_cselect_b32 s46, s27, s44
	s_cselect_b32 s45, s15, s66
	s_cselect_b32 s44, s64, s65
	v_lshl_add_u64 v[140:141], s[40:41], 0, v[136:137]
	s_add_i32 m0, s29, 0xc000
	ds_read_b128 v[180:183], v147
	ds_read_b128 v[184:187], v147 offset:1024
	ds_read_b128 v[188:191], v147 offset:2048
	ds_read_b128 v[192:195], v147 offset:3072
	ds_read_b128 v[196:199], v147 offset:4096
	ds_read_b128 v[204:207], v147 offset:5120
	ds_read_b128 v[208:211], v147 offset:6144
	ds_read_b128 v[212:215], v147 offset:7168
	global_load_lds_dwordx4 v[140:141], off
	v_lshl_add_u64 v[140:141], s[40:41], 0, v[138:139]
	s_add_i32 m0, s29, 0xe000
	s_nop 0
	global_load_lds_dwordx4 v[140:141], off
	s_waitcnt vmcnt(8)
	s_waitcnt lgkmcnt(0)
	s_barrier
	s_waitcnt lgkmcnt(0)
	v_mfma_f32_16x16x32_bf16 v[116:119], v[148:151], v[180:183], v[116:119]
	v_mfma_f32_16x16x32_bf16 v[124:127], v[156:159], v[180:183], v[124:127]
	v_mfma_f32_16x16x32_bf16 v[100:103], v[148:151], v[188:191], v[100:103]
	v_mfma_f32_16x16x32_bf16 v[108:111], v[156:159], v[188:191], v[108:111]
	v_mfma_f32_16x16x32_bf16 v[84:87], v[148:151], v[196:199], v[84:87]
	v_mfma_f32_16x16x32_bf16 v[92:95], v[156:159], v[196:199], v[92:95]
	v_mfma_f32_16x16x32_bf16 v[68:71], v[148:151], v[208:211], v[68:71]
	v_mfma_f32_16x16x32_bf16 v[76:79], v[156:159], v[208:211], v[76:79]
	v_mfma_f32_16x16x32_bf16 v[116:119], v[152:155], v[184:187], v[116:119]
	v_mfma_f32_16x16x32_bf16 v[124:127], v[160:163], v[184:187], v[124:127]
	v_mfma_f32_16x16x32_bf16 v[100:103], v[152:155], v[192:195], v[100:103]
	v_mfma_f32_16x16x32_bf16 v[108:111], v[160:163], v[192:195], v[108:111]
	v_mfma_f32_16x16x32_bf16 v[84:87], v[152:155], v[204:207], v[84:87]
	v_mfma_f32_16x16x32_bf16 v[92:95], v[160:163], v[204:207], v[92:95]
	v_mfma_f32_16x16x32_bf16 v[68:71], v[152:155], v[212:215], v[68:71]
	v_mfma_f32_16x16x32_bf16 v[76:79], v[160:163], v[212:215], v[76:79]
	v_mfma_f32_16x16x32_bf16 v[112:115], v[164:167], v[180:183], v[112:115]
	v_mfma_f32_16x16x32_bf16 v[120:123], v[172:175], v[180:183], v[120:123]
	v_mfma_f32_16x16x32_bf16 v[96:99], v[164:167], v[188:191], v[96:99]
	v_mfma_f32_16x16x32_bf16 v[104:107], v[172:175], v[188:191], v[104:107]
	v_mfma_f32_16x16x32_bf16 v[80:83], v[164:167], v[196:199], v[80:83]
	v_mfma_f32_16x16x32_bf16 v[88:91], v[172:175], v[196:199], v[88:91]
	v_mfma_f32_16x16x32_bf16 v[64:67], v[164:167], v[208:211], v[64:67]
	v_mfma_f32_16x16x32_bf16 v[72:75], v[172:175], v[208:211], v[72:75]
	v_mfma_f32_16x16x32_bf16 v[112:115], v[168:171], v[184:187], v[112:115]
	v_mfma_f32_16x16x32_bf16 v[120:123], v[176:179], v[184:187], v[120:123]
	v_mfma_f32_16x16x32_bf16 v[96:99], v[168:171], v[192:195], v[96:99]
	v_mfma_f32_16x16x32_bf16 v[104:107], v[176:179], v[192:195], v[104:107]
	v_mfma_f32_16x16x32_bf16 v[80:83], v[168:171], v[204:207], v[80:83]
	v_mfma_f32_16x16x32_bf16 v[88:91], v[176:179], v[204:207], v[88:91]
	v_mfma_f32_16x16x32_bf16 v[64:67], v[168:171], v[212:215], v[64:67]
	v_mfma_f32_16x16x32_bf16 v[72:75], v[176:179], v[212:215], v[72:75]
	s_barrier
	s_add_i32 s78, s60, s53
	v_lshl_add_u64 v[140:141], s[44:45], 0, v[130:131]
	s_mov_b32 m0, s78
	ds_read_b128 v[180:183], v147 offset:16384
	ds_read_b128 v[184:187], v147 offset:17408
	ds_read_b128 v[188:191], v147 offset:18432
	ds_read_b128 v[192:195], v147 offset:19456
	ds_read_b128 v[196:199], v147 offset:20480
	ds_read_b128 v[204:207], v147 offset:21504
	ds_read_b128 v[208:211], v147 offset:22528
	ds_read_b128 v[212:215], v147 offset:23552
	global_load_lds_dwordx4 v[140:141], off
	s_add_i32 m0, s78, 0x2000
	s_add_u32 s78, s44, 0x40000
	v_lshl_add_u64 v[200:201], s[44:45], 0, v[134:135]
	s_addc_u32 s79, s45, 0
	s_add_i32 s82, s61, s53
	global_load_lds_dwordx4 v[200:201], off
	v_lshl_add_u64 v[216:217], s[78:79], 0, v[130:131]
	s_mov_b32 m0, s82
	v_lshl_add_u64 v[218:219], s[46:47], 0, v[132:133]
	global_load_lds_dwordx4 v[216:217], off
	v_lshl_add_u64 v[216:217], s[78:79], 0, v[134:135]
	s_add_i32 m0, s82, 0x2000
	s_nop 0
	global_load_lds_dwordx4 v[216:217], off
	v_lshl_add_u64 v[216:217], s[46:47], 0, v[128:129]
	s_mov_b32 m0, s29
	s_nop 0
	global_load_lds_dwordx4 v[216:217], off
	s_mov_b32 m0, s54
	s_nop 0
	global_load_lds_dwordx4 v[218:219], off
	s_waitcnt vmcnt(8)
	s_waitcnt lgkmcnt(0)
	s_barrier
; #define PG8_STAGE(bufoff, gbase, voff) do { _Pragma("unroll") for (int _i = 0; _i < 2; ++_i) \
;         __builtin_amdgcn_global_load_lds((const unsigned*)((const char*)(gbase) + (voff)[_i]), (LAS unsigned*)(lds + (bufoff) + ldsw + _i * 8192), 16, 0, 0); } while (0)
; #define PG8_LDA(dst, b, h) do { _Pragma("unroll") for (int m = 0; m < 4; ++m) _Pragma("unroll") for (int k = 0; k < 2; ++k) dst[m][k] = *(const LAS bf16x8*)(lds + PG8_SA(b, h) + aoff + m * 2048 + k * 1024); } while (0)
; #define PG8_LDB(dst, b, h) do { _Pragma("unroll") for (int n = 0; n < 2; ++n) _Pragma("unroll") for (int k = 0; k < 2; ++k) dst[n][k] = *(const LAS bf16x8*)(lds + PG8_SB(b, h) + boff + n * 2048 + k * 1024); } while (0)
; #define PG8_MMA(ai, bj, At, Bt) do { __builtin_amdgcn_s_setprio(1); _Pragma("unroll") for (int m = 0; m < 4; ++m) _Pragma("unroll") for (int n = 0; n < 2; ++n) _Pragma("unroll") for (int k = 0; k < 2; ++k) \
;         acc[ai][bj][m][n] = __builtin_amdgcn_mfma_f32_16x16x32_bf16(Bt[n][k], At[m][k], acc[ai][bj][m][n], 0, 0, 0); __builtin_amdgcn_s_setprio(0); } while (0)
; #define PG8_WAIT_V(n) asm volatile("s_waitcnt vmcnt(" #n ")" ::: "memory")
; #define PG8_WAIT_L(n) asm volatile("s_waitcnt lgkmcnt(" #n ")" ::: "memory")
; #define PG8_BAR __builtin_amdgcn_s_barrier()
; #define PG8_SCHED __builtin_amdgcn_sched_barrier(0)
; template <class Epi>
; __device__ __forceinline__ void gemm_phase(LAS unsigned char* lds, const Gemm g, const Sched& S, const Epi& E) {
;     ...
;             PG8_LDA(At, 0, 1); PG8_STAGE(PG8_SB(0, 0), b2, voffB); PG8_STAGE(PG8_SB(0, 1), b2 + hstepB, voffB); PG8_STAGE(PG8_SA(0, 0), a2, voffA);
;             PG8_WAIT_V(8); PG8_WAIT_L(0); PG8_BAR; PG8_MMA(1, 0, At, B0); PG8_MMA(1, 1, At, B1); PG8_BAR; PG8_SCHED;
;             PG8_LDB(B0, 1, 0); PG8_LDB(B1, 1, 1); PG8_SCHED; PG8_LDA(At, 1, 0); PG8_STAGE(PG8_SA(0, 1), a2 + hstepA, voffA);
;             PG8_WAIT_V(8); PG8_WAIT_L(0); PG8_BAR; PG8_MMA(0, 0, At, B0); PG8_MMA(0, 1, At, B1); PG8_BAR; PG8_SCHED;
	s_waitcnt lgkmcnt(0)
	v_mfma_f32_16x16x32_bf16 v[52:55], v[148:151], v[180:183], v[52:55]
	v_mfma_f32_16x16x32_bf16 v[60:63], v[156:159], v[180:183], v[60:63]
	v_mfma_f32_16x16x32_bf16 v[36:39], v[148:151], v[188:191], v[36:39]
	v_mfma_f32_16x16x32_bf16 v[44:47], v[156:159], v[188:191], v[44:47]
	v_mfma_f32_16x16x32_bf16 v[20:23], v[148:151], v[196:199], v[20:23]
	v_mfma_f32_16x16x32_bf16 v[28:31], v[156:159], v[196:199], v[28:31]
	v_mfma_f32_16x16x32_bf16 v[4:7], v[148:151], v[208:211], v[4:7]
	v_mfma_f32_16x16x32_bf16 v[12:15], v[156:159], v[208:211], v[12:15]
	v_mfma_f32_16x16x32_bf16 v[52:55], v[152:155], v[184:187], v[52:55]
	v_mfma_f32_16x16x32_bf16 v[60:63], v[160:163], v[184:187], v[60:63]
	v_mfma_f32_16x16x32_bf16 v[36:39], v[152:155], v[192:195], v[36:39]
	v_mfma_f32_16x16x32_bf16 v[44:47], v[160:163], v[192:195], v[44:47]
	v_mfma_f32_16x16x32_bf16 v[20:23], v[152:155], v[204:207], v[20:23]
	v_mfma_f32_16x16x32_bf16 v[28:31], v[160:163], v[204:207], v[28:31]
	v_mfma_f32_16x16x32_bf16 v[4:7], v[152:155], v[212:215], v[4:7]
	v_mfma_f32_16x16x32_bf16 v[12:15], v[160:163], v[212:215], v[12:15]
	v_mfma_f32_16x16x32_bf16 v[48:51], v[164:167], v[180:183], v[48:51]
	v_mfma_f32_16x16x32_bf16 v[56:59], v[172:175], v[180:183], v[56:59]
	v_mfma_f32_16x16x32_bf16 v[32:35], v[164:167], v[188:191], v[32:35]
	v_mfma_f32_16x16x32_bf16 v[40:43], v[172:175], v[188:191], v[40:43]
	v_mfma_f32_16x16x32_bf16 v[16:19], v[164:167], v[196:199], v[16:19]
	v_mfma_f32_16x16x32_bf16 v[24:27], v[172:175], v[196:199], v[24:27]
	v_mfma_f32_16x16x32_bf16 v[0:3], v[164:167], v[208:211], v[0:3]
	v_mfma_f32_16x16x32_bf16 v[8:11], v[172:175], v[208:211], v[8:11]
	v_mfma_f32_16x16x32_bf16 v[48:51], v[168:171], v[184:187], v[48:51]
	v_mfma_f32_16x16x32_bf16 v[56:59], v[176:179], v[184:187], v[56:59]
	v_mfma_f32_16x16x32_bf16 v[32:35], v[168:171], v[192:195], v[32:35]
	v_mfma_f32_16x16x32_bf16 v[40:43], v[176:179], v[192:195], v[40:43]
	v_mfma_f32_16x16x32_bf16 v[16:19], v[168:171], v[204:207], v[16:19]
	v_mfma_f32_16x16x32_bf16 v[24:27], v[176:179], v[204:207], v[24:27]
	v_mfma_f32_16x16x32_bf16 v[0:3], v[168:171], v[212:215], v[0:3]
	v_mfma_f32_16x16x32_bf16 v[8:11], v[176:179], v[212:215], v[8:11]
	s_barrier
	s_add_i32 s78, 0, 0x18000
	s_add_i32 s79, 0, 0x1c000
	v_add_u32_e32 v160, s78, v143
	v_add_u32_e32 v176, s79, v143
	ds_read_b128 v[148:151], v160
	ds_read_b128 v[152:155], v160 offset:1024
	ds_read_b128 v[156:159], v160 offset:2048
	ds_read_b128 v[160:163], v160 offset:3072
	ds_read_b128 v[164:167], v176
	ds_read_b128 v[168:171], v176 offset:1024
	ds_read_b128 v[172:175], v176 offset:2048
	ds_read_b128 v[176:179], v176 offset:3072
	s_add_u32 s46, s46, 0x40000
	s_addc_u32 s47, s47, 0
	s_mov_b32 m0, s55
	v_lshl_add_u64 v[220:221], s[46:47], 0, v[128:129]
	ds_read_b128 v[180:183], v147 offset:32768
	ds_read_b128 v[184:187], v147 offset:33792
	ds_read_b128 v[188:191], v147 offset:34816
	ds_read_b128 v[192:195], v147 offset:35840
	ds_read_b128 v[196:199], v147 offset:36864
	ds_read_b128 v[204:207], v147 offset:37888
	ds_read_b128 v[208:211], v147 offset:38912
	ds_read_b128 v[212:215], v147 offset:39936
	global_load_lds_dwordx4 v[220:221], off
	v_lshl_add_u64 v[220:221], s[46:47], 0, v[132:133]
	s_mov_b32 m0, s56
	s_nop 0
	global_load_lds_dwordx4 v[220:221], off
	s_waitcnt vmcnt(8)
	s_waitcnt lgkmcnt(0)
	s_barrier
	s_waitcnt lgkmcnt(0)
	v_mfma_f32_16x16x32_bf16 v[116:119], v[148:151], v[180:183], v[116:119]
	v_mfma_f32_16x16x32_bf16 v[124:127], v[156:159], v[180:183], v[124:127]
	v_mfma_f32_16x16x32_bf16 v[100:103], v[148:151], v[188:191], v[100:103]
	v_mfma_f32_16x16x32_bf16 v[108:111], v[156:159], v[188:191], v[108:111]
	v_mfma_f32_16x16x32_bf16 v[84:87], v[148:151], v[196:199], v[84:87]
	v_mfma_f32_16x16x32_bf16 v[92:95], v[156:159], v[196:199], v[92:95]
	v_mfma_f32_16x16x32_bf16 v[68:71], v[148:151], v[208:211], v[68:71]
	v_mfma_f32_16x16x32_bf16 v[76:79], v[156:159], v[208:211], v[76:79]
	v_mfma_f32_16x16x32_bf16 v[116:119], v[152:155], v[184:187], v[116:119]
	v_mfma_f32_16x16x32_bf16 v[124:127], v[160:163], v[184:187], v[124:127]
	v_mfma_f32_16x16x32_bf16 v[100:103], v[152:155], v[192:195], v[100:103]
	v_mfma_f32_16x16x32_bf16 v[108:111], v[160:163], v[192:195], v[108:111]
	v_mfma_f32_16x16x32_bf16 v[84:87], v[152:155], v[204:207], v[84:87]
	v_mfma_f32_16x16x32_bf16 v[92:95], v[160:163], v[204:207], v[92:95]
	v_mfma_f32_16x16x32_bf16 v[68:71], v[152:155], v[212:215], v[68:71]
	v_mfma_f32_16x16x32_bf16 v[76:79], v[160:163], v[212:215], v[76:79]
	v_mfma_f32_16x16x32_bf16 v[112:115], v[164:167], v[180:183], v[112:115]
	v_mfma_f32_16x16x32_bf16 v[120:123], v[172:175], v[180:183], v[120:123]
	v_mfma_f32_16x16x32_bf16 v[96:99], v[164:167], v[188:191], v[96:99]
	v_mfma_f32_16x16x32_bf16 v[104:107], v[172:175], v[188:191], v[104:107]
	v_mfma_f32_16x16x32_bf16 v[80:83], v[164:167], v[196:199], v[80:83]
	v_mfma_f32_16x16x32_bf16 v[88:91], v[172:175], v[196:199], v[88:91]
	v_mfma_f32_16x16x32_bf16 v[64:67], v[164:167], v[208:211], v[64:67]
	v_mfma_f32_16x16x32_bf16 v[72:75], v[172:175], v[208:211], v[72:75]
	v_mfma_f32_16x16x32_bf16 v[112:115], v[168:171], v[184:187], v[112:115]
	v_mfma_f32_16x16x32_bf16 v[120:123], v[176:179], v[184:187], v[120:123]
	v_mfma_f32_16x16x32_bf16 v[96:99], v[168:171], v[192:195], v[96:99]
	v_mfma_f32_16x16x32_bf16 v[104:107], v[176:179], v[192:195], v[104:107]
	v_mfma_f32_16x16x32_bf16 v[80:83], v[168:171], v[204:207], v[80:83]
	v_mfma_f32_16x16x32_bf16 v[88:91], v[176:179], v[204:207], v[88:91]
	v_mfma_f32_16x16x32_bf16 v[64:67], v[168:171], v[212:215], v[64:67]
	v_mfma_f32_16x16x32_bf16 v[72:75], v[176:179], v[212:215], v[72:75]
	s_barrier
; #define PG8_STAGE(bufoff, gbase, voff) do { _Pragma("unroll") for (int _i = 0; _i < 2; ++_i) \
;         __builtin_amdgcn_global_load_lds((const unsigned*)((const char*)(gbase) + (voff)[_i]), (LAS unsigned*)(lds + (bufoff) + ldsw + _i * 8192), 16, 0, 0); } while (0)
; #define PG8_LDA(dst, b, h) do { _Pragma("unroll") for (int m = 0; m < 4; ++m) _Pragma("unroll") for (int k = 0; k < 2; ++k) dst[m][k] = *(const LAS bf16x8*)(lds + PG8_SA(b, h) + aoff + m * 2048 + k * 1024); } while (0)
; #define PG8_LDB(dst, b, h) do { _Pragma("unroll") for (int n = 0; n < 2; ++n) _Pragma("unroll") for (int k = 0; k < 2; ++k) dst[n][k] = *(const LAS bf16x8*)(lds + PG8_SB(b, h) + boff + n * 2048 + k * 1024); } while (0)
; #define PG8_MMA(ai, bj, At, Bt) do { __builtin_amdgcn_s_setprio(1); _Pragma("unroll") for (int m = 0; m < 4; ++m) _Pragma("unroll") for (int n = 0; n < 2; ++n) _Pragma("unroll") for (int k = 0; k < 2; ++k) \
;         acc[ai][bj][m][n] = __builtin_amdgcn_mfma_f32_16x16x32_bf16(Bt[n][k], At[m][k], acc[ai][bj][m][n], 0, 0, 0); __builtin_amdgcn_s_setprio(0); } while (0)
; #define PG8_WAIT_V(n) asm volatile("s_waitcnt vmcnt(" #n ")" ::: "memory")
; #define PG8_WAIT_L(n) asm volatile("s_waitcnt lgkmcnt(" #n ")" ::: "memory")
; #define PG8_BAR __builtin_amdgcn_s_barrier()
; #define PG8_SCHED __builtin_amdgcn_sched_barrier(0)
; template <class Epi>
; __device__ __forceinline__ void gemm_phase(LAS unsigned char* lds, const Gemm g, const Sched& S, const Epi& E) {
;     ...
;             PG8_LDB(B0, 1, 0); PG8_LDB(B1, 1, 1); PG8_SCHED; PG8_LDA(At, 1, 0); PG8_STAGE(PG8_SA(0, 1), a2 + hstepA, voffA);
;             PG8_WAIT_V(8); PG8_WAIT_L(0); PG8_BAR; PG8_MMA(0, 0, At, B0); PG8_MMA(0, 1, At, B1); PG8_BAR; PG8_SCHED;
;             PG8_LDA(At, 1, 1); PG8_STAGE(PG8_SB(1, 0), b3, voffB); PG8_STAGE(PG8_SB(1, 1), b3 + hstepB, voffB); PG8_STAGE(PG8_SA(1, 0), a3, voffA);
;             PG8_WAIT_V(8); PG8_WAIT_L(0); PG8_BAR; PG8_MMA(1, 0, At, B0); PG8_MMA(1, 1, At, B1); PG8_BAR; PG8_SCHED;
;         }
;         if (wr == 0) PG8_BAR;
	s_add_i32 s46, s78, s53
	v_lshl_add_u64 v[140:141], v[140:141], 0, s[4:5]
	s_mov_b32 m0, s46
	ds_read_b128 v[180:183], v147 offset:49152
	ds_read_b128 v[184:187], v147 offset:50176
	ds_read_b128 v[188:191], v147 offset:51200
	ds_read_b128 v[192:195], v147 offset:52224
	ds_read_b128 v[196:199], v147 offset:53248
	ds_read_b128 v[204:207], v147 offset:54272
	ds_read_b128 v[208:211], v147 offset:55296
	ds_read_b128 v[212:215], v147 offset:56320
	global_load_lds_dwordx4 v[140:141], off
	s_add_i32 m0, s46, 0x2000
	s_add_u32 s44, s44, 0x40080
	v_lshl_add_u64 v[140:141], v[200:201], 0, s[4:5]
	s_addc_u32 s45, s45, 0
	s_add_i32 s46, s79, s53
	global_load_lds_dwordx4 v[140:141], off
	v_lshl_add_u64 v[140:141], s[44:45], 0, v[130:131]
	s_mov_b32 m0, s46
	s_nop 0
	global_load_lds_dwordx4 v[140:141], off
	v_lshl_add_u64 v[140:141], s[44:45], 0, v[134:135]
	s_add_i32 m0, s46, 0x2000
	s_nop 0
	global_load_lds_dwordx4 v[140:141], off
	v_lshl_add_u64 v[140:141], v[216:217], 0, s[4:5]
	s_mov_b32 m0, s58
	s_nop 0
	global_load_lds_dwordx4 v[140:141], off
	v_lshl_add_u64 v[140:141], v[218:219], 0, s[4:5]
	s_mov_b32 m0, s59
	s_nop 0
	global_load_lds_dwordx4 v[140:141], off
	s_waitcnt vmcnt(8)
	s_waitcnt lgkmcnt(0)
	s_barrier
	s_waitcnt lgkmcnt(0)
	v_mfma_f32_16x16x32_bf16 v[52:55], v[148:151], v[180:183], v[52:55]
	v_mfma_f32_16x16x32_bf16 v[60:63], v[156:159], v[180:183], v[60:63]
	v_mfma_f32_16x16x32_bf16 v[36:39], v[148:151], v[188:191], v[36:39]
	v_mfma_f32_16x16x32_bf16 v[44:47], v[156:159], v[188:191], v[44:47]
	v_mfma_f32_16x16x32_bf16 v[20:23], v[148:151], v[196:199], v[20:23]
	v_mfma_f32_16x16x32_bf16 v[28:31], v[156:159], v[196:199], v[28:31]
	v_mfma_f32_16x16x32_bf16 v[4:7], v[148:151], v[208:211], v[4:7]
	v_mfma_f32_16x16x32_bf16 v[12:15], v[156:159], v[208:211], v[12:15]
	v_mfma_f32_16x16x32_bf16 v[52:55], v[152:155], v[184:187], v[52:55]
	v_mfma_f32_16x16x32_bf16 v[60:63], v[160:163], v[184:187], v[60:63]
	v_mfma_f32_16x16x32_bf16 v[36:39], v[152:155], v[192:195], v[36:39]
	v_mfma_f32_16x16x32_bf16 v[44:47], v[160:163], v[192:195], v[44:47]
	v_mfma_f32_16x16x32_bf16 v[20:23], v[152:155], v[204:207], v[20:23]
	v_mfma_f32_16x16x32_bf16 v[28:31], v[160:163], v[204:207], v[28:31]
	v_mfma_f32_16x16x32_bf16 v[4:7], v[152:155], v[212:215], v[4:7]
	v_mfma_f32_16x16x32_bf16 v[12:15], v[160:163], v[212:215], v[12:15]
	v_mfma_f32_16x16x32_bf16 v[48:51], v[164:167], v[180:183], v[48:51]
	v_mfma_f32_16x16x32_bf16 v[56:59], v[172:175], v[180:183], v[56:59]
	v_mfma_f32_16x16x32_bf16 v[32:35], v[164:167], v[188:191], v[32:35]
	v_mfma_f32_16x16x32_bf16 v[40:43], v[172:175], v[188:191], v[40:43]
	v_mfma_f32_16x16x32_bf16 v[16:19], v[164:167], v[196:199], v[16:19]
	v_mfma_f32_16x16x32_bf16 v[24:27], v[172:175], v[196:199], v[24:27]
	v_mfma_f32_16x16x32_bf16 v[0:3], v[164:167], v[208:211], v[0:3]
	v_mfma_f32_16x16x32_bf16 v[8:11], v[172:175], v[208:211], v[8:11]
	v_mfma_f32_16x16x32_bf16 v[48:51], v[168:171], v[184:187], v[48:51]
	v_mfma_f32_16x16x32_bf16 v[56:59], v[176:179], v[184:187], v[56:59]
	v_mfma_f32_16x16x32_bf16 v[32:35], v[168:171], v[192:195], v[32:35]
	v_mfma_f32_16x16x32_bf16 v[40:43], v[176:179], v[192:195], v[40:43]
	v_mfma_f32_16x16x32_bf16 v[16:19], v[168:171], v[204:207], v[16:19]
	v_mfma_f32_16x16x32_bf16 v[24:27], v[176:179], v[204:207], v[24:27]
	v_mfma_f32_16x16x32_bf16 v[0:3], v[168:171], v[212:215], v[0:3]
	v_mfma_f32_16x16x32_bf16 v[8:11], v[176:179], v[212:215], v[8:11]
	s_barrier
	s_add_i32 s67, s67, 2
	s_add_u32 s40, s40, 0x100
	s_addc_u32 s41, s41, 0
	s_add_u32 s65, s65, 0x100
	s_addc_u32 s66, s66, 0
	s_cmp_gt_u32 s67, 13
	s_cbranch_scc0 .LBB0_163
	s_and_b64 vcc, exec, s[6:7]
	s_cbranch_vccz .LBB0_166
	s_barrier

; #define PG8_STAGE(bufoff, gbase, voff) do { _Pragma("unroll") for (int _i = 0; _i < 2; ++_i) \
;         __builtin_amdgcn_global_load_lds((const unsigned*)((const char*)(gbase) + (voff)[_i]), (LAS unsigned*)(lds + (bufoff) + ldsw + _i * 8192), 16, 0, 0); } while (0)
; #define PG8_LDA(dst, b, h) do { _Pragma("unroll") for (int m = 0; m < 4; ++m) _Pragma("unroll") for (int k = 0; k < 2; ++k) dst[m][k] = *(const LAS bf16x8*)(lds + PG8_SA(b, h) + aoff + m * 2048 + k * 1024); } while (0)
; #define PG8_LDB(dst, b, h) do { _Pragma("unroll") for (int n = 0; n < 2; ++n) _Pragma("unroll") for (int k = 0; k < 2; ++k) dst[n][k] = *(const LAS bf16x8*)(lds + PG8_SB(b, h) + boff + n * 2048 + k * 1024); } while (0)
; #define PG8_MMA(ai, bj, At, Bt) do { __builtin_amdgcn_s_setprio(1); _Pragma("unroll") for (int m = 0; m < 4; ++m) _Pragma("unroll") for (int n = 0; n < 2; ++n) _Pragma("unroll") for (int k = 0; k < 2; ++k) \
;         acc[ai][bj][m][n] = __builtin_amdgcn_mfma_f32_16x16x32_bf16(Bt[n][k], At[m][k], acc[ai][bj][m][n], 0, 0, 0); __builtin_amdgcn_s_setprio(0); } while (0)
; #define PG8_WAIT_V(n) asm volatile("s_waitcnt vmcnt(" #n ")" ::: "memory")
; #define PG8_WAIT_L(n) asm volatile("s_waitcnt lgkmcnt(" #n ")" ::: "memory")
; #define PG8_BAR __builtin_amdgcn_s_barrier()
; #define PG8_SCHED __builtin_amdgcn_sched_barrier(0)
; template <class Epi>
; __device__ __forceinline__ void gemm_phase(LAS unsigned char* lds, const Gemm g, const Sched& S, const Epi& E) {
;     ...
;             PG8_LDB(B0, 0, 0); PG8_LDB(B1, 0, 1); PG8_SCHED; PG8_LDA(At, 0, 0); PG8_STAGE(PG8_SA(1, 1), a1 + hstepA, voffA);
;             PG8_WAIT_V(8); PG8_WAIT_L(0); PG8_BAR; PG8_MMA(0, 0, At, B0); PG8_MMA(0, 1, At, B1); PG8_BAR; PG8_SCHED;
;             PG8_LDA(At, 0, 1); PG8_STAGE(PG8_SB(0, 0), b2, voffB); PG8_STAGE(PG8_SB(0, 1), b2 + hstepB, voffB); PG8_STAGE(PG8_SA(0, 0), a2, voffA);
;             PG8_WAIT_V(8); PG8_WAIT_L(0); PG8_BAR; PG8_MMA(1, 0, At, B0); PG8_MMA(1, 1, At, B1); PG8_BAR; PG8_SCHED;
.LBB0_205:
	ds_read_b128 v[136:139], v145
	ds_read_b128 v[148:151], v145 offset:1024
	ds_read_b128 v[152:155], v145 offset:2048
	ds_read_b128 v[156:159], v145 offset:3072
	ds_read_b128 v[160:163], v146
	ds_read_b128 v[164:167], v146 offset:1024
	ds_read_b128 v[168:171], v146 offset:2048
	ds_read_b128 v[172:175], v146 offset:3072
	s_add_u32 s44, s40, 0xfffc0080
	s_addc_u32 s45, s41, -1
	s_cmp_eq_u32 s66, 12
	s_cselect_b32 s47, s15, s45
	s_cselect_b32 s46, s27, s44
	s_cselect_b32 s45, s21, s65
	s_cselect_b32 s44, s63, s64
	v_lshl_add_u64 v[140:141], s[40:41], 0, v[132:133]
	s_add_i32 m0, s29, 0xc000
	ds_read_b128 v[176:179], v147
	ds_read_b128 v[180:183], v147 offset:1024
	ds_read_b128 v[184:187], v147 offset:2048
	ds_read_b128 v[188:191], v147 offset:3072
	ds_read_b128 v[192:195], v147 offset:4096
	ds_read_b128 v[196:199], v147 offset:5120
	ds_read_b128 v[204:207], v147 offset:6144
	ds_read_b128 v[208:211], v147 offset:7168
	global_load_lds_dwordx4 v[140:141], off
	v_lshl_add_u64 v[140:141], s[40:41], 0, v[134:135]
	s_add_i32 m0, s29, 0xe000
	s_nop 0
	global_load_lds_dwordx4 v[140:141], off
	s_waitcnt vmcnt(8)
	s_waitcnt lgkmcnt(0)
	s_barrier
	s_waitcnt lgkmcnt(0)
	v_mfma_f32_16x16x32_bf16 v[124:127], v[136:139], v[176:179], v[124:127]
	v_mfma_f32_16x16x32_bf16 v[120:123], v[152:155], v[176:179], v[120:123]
	v_mfma_f32_16x16x32_bf16 v[108:111], v[136:139], v[184:187], v[108:111]
	v_mfma_f32_16x16x32_bf16 v[104:107], v[152:155], v[184:187], v[104:107]
	v_mfma_f32_16x16x32_bf16 v[92:95], v[136:139], v[192:195], v[92:95]
	v_mfma_f32_16x16x32_bf16 v[88:91], v[152:155], v[192:195], v[88:91]
	v_mfma_f32_16x16x32_bf16 v[76:79], v[136:139], v[204:207], v[76:79]
	v_mfma_f32_16x16x32_bf16 v[72:75], v[152:155], v[204:207], v[72:75]
	v_mfma_f32_16x16x32_bf16 v[124:127], v[148:151], v[180:183], v[124:127]
	v_mfma_f32_16x16x32_bf16 v[120:123], v[156:159], v[180:183], v[120:123]
	v_mfma_f32_16x16x32_bf16 v[108:111], v[148:151], v[188:191], v[108:111]
	v_mfma_f32_16x16x32_bf16 v[104:107], v[156:159], v[188:191], v[104:107]
	v_mfma_f32_16x16x32_bf16 v[92:95], v[148:151], v[196:199], v[92:95]
	v_mfma_f32_16x16x32_bf16 v[88:91], v[156:159], v[196:199], v[88:91]
	v_mfma_f32_16x16x32_bf16 v[76:79], v[148:151], v[208:211], v[76:79]
	v_mfma_f32_16x16x32_bf16 v[72:75], v[156:159], v[208:211], v[72:75]
	v_mfma_f32_16x16x32_bf16 v[116:119], v[160:163], v[176:179], v[116:119]
	v_mfma_f32_16x16x32_bf16 v[112:115], v[168:171], v[176:179], v[112:115]
	v_mfma_f32_16x16x32_bf16 v[100:103], v[160:163], v[184:187], v[100:103]
	v_mfma_f32_16x16x32_bf16 v[96:99], v[168:171], v[184:187], v[96:99]
	v_mfma_f32_16x16x32_bf16 v[84:87], v[160:163], v[192:195], v[84:87]
	v_mfma_f32_16x16x32_bf16 v[80:83], v[168:171], v[192:195], v[80:83]
	v_mfma_f32_16x16x32_bf16 v[68:71], v[160:163], v[204:207], v[68:71]
	v_mfma_f32_16x16x32_bf16 v[64:67], v[168:171], v[204:207], v[64:67]
	v_mfma_f32_16x16x32_bf16 v[116:119], v[164:167], v[180:183], v[116:119]
	v_mfma_f32_16x16x32_bf16 v[112:115], v[172:175], v[180:183], v[112:115]
	v_mfma_f32_16x16x32_bf16 v[100:103], v[164:167], v[188:191], v[100:103]
	v_mfma_f32_16x16x32_bf16 v[96:99], v[172:175], v[188:191], v[96:99]
	v_mfma_f32_16x16x32_bf16 v[84:87], v[164:167], v[196:199], v[84:87]
	v_mfma_f32_16x16x32_bf16 v[80:83], v[172:175], v[196:199], v[80:83]
	v_mfma_f32_16x16x32_bf16 v[68:71], v[164:167], v[208:211], v[68:71]
	v_mfma_f32_16x16x32_bf16 v[64:67], v[172:175], v[208:211], v[64:67]
	s_barrier
	s_add_i32 s67, s61, s52
	v_lshl_add_u64 v[140:141], s[44:45], 0, v[128:129]
	s_mov_b32 m0, s67
	ds_read_b128 v[176:179], v147 offset:16384
	ds_read_b128 v[180:183], v147 offset:17408
	ds_read_b128 v[184:187], v147 offset:18432
	ds_read_b128 v[188:191], v147 offset:19456
	ds_read_b128 v[192:195], v147 offset:20480
	ds_read_b128 v[196:199], v147 offset:21504
	ds_read_b128 v[204:207], v147 offset:22528
	ds_read_b128 v[208:211], v147 offset:23552
	global_load_lds_dwordx4 v[140:141], off
	s_add_i32 m0, s67, 0x2000
	s_add_u32 s78, s44, 0x40000
	v_lshl_add_u64 v[200:201], s[44:45], 0, v[130:131]
	s_addc_u32 s79, s45, 0
	s_add_i32 s67, s62, s52
	global_load_lds_dwordx4 v[200:201], off
	v_lshl_add_u64 v[212:213], s[78:79], 0, v[128:129]
	s_mov_b32 m0, s67
	v_lshl_add_u64 v[214:215], s[46:47], 0, v[130:131]
	global_load_lds_dwordx4 v[212:213], off
	v_lshl_add_u64 v[212:213], s[78:79], 0, v[130:131]
	s_add_i32 m0, s67, 0x2000
	s_nop 0
	global_load_lds_dwordx4 v[212:213], off
	v_lshl_add_u64 v[212:213], s[46:47], 0, v[128:129]
	s_mov_b32 m0, s29
	s_nop 0
	global_load_lds_dwordx4 v[212:213], off
	s_mov_b32 m0, s55
	s_nop 0
	global_load_lds_dwordx4 v[214:215], off
	s_waitcnt vmcnt(8)
	s_waitcnt lgkmcnt(0)
	s_barrier
; #define PG8_STAGE(bufoff, gbase, voff) do { _Pragma("unroll") for (int _i = 0; _i < 2; ++_i) \
;         __builtin_amdgcn_global_load_lds((const unsigned*)((const char*)(gbase) + (voff)[_i]), (LAS unsigned*)(lds + (bufoff) + ldsw + _i * 8192), 16, 0, 0); } while (0)
; #define PG8_LDA(dst, b, h) do { _Pragma("unroll") for (int m = 0; m < 4; ++m) _Pragma("unroll") for (int k = 0; k < 2; ++k) dst[m][k] = *(const LAS bf16x8*)(lds + PG8_SA(b, h) + aoff + m * 2048 + k * 1024); } while (0)
; #define PG8_LDB(dst, b, h) do { _Pragma("unroll") for (int n = 0; n < 2; ++n) _Pragma("unroll") for (int k = 0; k < 2; ++k) dst[n][k] = *(const LAS bf16x8*)(lds + PG8_SB(b, h) + boff + n * 2048 + k * 1024); } while (0)
; #define PG8_MMA(ai, bj, At, Bt) do { __builtin_amdgcn_s_setprio(1); _Pragma("unroll") for (int m = 0; m < 4; ++m) _Pragma("unroll") for (int n = 0; n < 2; ++n) _Pragma("unroll") for (int k = 0; k < 2; ++k) \
;         acc[ai][bj][m][n] = __builtin_amdgcn_mfma_f32_16x16x32_bf16(Bt[n][k], At[m][k], acc[ai][bj][m][n], 0, 0, 0); __builtin_amdgcn_s_setprio(0); } while (0)
; #define PG8_WAIT_V(n) asm volatile("s_waitcnt vmcnt(" #n ")" ::: "memory")
; #define PG8_WAIT_L(n) asm volatile("s_waitcnt lgkmcnt(" #n ")" ::: "memory")
; #define PG8_BAR __builtin_amdgcn_s_barrier()
; #define PG8_SCHED __builtin_amdgcn_sched_barrier(0)
; template <class Epi>
; __device__ __forceinline__ void gemm_phase(LAS unsigned char* lds, const Gemm g, const Sched& S, const Epi& E) {
;     ...
;             PG8_LDA(At, 0, 1); PG8_STAGE(PG8_SB(0, 0), b2, voffB); PG8_STAGE(PG8_SB(0, 1), b2 + hstepB, voffB); PG8_STAGE(PG8_SA(0, 0), a2, voffA);
;             PG8_WAIT_V(8); PG8_WAIT_L(0); PG8_BAR; PG8_MMA(1, 0, At, B0); PG8_MMA(1, 1, At, B1); PG8_BAR; PG8_SCHED;
;             PG8_LDB(B0, 1, 0); PG8_LDB(B1, 1, 1); PG8_SCHED; PG8_LDA(At, 1, 0); PG8_STAGE(PG8_SA(0, 1), a2 + hstepA, voffA);
;             PG8_WAIT_V(8); PG8_WAIT_L(0); PG8_BAR; PG8_MMA(0, 0, At, B0); PG8_MMA(0, 1, At, B1); PG8_BAR; PG8_SCHED;
	s_waitcnt lgkmcnt(0)
	v_mfma_f32_16x16x32_bf16 v[60:63], v[136:139], v[176:179], v[60:63]
	v_mfma_f32_16x16x32_bf16 v[56:59], v[152:155], v[176:179], v[56:59]
	v_mfma_f32_16x16x32_bf16 v[44:47], v[136:139], v[184:187], v[44:47]
	v_mfma_f32_16x16x32_bf16 v[40:43], v[152:155], v[184:187], v[40:43]
	v_mfma_f32_16x16x32_bf16 v[28:31], v[136:139], v[192:195], v[28:31]
	v_mfma_f32_16x16x32_bf16 v[24:27], v[152:155], v[192:195], v[24:27]
	v_mfma_f32_16x16x32_bf16 v[12:15], v[136:139], v[204:207], v[12:15]
	v_mfma_f32_16x16x32_bf16 v[8:11], v[152:155], v[204:207], v[8:11]
	v_mfma_f32_16x16x32_bf16 v[60:63], v[148:151], v[180:183], v[60:63]
	v_mfma_f32_16x16x32_bf16 v[56:59], v[156:159], v[180:183], v[56:59]
	v_mfma_f32_16x16x32_bf16 v[44:47], v[148:151], v[188:191], v[44:47]
	v_mfma_f32_16x16x32_bf16 v[40:43], v[156:159], v[188:191], v[40:43]
	v_mfma_f32_16x16x32_bf16 v[28:31], v[148:151], v[196:199], v[28:31]
	v_mfma_f32_16x16x32_bf16 v[24:27], v[156:159], v[196:199], v[24:27]
	v_mfma_f32_16x16x32_bf16 v[12:15], v[148:151], v[208:211], v[12:15]
	v_mfma_f32_16x16x32_bf16 v[8:11], v[156:159], v[208:211], v[8:11]
	v_mfma_f32_16x16x32_bf16 v[52:55], v[160:163], v[176:179], v[52:55]
	v_mfma_f32_16x16x32_bf16 v[48:51], v[168:171], v[176:179], v[48:51]
	v_mfma_f32_16x16x32_bf16 v[36:39], v[160:163], v[184:187], v[36:39]
	v_mfma_f32_16x16x32_bf16 v[32:35], v[168:171], v[184:187], v[32:35]
	v_mfma_f32_16x16x32_bf16 v[20:23], v[160:163], v[192:195], v[20:23]
	v_mfma_f32_16x16x32_bf16 v[16:19], v[168:171], v[192:195], v[16:19]
	v_mfma_f32_16x16x32_bf16 v[4:7], v[160:163], v[204:207], v[4:7]
	v_mfma_f32_16x16x32_bf16 v[0:3], v[168:171], v[204:207], v[0:3]
	v_mfma_f32_16x16x32_bf16 v[52:55], v[164:167], v[180:183], v[52:55]
	v_mfma_f32_16x16x32_bf16 v[48:51], v[172:175], v[180:183], v[48:51]
	v_mfma_f32_16x16x32_bf16 v[36:39], v[164:167], v[188:191], v[36:39]
	v_mfma_f32_16x16x32_bf16 v[32:35], v[172:175], v[188:191], v[32:35]
	v_mfma_f32_16x16x32_bf16 v[20:23], v[164:167], v[196:199], v[20:23]
	v_mfma_f32_16x16x32_bf16 v[16:19], v[172:175], v[196:199], v[16:19]
	v_mfma_f32_16x16x32_bf16 v[4:7], v[164:167], v[208:211], v[4:7]
	v_mfma_f32_16x16x32_bf16 v[0:3], v[172:175], v[208:211], v[0:3]
	s_barrier
	s_add_i32 s67, 0, 0x18000
	s_add_i32 s78, 0, 0x1c000
	v_add_u32_e32 v156, s67, v143
	v_add_u32_e32 v172, s78, v143
	ds_read_b128 v[136:139], v156
	ds_read_b128 v[148:151], v156 offset:1024
	ds_read_b128 v[152:155], v156 offset:2048
	ds_read_b128 v[156:159], v156 offset:3072
	ds_read_b128 v[160:163], v172
	ds_read_b128 v[164:167], v172 offset:1024
	ds_read_b128 v[168:171], v172 offset:2048
	ds_read_b128 v[172:175], v172 offset:3072
	s_add_u32 s46, s46, 0x40000
	s_addc_u32 s47, s47, 0
	s_mov_b32 m0, s56
	v_lshl_add_u64 v[216:217], s[46:47], 0, v[128:129]
	ds_read_b128 v[176:179], v147 offset:32768
	ds_read_b128 v[180:183], v147 offset:33792
	ds_read_b128 v[184:187], v147 offset:34816
	ds_read_b128 v[188:191], v147 offset:35840
	ds_read_b128 v[192:195], v147 offset:36864
	ds_read_b128 v[196:199], v147 offset:37888
	ds_read_b128 v[204:207], v147 offset:38912
	ds_read_b128 v[208:211], v147 offset:39936
	global_load_lds_dwordx4 v[216:217], off
	v_lshl_add_u64 v[216:217], s[46:47], 0, v[130:131]
	s_mov_b32 m0, s57
	s_nop 0
	global_load_lds_dwordx4 v[216:217], off
	s_waitcnt vmcnt(8)
	s_waitcnt lgkmcnt(0)
	s_barrier
	s_waitcnt lgkmcnt(0)
	v_mfma_f32_16x16x32_bf16 v[124:127], v[136:139], v[176:179], v[124:127]
	v_mfma_f32_16x16x32_bf16 v[120:123], v[152:155], v[176:179], v[120:123]
	v_mfma_f32_16x16x32_bf16 v[108:111], v[136:139], v[184:187], v[108:111]
	v_mfma_f32_16x16x32_bf16 v[104:107], v[152:155], v[184:187], v[104:107]
	v_mfma_f32_16x16x32_bf16 v[92:95], v[136:139], v[192:195], v[92:95]
	v_mfma_f32_16x16x32_bf16 v[88:91], v[152:155], v[192:195], v[88:91]
	v_mfma_f32_16x16x32_bf16 v[76:79], v[136:139], v[204:207], v[76:79]
	v_mfma_f32_16x16x32_bf16 v[72:75], v[152:155], v[204:207], v[72:75]
	v_mfma_f32_16x16x32_bf16 v[124:127], v[148:151], v[180:183], v[124:127]
	v_mfma_f32_16x16x32_bf16 v[120:123], v[156:159], v[180:183], v[120:123]
	v_mfma_f32_16x16x32_bf16 v[108:111], v[148:151], v[188:191], v[108:111]
	v_mfma_f32_16x16x32_bf16 v[104:107], v[156:159], v[188:191], v[104:107]
	v_mfma_f32_16x16x32_bf16 v[92:95], v[148:151], v[196:199], v[92:95]
	v_mfma_f32_16x16x32_bf16 v[88:91], v[156:159], v[196:199], v[88:91]
	v_mfma_f32_16x16x32_bf16 v[76:79], v[148:151], v[208:211], v[76:79]
	v_mfma_f32_16x16x32_bf16 v[72:75], v[156:159], v[208:211], v[72:75]
	v_mfma_f32_16x16x32_bf16 v[116:119], v[160:163], v[176:179], v[116:119]
	v_mfma_f32_16x16x32_bf16 v[112:115], v[168:171], v[176:179], v[112:115]
	v_mfma_f32_16x16x32_bf16 v[100:103], v[160:163], v[184:187], v[100:103]
	v_mfma_f32_16x16x32_bf16 v[96:99], v[168:171], v[184:187], v[96:99]
	v_mfma_f32_16x16x32_bf16 v[84:87], v[160:163], v[192:195], v[84:87]
	v_mfma_f32_16x16x32_bf16 v[80:83], v[168:171], v[192:195], v[80:83]
	v_mfma_f32_16x16x32_bf16 v[68:71], v[160:163], v[204:207], v[68:71]
	v_mfma_f32_16x16x32_bf16 v[64:67], v[168:171], v[204:207], v[64:67]
	v_mfma_f32_16x16x32_bf16 v[116:119], v[164:167], v[180:183], v[116:119]
	v_mfma_f32_16x16x32_bf16 v[112:115], v[172:175], v[180:183], v[112:115]
	v_mfma_f32_16x16x32_bf16 v[100:103], v[164:167], v[188:191], v[100:103]
	v_mfma_f32_16x16x32_bf16 v[96:99], v[172:175], v[188:191], v[96:99]
	v_mfma_f32_16x16x32_bf16 v[84:87], v[164:167], v[196:199], v[84:87]
	v_mfma_f32_16x16x32_bf16 v[80:83], v[172:175], v[196:199], v[80:83]
	v_mfma_f32_16x16x32_bf16 v[68:71], v[164:167], v[208:211], v[68:71]
	v_mfma_f32_16x16x32_bf16 v[64:67], v[172:175], v[208:211], v[64:67]
	s_barrier
; #define PG8_STAGE(bufoff, gbase, voff) do { _Pragma("unroll") for (int _i = 0; _i < 2; ++_i) \
;         __builtin_amdgcn_global_load_lds((const unsigned*)((const char*)(gbase) + (voff)[_i]), (LAS unsigned*)(lds + (bufoff) + ldsw + _i * 8192), 16, 0, 0); } while (0)
; #define PG8_LDA(dst, b, h) do { _Pragma("unroll") for (int m = 0; m < 4; ++m) _Pragma("unroll") for (int k = 0; k < 2; ++k) dst[m][k] = *(const LAS bf16x8*)(lds + PG8_SA(b, h) + aoff + m * 2048 + k * 1024); } while (0)
; #define PG8_LDB(dst, b, h) do { _Pragma("unroll") for (int n = 0; n < 2; ++n) _Pragma("unroll") for (int k = 0; k < 2; ++k) dst[n][k] = *(const LAS bf16x8*)(lds + PG8_SB(b, h) + boff + n * 2048 + k * 1024); } while (0)
; #define PG8_MMA(ai, bj, At, Bt) do { __builtin_amdgcn_s_setprio(1); _Pragma("unroll") for (int m = 0; m < 4; ++m) _Pragma("unroll") for (int n = 0; n < 2; ++n) _Pragma("unroll") for (int k = 0; k < 2; ++k) \
;         acc[ai][bj][m][n] = __builtin_amdgcn_mfma_f32_16x16x32_bf16(Bt[n][k], At[m][k], acc[ai][bj][m][n], 0, 0, 0); __builtin_amdgcn_s_setprio(0); } while (0)
; #define PG8_WAIT_V(n) asm volatile("s_waitcnt vmcnt(" #n ")" ::: "memory")
; #define PG8_WAIT_L(n) asm volatile("s_waitcnt lgkmcnt(" #n ")" ::: "memory")
; #define PG8_BAR __builtin_amdgcn_s_barrier()
; #define PG8_SCHED __builtin_amdgcn_sched_barrier(0)
; template <class Epi>
; __device__ __forceinline__ void gemm_phase(LAS unsigned char* lds, const Gemm g, const Sched& S, const Epi& E) {
;     ...
;             PG8_LDB(B0, 1, 0); PG8_LDB(B1, 1, 1); PG8_SCHED; PG8_LDA(At, 1, 0); PG8_STAGE(PG8_SA(0, 1), a2 + hstepA, voffA);
;             PG8_WAIT_V(8); PG8_WAIT_L(0); PG8_BAR; PG8_MMA(0, 0, At, B0); PG8_MMA(0, 1, At, B1); PG8_BAR; PG8_SCHED;
;             PG8_LDA(At, 1, 1); PG8_STAGE(PG8_SB(1, 0), b3, voffB); PG8_STAGE(PG8_SB(1, 1), b3 + hstepB, voffB); PG8_STAGE(PG8_SA(1, 0), a3, voffA);
;             PG8_WAIT_V(8); PG8_WAIT_L(0); PG8_BAR; PG8_MMA(1, 0, At, B0); PG8_MMA(1, 1, At, B1); PG8_BAR; PG8_SCHED;
;         }
;         if (wr == 0) PG8_BAR;
	s_add_i32 s46, s67, s52
	v_lshl_add_u64 v[140:141], v[140:141], 0, s[4:5]
	s_mov_b32 m0, s46
	ds_read_b128 v[176:179], v147 offset:49152
	ds_read_b128 v[180:183], v147 offset:50176
	ds_read_b128 v[184:187], v147 offset:51200
	ds_read_b128 v[188:191], v147 offset:52224
	ds_read_b128 v[192:195], v147 offset:53248
	ds_read_b128 v[196:199], v147 offset:54272
	ds_read_b128 v[204:207], v147 offset:55296
	ds_read_b128 v[208:211], v147 offset:56320
	global_load_lds_dwordx4 v[140:141], off
	s_add_i32 m0, s46, 0x2000
	s_add_u32 s44, s44, 0x40080
	v_lshl_add_u64 v[140:141], v[200:201], 0, s[4:5]
	s_addc_u32 s45, s45, 0
	s_add_i32 s46, s78, s52
	global_load_lds_dwordx4 v[140:141], off
	v_lshl_add_u64 v[140:141], s[44:45], 0, v[128:129]
	s_mov_b32 m0, s46
	s_nop 0
	global_load_lds_dwordx4 v[140:141], off
	v_lshl_add_u64 v[140:141], s[44:45], 0, v[130:131]
	s_add_i32 m0, s46, 0x2000
	s_nop 0
	global_load_lds_dwordx4 v[140:141], off
	v_lshl_add_u64 v[140:141], v[212:213], 0, s[4:5]
	s_mov_b32 m0, s59
	s_nop 0
	global_load_lds_dwordx4 v[140:141], off
	v_lshl_add_u64 v[140:141], v[214:215], 0, s[4:5]
	s_mov_b32 m0, s60
	s_nop 0
	global_load_lds_dwordx4 v[140:141], off
	s_waitcnt vmcnt(8)
	s_waitcnt lgkmcnt(0)
	s_barrier
	s_waitcnt lgkmcnt(0)
	v_mfma_f32_16x16x32_bf16 v[60:63], v[136:139], v[176:179], v[60:63]
	v_mfma_f32_16x16x32_bf16 v[56:59], v[152:155], v[176:179], v[56:59]
	v_mfma_f32_16x16x32_bf16 v[44:47], v[136:139], v[184:187], v[44:47]
	v_mfma_f32_16x16x32_bf16 v[40:43], v[152:155], v[184:187], v[40:43]
	v_mfma_f32_16x16x32_bf16 v[28:31], v[136:139], v[192:195], v[28:31]
	v_mfma_f32_16x16x32_bf16 v[24:27], v[152:155], v[192:195], v[24:27]
	v_mfma_f32_16x16x32_bf16 v[12:15], v[136:139], v[204:207], v[12:15]
	v_mfma_f32_16x16x32_bf16 v[8:11], v[152:155], v[204:207], v[8:11]
	v_mfma_f32_16x16x32_bf16 v[60:63], v[148:151], v[180:183], v[60:63]
	v_mfma_f32_16x16x32_bf16 v[56:59], v[156:159], v[180:183], v[56:59]
	v_mfma_f32_16x16x32_bf16 v[44:47], v[148:151], v[188:191], v[44:47]
	v_mfma_f32_16x16x32_bf16 v[40:43], v[156:159], v[188:191], v[40:43]
	v_mfma_f32_16x16x32_bf16 v[28:31], v[148:151], v[196:199], v[28:31]
	v_mfma_f32_16x16x32_bf16 v[24:27], v[156:159], v[196:199], v[24:27]
	v_mfma_f32_16x16x32_bf16 v[12:15], v[148:151], v[208:211], v[12:15]
	v_mfma_f32_16x16x32_bf16 v[8:11], v[156:159], v[208:211], v[8:11]
	v_mfma_f32_16x16x32_bf16 v[52:55], v[160:163], v[176:179], v[52:55]
	v_mfma_f32_16x16x32_bf16 v[48:51], v[168:171], v[176:179], v[48:51]
	v_mfma_f32_16x16x32_bf16 v[36:39], v[160:163], v[184:187], v[36:39]
	v_mfma_f32_16x16x32_bf16 v[32:35], v[168:171], v[184:187], v[32:35]
	v_mfma_f32_16x16x32_bf16 v[20:23], v[160:163], v[192:195], v[20:23]
	v_mfma_f32_16x16x32_bf16 v[16:19], v[168:171], v[192:195], v[16:19]
	v_mfma_f32_16x16x32_bf16 v[4:7], v[160:163], v[204:207], v[4:7]
	v_mfma_f32_16x16x32_bf16 v[0:3], v[168:171], v[204:207], v[0:3]
	v_mfma_f32_16x16x32_bf16 v[52:55], v[164:167], v[180:183], v[52:55]
	v_mfma_f32_16x16x32_bf16 v[48:51], v[172:175], v[180:183], v[48:51]
	v_mfma_f32_16x16x32_bf16 v[36:39], v[164:167], v[188:191], v[36:39]
	v_mfma_f32_16x16x32_bf16 v[32:35], v[172:175], v[188:191], v[32:35]
	v_mfma_f32_16x16x32_bf16 v[20:23], v[164:167], v[196:199], v[20:23]
	v_mfma_f32_16x16x32_bf16 v[16:19], v[172:175], v[196:199], v[16:19]
	v_mfma_f32_16x16x32_bf16 v[4:7], v[164:167], v[208:211], v[4:7]
	v_mfma_f32_16x16x32_bf16 v[0:3], v[172:175], v[208:211], v[0:3]
	s_barrier
	s_add_i32 s66, s66, 2
	s_add_u32 s40, s40, 0x100
	s_addc_u32 s41, s41, 0
	s_add_u32 s64, s64, 0x100
	s_addc_u32 s65, s65, 0
	s_cmp_gt_u32 s66, 13
	s_cbranch_scc0 .LBB0_205
	s_and_b64 vcc, exec, s[6:7]
	s_cbranch_vccz .LBB0_208
	s_barrier

; #define PG8_STAGE(bufoff, gbase, voff) do { _Pragma("unroll") for (int _i = 0; _i < 2; ++_i) \
;         __builtin_amdgcn_global_load_lds((const unsigned*)((const char*)(gbase) + (voff)[_i]), (LAS unsigned*)(lds + (bufoff) + ldsw + _i * 8192), 16, 0, 0); } while (0)
; #define PG8_LDA(dst, b, h) do { _Pragma("unroll") for (int m = 0; m < 4; ++m) _Pragma("unroll") for (int k = 0; k < 2; ++k) dst[m][k] = *(const LAS bf16x8*)(lds + PG8_SA(b, h) + aoff + m * 2048 + k * 1024); } while (0)
; #define PG8_LDB(dst, b, h) do { _Pragma("unroll") for (int n = 0; n < 2; ++n) _Pragma("unroll") for (int k = 0; k < 2; ++k) dst[n][k] = *(const LAS bf16x8*)(lds + PG8_SB(b, h) + boff + n * 2048 + k * 1024); } while (0)
; #define PG8_MMA(ai, bj, At, Bt) do { __builtin_amdgcn_s_setprio(1); _Pragma("unroll") for (int m = 0; m < 4; ++m) _Pragma("unroll") for (int n = 0; n < 2; ++n) _Pragma("unroll") for (int k = 0; k < 2; ++k) \
;         acc[ai][bj][m][n] = __builtin_amdgcn_mfma_f32_16x16x32_bf16(Bt[n][k], At[m][k], acc[ai][bj][m][n], 0, 0, 0); __builtin_amdgcn_s_setprio(0); } while (0)
; #define PG8_WAIT_V(n) asm volatile("s_waitcnt vmcnt(" #n ")" ::: "memory")
; #define PG8_WAIT_L(n) asm volatile("s_waitcnt lgkmcnt(" #n ")" ::: "memory")
; #define PG8_BAR __builtin_amdgcn_s_barrier()
; #define PG8_SCHED __builtin_amdgcn_sched_barrier(0)
; template <class Epi>
; __device__ __forceinline__ void gemm_phase(LAS unsigned char* lds, const Gemm g, const Sched& S, const Epi& E) {
;     ...
;             PG8_LDB(B0, 0, 0); PG8_LDB(B1, 0, 1); PG8_SCHED; PG8_LDA(At, 0, 0); PG8_STAGE(PG8_SA(1, 1), a1 + hstepA, voffA);
;             PG8_WAIT_V(8); PG8_WAIT_L(0); PG8_BAR; PG8_MMA(0, 0, At, B0); PG8_MMA(0, 1, At, B1); PG8_BAR; PG8_SCHED;
;             PG8_LDA(At, 0, 1); PG8_STAGE(PG8_SB(0, 0), b2, voffB); PG8_STAGE(PG8_SB(0, 1), b2 + hstepB, voffB); PG8_STAGE(PG8_SA(0, 0), a2, voffA);
;             PG8_WAIT_V(8); PG8_WAIT_L(0); PG8_BAR; PG8_MMA(1, 0, At, B0); PG8_MMA(1, 1, At, B1); PG8_BAR; PG8_SCHED;
.LBB0_293:
	ds_read_b128 v[146:149], v143
	ds_read_b128 v[150:153], v143 offset:1024
	ds_read_b128 v[154:157], v143 offset:2048
	ds_read_b128 v[158:161], v143 offset:3072
	ds_read_b128 v[162:165], v144
	ds_read_b128 v[166:169], v144 offset:1024
	ds_read_b128 v[170:173], v144 offset:2048
	ds_read_b128 v[174:177], v144 offset:3072
	s_add_u32 s40, s28, 0xfffc0080
	s_addc_u32 s41, s29, -1
	s_cmp_eq_u32 s66, 12
	s_cselect_b32 s45, s23, s41
	s_cselect_b32 s44, s62, s40
	s_cselect_b32 s41, s15, s65
	s_cselect_b32 s40, s63, s64
	v_lshl_add_u64 v[212:213], s[28:29], 0, v[136:137]
	s_add_i32 m0, s21, 0xc000
	ds_read_b128 v[178:181], v145
	ds_read_b128 v[182:185], v145 offset:1024
	ds_read_b128 v[186:189], v145 offset:2048
	ds_read_b128 v[190:193], v145 offset:3072
	ds_read_b128 v[194:197], v145 offset:4096
	ds_read_b128 v[198:201], v145 offset:5120
	ds_read_b128 v[204:207], v145 offset:6144
	ds_read_b128 v[208:211], v145 offset:7168
	global_load_lds_dwordx4 v[212:213], off
	v_lshl_add_u64 v[212:213], s[28:29], 0, v[138:139]
	s_add_i32 m0, s21, 0xe000
	s_nop 0
	global_load_lds_dwordx4 v[212:213], off
	s_waitcnt vmcnt(8)
	s_waitcnt lgkmcnt(0)
	s_barrier
	s_waitcnt lgkmcnt(0)
	v_mfma_f32_16x16x32_bf16 v[124:127], v[146:149], v[178:181], v[124:127]
	v_mfma_f32_16x16x32_bf16 v[120:123], v[154:157], v[178:181], v[120:123]
	v_mfma_f32_16x16x32_bf16 v[116:119], v[146:149], v[186:189], v[116:119]
	v_mfma_f32_16x16x32_bf16 v[112:115], v[154:157], v[186:189], v[112:115]
	v_mfma_f32_16x16x32_bf16 v[100:103], v[146:149], v[194:197], v[100:103]
	v_mfma_f32_16x16x32_bf16 v[96:99], v[154:157], v[194:197], v[96:99]
	v_mfma_f32_16x16x32_bf16 v[84:87], v[146:149], v[204:207], v[84:87]
	v_mfma_f32_16x16x32_bf16 v[80:83], v[154:157], v[204:207], v[80:83]
	v_mfma_f32_16x16x32_bf16 v[124:127], v[150:153], v[182:185], v[124:127]
	v_mfma_f32_16x16x32_bf16 v[120:123], v[158:161], v[182:185], v[120:123]
	v_mfma_f32_16x16x32_bf16 v[116:119], v[150:153], v[190:193], v[116:119]
	v_mfma_f32_16x16x32_bf16 v[112:115], v[158:161], v[190:193], v[112:115]
	v_mfma_f32_16x16x32_bf16 v[100:103], v[150:153], v[198:201], v[100:103]
	v_mfma_f32_16x16x32_bf16 v[96:99], v[158:161], v[198:201], v[96:99]
	v_mfma_f32_16x16x32_bf16 v[84:87], v[150:153], v[208:211], v[84:87]
	v_mfma_f32_16x16x32_bf16 v[80:83], v[158:161], v[208:211], v[80:83]
	v_mfma_f32_16x16x32_bf16 v[108:111], v[162:165], v[178:181], v[108:111]
	v_mfma_f32_16x16x32_bf16 v[104:107], v[170:173], v[178:181], v[104:107]
	v_mfma_f32_16x16x32_bf16 v[92:95], v[162:165], v[186:189], v[92:95]
	v_mfma_f32_16x16x32_bf16 v[88:91], v[170:173], v[186:189], v[88:91]
	v_mfma_f32_16x16x32_bf16 v[76:79], v[162:165], v[194:197], v[76:79]
	v_mfma_f32_16x16x32_bf16 v[72:75], v[170:173], v[194:197], v[72:75]
	v_mfma_f32_16x16x32_bf16 v[68:71], v[162:165], v[204:207], v[68:71]
	v_mfma_f32_16x16x32_bf16 v[64:67], v[170:173], v[204:207], v[64:67]
	v_mfma_f32_16x16x32_bf16 v[108:111], v[166:169], v[182:185], v[108:111]
	v_mfma_f32_16x16x32_bf16 v[104:107], v[174:177], v[182:185], v[104:107]
	v_mfma_f32_16x16x32_bf16 v[92:95], v[166:169], v[190:193], v[92:95]
	v_mfma_f32_16x16x32_bf16 v[88:91], v[174:177], v[190:193], v[88:91]
	v_mfma_f32_16x16x32_bf16 v[76:79], v[166:169], v[198:201], v[76:79]
	v_mfma_f32_16x16x32_bf16 v[72:75], v[174:177], v[198:201], v[72:75]
	v_mfma_f32_16x16x32_bf16 v[68:71], v[166:169], v[208:211], v[68:71]
	v_mfma_f32_16x16x32_bf16 v[64:67], v[174:177], v[208:211], v[64:67]
	s_barrier
	s_add_i32 s67, s59, s52
	v_lshl_add_u64 v[212:213], s[40:41], 0, v[130:131]
	s_mov_b32 m0, s67
	ds_read_b128 v[178:181], v145 offset:16384
	ds_read_b128 v[182:185], v145 offset:17408
	ds_read_b128 v[186:189], v145 offset:18432
	ds_read_b128 v[190:193], v145 offset:19456
	ds_read_b128 v[194:197], v145 offset:20480
	ds_read_b128 v[198:201], v145 offset:21504
	ds_read_b128 v[204:207], v145 offset:22528
	ds_read_b128 v[208:211], v145 offset:23552
	global_load_lds_dwordx4 v[212:213], off
	s_add_i32 m0, s67, 0x2000
	s_add_u32 s78, s40, 0x40000
	v_lshl_add_u64 v[214:215], s[40:41], 0, v[134:135]
	s_addc_u32 s79, s41, 0
	s_add_i32 s67, s60, s52
	global_load_lds_dwordx4 v[214:215], off
	v_lshl_add_u64 v[216:217], s[78:79], 0, v[130:131]
	s_mov_b32 m0, s67
	v_lshl_add_u64 v[218:219], s[44:45], 0, v[132:133]
	global_load_lds_dwordx4 v[216:217], off
	v_lshl_add_u64 v[216:217], s[78:79], 0, v[134:135]
	s_add_i32 m0, s67, 0x2000
	s_nop 0
	global_load_lds_dwordx4 v[216:217], off
	v_lshl_add_u64 v[216:217], s[44:45], 0, v[128:129]
	s_mov_b32 m0, s21
	s_nop 0
	global_load_lds_dwordx4 v[216:217], off
	s_mov_b32 m0, s53
	s_nop 0
	global_load_lds_dwordx4 v[218:219], off
	s_waitcnt vmcnt(8)
	s_waitcnt lgkmcnt(0)
	s_barrier
; #define PG8_STAGE(bufoff, gbase, voff) do { _Pragma("unroll") for (int _i = 0; _i < 2; ++_i) \
;         __builtin_amdgcn_global_load_lds((const unsigned*)((const char*)(gbase) + (voff)[_i]), (LAS unsigned*)(lds + (bufoff) + ldsw + _i * 8192), 16, 0, 0); } while (0)
; #define PG8_LDA(dst, b, h) do { _Pragma("unroll") for (int m = 0; m < 4; ++m) _Pragma("unroll") for (int k = 0; k < 2; ++k) dst[m][k] = *(const LAS bf16x8*)(lds + PG8_SA(b, h) + aoff + m * 2048 + k * 1024); } while (0)
; #define PG8_LDB(dst, b, h) do { _Pragma("unroll") for (int n = 0; n < 2; ++n) _Pragma("unroll") for (int k = 0; k < 2; ++k) dst[n][k] = *(const LAS bf16x8*)(lds + PG8_SB(b, h) + boff + n * 2048 + k * 1024); } while (0)
; #define PG8_MMA(ai, bj, At, Bt) do { __builtin_amdgcn_s_setprio(1); _Pragma("unroll") for (int m = 0; m < 4; ++m) _Pragma("unroll") for (int n = 0; n < 2; ++n) _Pragma("unroll") for (int k = 0; k < 2; ++k) \
;         acc[ai][bj][m][n] = __builtin_amdgcn_mfma_f32_16x16x32_bf16(Bt[n][k], At[m][k], acc[ai][bj][m][n], 0, 0, 0); __builtin_amdgcn_s_setprio(0); } while (0)
; #define PG8_WAIT_V(n) asm volatile("s_waitcnt vmcnt(" #n ")" ::: "memory")
; #define PG8_WAIT_L(n) asm volatile("s_waitcnt lgkmcnt(" #n ")" ::: "memory")
; #define PG8_BAR __builtin_amdgcn_s_barrier()
; #define PG8_SCHED __builtin_amdgcn_sched_barrier(0)
; template <class Epi>
; __device__ __forceinline__ void gemm_phase(LAS unsigned char* lds, const Gemm g, const Sched& S, const Epi& E) {
;     ...
;             PG8_LDA(At, 0, 1); PG8_STAGE(PG8_SB(0, 0), b2, voffB); PG8_STAGE(PG8_SB(0, 1), b2 + hstepB, voffB); PG8_STAGE(PG8_SA(0, 0), a2, voffA);
;             PG8_WAIT_V(8); PG8_WAIT_L(0); PG8_BAR; PG8_MMA(1, 0, At, B0); PG8_MMA(1, 1, At, B1); PG8_BAR; PG8_SCHED;
;             PG8_LDB(B0, 1, 0); PG8_LDB(B1, 1, 1); PG8_SCHED; PG8_LDA(At, 1, 0); PG8_STAGE(PG8_SA(0, 1), a2 + hstepA, voffA);
;             PG8_WAIT_V(8); PG8_WAIT_L(0); PG8_BAR; PG8_MMA(0, 0, At, B0); PG8_MMA(0, 1, At, B1); PG8_BAR; PG8_SCHED;
	s_waitcnt lgkmcnt(0)
	v_mfma_f32_16x16x32_bf16 v[60:63], v[146:149], v[178:181], v[60:63]
	v_mfma_f32_16x16x32_bf16 v[56:59], v[154:157], v[178:181], v[56:59]
	v_mfma_f32_16x16x32_bf16 v[52:55], v[146:149], v[186:189], v[52:55]
	v_mfma_f32_16x16x32_bf16 v[48:51], v[154:157], v[186:189], v[48:51]
	v_mfma_f32_16x16x32_bf16 v[36:39], v[146:149], v[194:197], v[36:39]
	v_mfma_f32_16x16x32_bf16 v[32:35], v[154:157], v[194:197], v[32:35]
	v_mfma_f32_16x16x32_bf16 v[20:23], v[146:149], v[204:207], v[20:23]
	v_mfma_f32_16x16x32_bf16 v[16:19], v[154:157], v[204:207], v[16:19]
	v_mfma_f32_16x16x32_bf16 v[60:63], v[150:153], v[182:185], v[60:63]
	v_mfma_f32_16x16x32_bf16 v[56:59], v[158:161], v[182:185], v[56:59]
	v_mfma_f32_16x16x32_bf16 v[52:55], v[150:153], v[190:193], v[52:55]
	v_mfma_f32_16x16x32_bf16 v[48:51], v[158:161], v[190:193], v[48:51]
	v_mfma_f32_16x16x32_bf16 v[36:39], v[150:153], v[198:201], v[36:39]
	v_mfma_f32_16x16x32_bf16 v[32:35], v[158:161], v[198:201], v[32:35]
	v_mfma_f32_16x16x32_bf16 v[20:23], v[150:153], v[208:211], v[20:23]
	v_mfma_f32_16x16x32_bf16 v[16:19], v[158:161], v[208:211], v[16:19]
	v_mfma_f32_16x16x32_bf16 v[44:47], v[162:165], v[178:181], v[44:47]
	v_mfma_f32_16x16x32_bf16 v[40:43], v[170:173], v[178:181], v[40:43]
	v_mfma_f32_16x16x32_bf16 v[28:31], v[162:165], v[186:189], v[28:31]
	v_mfma_f32_16x16x32_bf16 v[24:27], v[170:173], v[186:189], v[24:27]
	v_mfma_f32_16x16x32_bf16 v[12:15], v[162:165], v[194:197], v[12:15]
	v_mfma_f32_16x16x32_bf16 v[8:11], v[170:173], v[194:197], v[8:11]
	v_mfma_f32_16x16x32_bf16 v[4:7], v[162:165], v[204:207], v[4:7]
	v_mfma_f32_16x16x32_bf16 v[0:3], v[170:173], v[204:207], v[0:3]
	v_mfma_f32_16x16x32_bf16 v[44:47], v[166:169], v[182:185], v[44:47]
	v_mfma_f32_16x16x32_bf16 v[40:43], v[174:177], v[182:185], v[40:43]
	v_mfma_f32_16x16x32_bf16 v[28:31], v[166:169], v[190:193], v[28:31]
	v_mfma_f32_16x16x32_bf16 v[24:27], v[174:177], v[190:193], v[24:27]
	v_mfma_f32_16x16x32_bf16 v[12:15], v[166:169], v[198:201], v[12:15]
	v_mfma_f32_16x16x32_bf16 v[8:11], v[174:177], v[198:201], v[8:11]
	v_mfma_f32_16x16x32_bf16 v[4:7], v[166:169], v[208:211], v[4:7]
	v_mfma_f32_16x16x32_bf16 v[0:3], v[174:177], v[208:211], v[0:3]
	s_barrier
	s_add_i32 s67, 0, 0x18000
	s_add_i32 s78, 0, 0x1c000
	v_add_u32_e32 v158, s67, v141
	v_add_u32_e32 v174, s78, v141
	ds_read_b128 v[146:149], v158
	ds_read_b128 v[150:153], v158 offset:1024
	ds_read_b128 v[154:157], v158 offset:2048
	ds_read_b128 v[158:161], v158 offset:3072
	ds_read_b128 v[162:165], v174
	ds_read_b128 v[166:169], v174 offset:1024
	ds_read_b128 v[170:173], v174 offset:2048
	ds_read_b128 v[174:177], v174 offset:3072
	s_add_u32 s44, s44, 0x40000
	s_addc_u32 s45, s45, 0
	s_mov_b32 m0, s54
	v_lshl_add_u64 v[220:221], s[44:45], 0, v[128:129]
	ds_read_b128 v[178:181], v145 offset:32768
	ds_read_b128 v[182:185], v145 offset:33792
	ds_read_b128 v[186:189], v145 offset:34816
	ds_read_b128 v[190:193], v145 offset:35840
	ds_read_b128 v[194:197], v145 offset:36864
	ds_read_b128 v[198:201], v145 offset:37888
	ds_read_b128 v[204:207], v145 offset:38912
	ds_read_b128 v[208:211], v145 offset:39936
	global_load_lds_dwordx4 v[220:221], off
	v_lshl_add_u64 v[220:221], s[44:45], 0, v[132:133]
	s_mov_b32 m0, s55
	s_nop 0
	global_load_lds_dwordx4 v[220:221], off
	s_waitcnt vmcnt(8)
	s_waitcnt lgkmcnt(0)
	s_barrier
	s_waitcnt lgkmcnt(0)
	v_mfma_f32_16x16x32_bf16 v[124:127], v[146:149], v[178:181], v[124:127]
	v_mfma_f32_16x16x32_bf16 v[120:123], v[154:157], v[178:181], v[120:123]
	v_mfma_f32_16x16x32_bf16 v[116:119], v[146:149], v[186:189], v[116:119]
	v_mfma_f32_16x16x32_bf16 v[112:115], v[154:157], v[186:189], v[112:115]
	v_mfma_f32_16x16x32_bf16 v[100:103], v[146:149], v[194:197], v[100:103]
	v_mfma_f32_16x16x32_bf16 v[96:99], v[154:157], v[194:197], v[96:99]
	v_mfma_f32_16x16x32_bf16 v[84:87], v[146:149], v[204:207], v[84:87]
	v_mfma_f32_16x16x32_bf16 v[80:83], v[154:157], v[204:207], v[80:83]
	v_mfma_f32_16x16x32_bf16 v[124:127], v[150:153], v[182:185], v[124:127]
	v_mfma_f32_16x16x32_bf16 v[120:123], v[158:161], v[182:185], v[120:123]
	v_mfma_f32_16x16x32_bf16 v[116:119], v[150:153], v[190:193], v[116:119]
	v_mfma_f32_16x16x32_bf16 v[112:115], v[158:161], v[190:193], v[112:115]
	v_mfma_f32_16x16x32_bf16 v[100:103], v[150:153], v[198:201], v[100:103]
	v_mfma_f32_16x16x32_bf16 v[96:99], v[158:161], v[198:201], v[96:99]
	v_mfma_f32_16x16x32_bf16 v[84:87], v[150:153], v[208:211], v[84:87]
	v_mfma_f32_16x16x32_bf16 v[80:83], v[158:161], v[208:211], v[80:83]
	v_mfma_f32_16x16x32_bf16 v[108:111], v[162:165], v[178:181], v[108:111]
	v_mfma_f32_16x16x32_bf16 v[104:107], v[170:173], v[178:181], v[104:107]
	v_mfma_f32_16x16x32_bf16 v[92:95], v[162:165], v[186:189], v[92:95]
	v_mfma_f32_16x16x32_bf16 v[88:91], v[170:173], v[186:189], v[88:91]
	v_mfma_f32_16x16x32_bf16 v[76:79], v[162:165], v[194:197], v[76:79]
	v_mfma_f32_16x16x32_bf16 v[72:75], v[170:173], v[194:197], v[72:75]
	v_mfma_f32_16x16x32_bf16 v[68:71], v[162:165], v[204:207], v[68:71]
	v_mfma_f32_16x16x32_bf16 v[64:67], v[170:173], v[204:207], v[64:67]
	v_mfma_f32_16x16x32_bf16 v[108:111], v[166:169], v[182:185], v[108:111]
	v_mfma_f32_16x16x32_bf16 v[104:107], v[174:177], v[182:185], v[104:107]
	v_mfma_f32_16x16x32_bf16 v[92:95], v[166:169], v[190:193], v[92:95]
	v_mfma_f32_16x16x32_bf16 v[88:91], v[174:177], v[190:193], v[88:91]
	v_mfma_f32_16x16x32_bf16 v[76:79], v[166:169], v[198:201], v[76:79]
	v_mfma_f32_16x16x32_bf16 v[72:75], v[174:177], v[198:201], v[72:75]
	v_mfma_f32_16x16x32_bf16 v[68:71], v[166:169], v[208:211], v[68:71]
	v_mfma_f32_16x16x32_bf16 v[64:67], v[174:177], v[208:211], v[64:67]
	s_barrier
; #define PG8_STAGE(bufoff, gbase, voff) do { _Pragma("unroll") for (int _i = 0; _i < 2; ++_i) \
;         __builtin_amdgcn_global_load_lds((const unsigned*)((const char*)(gbase) + (voff)[_i]), (LAS unsigned*)(lds + (bufoff) + ldsw + _i * 8192), 16, 0, 0); } while (0)
; #define PG8_LDA(dst, b, h) do { _Pragma("unroll") for (int m = 0; m < 4; ++m) _Pragma("unroll") for (int k = 0; k < 2; ++k) dst[m][k] = *(const LAS bf16x8*)(lds + PG8_SA(b, h) + aoff + m * 2048 + k * 1024); } while (0)
; #define PG8_LDB(dst, b, h) do { _Pragma("unroll") for (int n = 0; n < 2; ++n) _Pragma("unroll") for (int k = 0; k < 2; ++k) dst[n][k] = *(const LAS bf16x8*)(lds + PG8_SB(b, h) + boff + n * 2048 + k * 1024); } while (0)
; #define PG8_MMA(ai, bj, At, Bt) do { __builtin_amdgcn_s_setprio(1); _Pragma("unroll") for (int m = 0; m < 4; ++m) _Pragma("unroll") for (int n = 0; n < 2; ++n) _Pragma("unroll") for (int k = 0; k < 2; ++k) \
;         acc[ai][bj][m][n] = __builtin_amdgcn_mfma_f32_16x16x32_bf16(Bt[n][k], At[m][k], acc[ai][bj][m][n], 0, 0, 0); __builtin_amdgcn_s_setprio(0); } while (0)
; #define PG8_WAIT_V(n) asm volatile("s_waitcnt vmcnt(" #n ")" ::: "memory")
; #define PG8_WAIT_L(n) asm volatile("s_waitcnt lgkmcnt(" #n ")" ::: "memory")
; #define PG8_BAR __builtin_amdgcn_s_barrier()
; #define PG8_SCHED __builtin_amdgcn_sched_barrier(0)
; template <class Epi>
; __device__ __forceinline__ void gemm_phase(LAS unsigned char* lds, const Gemm g, const Sched& S, const Epi& E) {
;     ...
;             PG8_LDB(B0, 1, 0); PG8_LDB(B1, 1, 1); PG8_SCHED; PG8_LDA(At, 1, 0); PG8_STAGE(PG8_SA(0, 1), a2 + hstepA, voffA);
;             PG8_WAIT_V(8); PG8_WAIT_L(0); PG8_BAR; PG8_MMA(0, 0, At, B0); PG8_MMA(0, 1, At, B1); PG8_BAR; PG8_SCHED;
;             PG8_LDA(At, 1, 1); PG8_STAGE(PG8_SB(1, 0), b3, voffB); PG8_STAGE(PG8_SB(1, 1), b3 + hstepB, voffB); PG8_STAGE(PG8_SA(1, 0), a3, voffA);
;             PG8_WAIT_V(8); PG8_WAIT_L(0); PG8_BAR; PG8_MMA(1, 0, At, B0); PG8_MMA(1, 1, At, B1); PG8_BAR; PG8_SCHED;
;         }
;         if (wr == 0) PG8_BAR;
	s_add_i32 s44, s67, s52
	v_lshl_add_u64 v[212:213], v[212:213], 0, s[4:5]
	s_mov_b32 m0, s44
	ds_read_b128 v[178:181], v145 offset:49152
	ds_read_b128 v[182:185], v145 offset:50176
	ds_read_b128 v[186:189], v145 offset:51200
	ds_read_b128 v[190:193], v145 offset:52224
	ds_read_b128 v[194:197], v145 offset:53248
	ds_read_b128 v[198:201], v145 offset:54272
	ds_read_b128 v[204:207], v145 offset:55296
	ds_read_b128 v[208:211], v145 offset:56320
	global_load_lds_dwordx4 v[212:213], off
	s_add_i32 m0, s44, 0x2000
	s_add_u32 s40, s40, 0x40080
	v_lshl_add_u64 v[212:213], v[214:215], 0, s[4:5]
	s_addc_u32 s41, s41, 0
	s_add_i32 s44, s78, s52
	global_load_lds_dwordx4 v[212:213], off
	v_lshl_add_u64 v[212:213], s[40:41], 0, v[130:131]
	s_mov_b32 m0, s44
	s_nop 0
	global_load_lds_dwordx4 v[212:213], off
	v_lshl_add_u64 v[212:213], s[40:41], 0, v[134:135]
	s_add_i32 m0, s44, 0x2000
	s_nop 0
	global_load_lds_dwordx4 v[212:213], off
	v_lshl_add_u64 v[212:213], v[216:217], 0, s[4:5]
	s_mov_b32 m0, s57
	s_nop 0
	global_load_lds_dwordx4 v[212:213], off
	v_lshl_add_u64 v[212:213], v[218:219], 0, s[4:5]
	s_mov_b32 m0, s58
	s_nop 0
	global_load_lds_dwordx4 v[212:213], off
	s_waitcnt vmcnt(8)
	s_waitcnt lgkmcnt(0)
	s_barrier
	s_waitcnt lgkmcnt(0)
	v_mfma_f32_16x16x32_bf16 v[60:63], v[146:149], v[178:181], v[60:63]
	v_mfma_f32_16x16x32_bf16 v[56:59], v[154:157], v[178:181], v[56:59]
	v_mfma_f32_16x16x32_bf16 v[52:55], v[146:149], v[186:189], v[52:55]
	v_mfma_f32_16x16x32_bf16 v[48:51], v[154:157], v[186:189], v[48:51]
	v_mfma_f32_16x16x32_bf16 v[36:39], v[146:149], v[194:197], v[36:39]
	v_mfma_f32_16x16x32_bf16 v[32:35], v[154:157], v[194:197], v[32:35]
	v_mfma_f32_16x16x32_bf16 v[20:23], v[146:149], v[204:207], v[20:23]
	v_mfma_f32_16x16x32_bf16 v[16:19], v[154:157], v[204:207], v[16:19]
	v_mfma_f32_16x16x32_bf16 v[60:63], v[150:153], v[182:185], v[60:63]
	v_mfma_f32_16x16x32_bf16 v[56:59], v[158:161], v[182:185], v[56:59]
	v_mfma_f32_16x16x32_bf16 v[52:55], v[150:153], v[190:193], v[52:55]
	v_mfma_f32_16x16x32_bf16 v[48:51], v[158:161], v[190:193], v[48:51]
	v_mfma_f32_16x16x32_bf16 v[36:39], v[150:153], v[198:201], v[36:39]
	v_mfma_f32_16x16x32_bf16 v[32:35], v[158:161], v[198:201], v[32:35]
	v_mfma_f32_16x16x32_bf16 v[20:23], v[150:153], v[208:211], v[20:23]
	v_mfma_f32_16x16x32_bf16 v[16:19], v[158:161], v[208:211], v[16:19]
	v_mfma_f32_16x16x32_bf16 v[44:47], v[162:165], v[178:181], v[44:47]
	v_mfma_f32_16x16x32_bf16 v[40:43], v[170:173], v[178:181], v[40:43]
	v_mfma_f32_16x16x32_bf16 v[28:31], v[162:165], v[186:189], v[28:31]
	v_mfma_f32_16x16x32_bf16 v[24:27], v[170:173], v[186:189], v[24:27]
	v_mfma_f32_16x16x32_bf16 v[12:15], v[162:165], v[194:197], v[12:15]
	v_mfma_f32_16x16x32_bf16 v[8:11], v[170:173], v[194:197], v[8:11]
	v_mfma_f32_16x16x32_bf16 v[4:7], v[162:165], v[204:207], v[4:7]
	v_mfma_f32_16x16x32_bf16 v[0:3], v[170:173], v[204:207], v[0:3]
	v_mfma_f32_16x16x32_bf16 v[44:47], v[166:169], v[182:185], v[44:47]
	v_mfma_f32_16x16x32_bf16 v[40:43], v[174:177], v[182:185], v[40:43]
	v_mfma_f32_16x16x32_bf16 v[28:31], v[166:169], v[190:193], v[28:31]
	v_mfma_f32_16x16x32_bf16 v[24:27], v[174:177], v[190:193], v[24:27]
	v_mfma_f32_16x16x32_bf16 v[12:15], v[166:169], v[198:201], v[12:15]
	v_mfma_f32_16x16x32_bf16 v[8:11], v[174:177], v[198:201], v[8:11]
	v_mfma_f32_16x16x32_bf16 v[4:7], v[166:169], v[208:211], v[4:7]
	v_mfma_f32_16x16x32_bf16 v[0:3], v[174:177], v[208:211], v[0:3]
	s_barrier
	s_add_i32 s66, s66, 2
	s_add_u32 s28, s28, 0x100
	s_addc_u32 s29, s29, 0
	s_add_u32 s64, s64, 0x100
	s_addc_u32 s65, s65, 0
	s_cmp_gt_u32 s66, 13
	s_cbranch_scc0 .LBB0_293
	s_and_b64 vcc, exec, s[6:7]
	s_cbranch_vccz .LBB0_296
	s_barrier

; #define PG8_STAGE(bufoff, gbase, voff) do { _Pragma("unroll") for (int _i = 0; _i < 2; ++_i) \
;         __builtin_amdgcn_global_load_lds((const unsigned*)((const char*)(gbase) + (voff)[_i]), (LAS unsigned*)(lds + (bufoff) + ldsw + _i * 8192), 16, 0, 0); } while (0)
; #define PG8_LDA(dst, b, h) do { _Pragma("unroll") for (int m = 0; m < 4; ++m) _Pragma("unroll") for (int k = 0; k < 2; ++k) dst[m][k] = *(const LAS bf16x8*)(lds + PG8_SA(b, h) + aoff + m * 2048 + k * 1024); } while (0)
; #define PG8_LDB(dst, b, h) do { _Pragma("unroll") for (int n = 0; n < 2; ++n) _Pragma("unroll") for (int k = 0; k < 2; ++k) dst[n][k] = *(const LAS bf16x8*)(lds + PG8_SB(b, h) + boff + n * 2048 + k * 1024); } while (0)
; #define PG8_MMA(ai, bj, At, Bt) do { __builtin_amdgcn_s_setprio(1); _Pragma("unroll") for (int m = 0; m < 4; ++m) _Pragma("unroll") for (int n = 0; n < 2; ++n) _Pragma("unroll") for (int k = 0; k < 2; ++k) \
;         acc[ai][bj][m][n] = __builtin_amdgcn_mfma_f32_16x16x32_bf16(Bt[n][k], At[m][k], acc[ai][bj][m][n], 0, 0, 0); __builtin_amdgcn_s_setprio(0); } while (0)
; #define PG8_WAIT_V(n) asm volatile("s_waitcnt vmcnt(" #n ")" ::: "memory")
; #define PG8_WAIT_L(n) asm volatile("s_waitcnt lgkmcnt(" #n ")" ::: "memory")
; #define PG8_BAR __builtin_amdgcn_s_barrier()
; #define PG8_SCHED __builtin_amdgcn_sched_barrier(0)
; template <class Epi>
; __device__ __forceinline__ void gemm_phase(LAS unsigned char* lds, const Gemm g, const Sched& S, const Epi& E) {
;     ...
;             PG8_LDB(B0, 0, 0); PG8_LDB(B1, 0, 1); PG8_SCHED; PG8_LDA(At, 0, 0); PG8_STAGE(PG8_SA(1, 1), a1 + hstepA, voffA);
;             PG8_WAIT_V(8); PG8_WAIT_L(0); PG8_BAR; PG8_MMA(0, 0, At, B0); PG8_MMA(0, 1, At, B1); PG8_BAR; PG8_SCHED;
;             PG8_LDA(At, 0, 1); PG8_STAGE(PG8_SB(0, 0), b2, voffB); PG8_STAGE(PG8_SB(0, 1), b2 + hstepB, voffB); PG8_STAGE(PG8_SA(0, 0), a2, voffA);
;             PG8_WAIT_V(8); PG8_WAIT_L(0); PG8_BAR; PG8_MMA(1, 0, At, B0); PG8_MMA(1, 1, At, B1); PG8_BAR; PG8_SCHED;
.LBB0_374:
	v_add_u32_e32 v158, s64, v144
	v_add_u32_e32 v174, s65, v144
	s_add_u32 s40, s26, s28
	ds_read_b128 v[146:149], v158
	ds_read_b128 v[150:153], v158 offset:1024
	ds_read_b128 v[154:157], v158 offset:2048
	ds_read_b128 v[158:161], v158 offset:3072
	ds_read_b128 v[162:165], v174
	ds_read_b128 v[166:169], v174 offset:1024
	ds_read_b128 v[170:173], v174 offset:2048
	ds_read_b128 v[174:177], v174 offset:3072
	s_addc_u32 s41, s27, s29
	s_add_u32 s40, s40, 0x100
	s_addc_u32 s41, s41, 0
	s_add_u32 s84, s87, s28
	s_addc_u32 s85, s88, s29
	s_cmpk_eq_i32 s28, 0x1500
	s_cselect_b32 s45, s23, s41
	s_cselect_b32 s44, s22, s40
	s_cselect_b32 s41, s25, s85
	s_cselect_b32 s40, s24, s84
	s_mov_b32 m0, s66
	v_lshl_add_u64 v[186:187], v[140:141], 0, s[28:29]
	ds_read_b128 v[178:181], v145
	ds_read_b128 v[182:185], v145 offset:1024
	ds_read_b128 v[192:195], v145 offset:2048
	ds_read_b128 v[196:199], v145 offset:3072
	ds_read_b128 v[204:207], v145 offset:4096
	ds_read_b128 v[208:211], v145 offset:5120
	ds_read_b128 v[212:215], v145 offset:6144
	ds_read_b128 v[216:219], v145 offset:7168
	global_load_lds_dwordx4 v[186:187], off
	v_lshl_add_u64 v[186:187], v[142:143], 0, s[28:29]
	s_mov_b32 m0, s67
	s_nop 0
	global_load_lds_dwordx4 v[186:187], off
	s_waitcnt vmcnt(8)
	s_waitcnt lgkmcnt(0)
	s_barrier
	s_waitcnt lgkmcnt(0)
	v_mfma_f32_16x16x32_bf16 v[124:127], v[146:149], v[178:181], v[124:127]
	v_mfma_f32_16x16x32_bf16 v[120:123], v[154:157], v[178:181], v[120:123]
	v_mfma_f32_16x16x32_bf16 v[108:111], v[146:149], v[192:195], v[108:111]
	v_mfma_f32_16x16x32_bf16 v[104:107], v[154:157], v[192:195], v[104:107]
	v_mfma_f32_16x16x32_bf16 v[92:95], v[146:149], v[204:207], v[92:95]
	v_mfma_f32_16x16x32_bf16 v[88:91], v[154:157], v[204:207], v[88:91]
	v_mfma_f32_16x16x32_bf16 v[76:79], v[146:149], v[212:215], v[76:79]
	v_mfma_f32_16x16x32_bf16 v[72:75], v[154:157], v[212:215], v[72:75]
	v_mfma_f32_16x16x32_bf16 v[124:127], v[150:153], v[182:185], v[124:127]
	v_mfma_f32_16x16x32_bf16 v[120:123], v[158:161], v[182:185], v[120:123]
	v_mfma_f32_16x16x32_bf16 v[108:111], v[150:153], v[196:199], v[108:111]
	v_mfma_f32_16x16x32_bf16 v[104:107], v[158:161], v[196:199], v[104:107]
	v_mfma_f32_16x16x32_bf16 v[92:95], v[150:153], v[208:211], v[92:95]
	v_mfma_f32_16x16x32_bf16 v[88:91], v[158:161], v[208:211], v[88:91]
	v_mfma_f32_16x16x32_bf16 v[76:79], v[150:153], v[216:219], v[76:79]
	v_mfma_f32_16x16x32_bf16 v[72:75], v[158:161], v[216:219], v[72:75]
	v_mfma_f32_16x16x32_bf16 v[116:119], v[162:165], v[178:181], v[116:119]
	v_mfma_f32_16x16x32_bf16 v[112:115], v[170:173], v[178:181], v[112:115]
	v_mfma_f32_16x16x32_bf16 v[100:103], v[162:165], v[192:195], v[100:103]
	v_mfma_f32_16x16x32_bf16 v[96:99], v[170:173], v[192:195], v[96:99]
	v_mfma_f32_16x16x32_bf16 v[84:87], v[162:165], v[204:207], v[84:87]
	v_mfma_f32_16x16x32_bf16 v[80:83], v[170:173], v[204:207], v[80:83]
	v_mfma_f32_16x16x32_bf16 v[68:71], v[162:165], v[212:215], v[68:71]
	v_mfma_f32_16x16x32_bf16 v[64:67], v[170:173], v[212:215], v[64:67]
	v_mfma_f32_16x16x32_bf16 v[116:119], v[166:169], v[182:185], v[116:119]
	v_mfma_f32_16x16x32_bf16 v[112:115], v[174:177], v[182:185], v[112:115]
	v_mfma_f32_16x16x32_bf16 v[100:103], v[166:169], v[196:199], v[100:103]
	v_mfma_f32_16x16x32_bf16 v[96:99], v[174:177], v[196:199], v[96:99]
	v_mfma_f32_16x16x32_bf16 v[84:87], v[166:169], v[208:211], v[84:87]
	v_mfma_f32_16x16x32_bf16 v[80:83], v[174:177], v[208:211], v[80:83]
	v_mfma_f32_16x16x32_bf16 v[68:71], v[166:169], v[216:219], v[68:71]
	v_mfma_f32_16x16x32_bf16 v[64:67], v[174:177], v[216:219], v[64:67]
	s_barrier
	s_mov_b32 m0, s78
	v_lshl_add_u64 v[186:187], s[40:41], 0, v[130:131]
	ds_read_b128 v[178:181], v145 offset:16384
	ds_read_b128 v[182:185], v145 offset:17408
	ds_read_b128 v[192:195], v145 offset:18432
	ds_read_b128 v[196:199], v145 offset:19456
	ds_read_b128 v[204:207], v145 offset:20480
	ds_read_b128 v[208:211], v145 offset:21504
	ds_read_b128 v[212:215], v145 offset:22528
	ds_read_b128 v[216:219], v145 offset:23552
	global_load_lds_dwordx4 v[186:187], off
	s_add_i32 m0, s78, 0x2000
	s_add_u32 s84, s40, 0xb0000
	v_lshl_add_u64 v[200:201], s[40:41], 0, v[134:135]
	s_addc_u32 s85, s41, 0
	s_add_i32 s90, s65, s56
	global_load_lds_dwordx4 v[200:201], off
	v_lshl_add_u64 v[220:221], s[84:85], 0, v[130:131]
	s_mov_b32 m0, s90
	v_lshl_add_u64 v[222:223], s[44:45], 0, v[132:133]
	global_load_lds_dwordx4 v[220:221], off
	v_lshl_add_u64 v[220:221], s[84:85], 0, v[134:135]
	s_add_i32 m0, s90, 0x2000
	s_nop 0
	global_load_lds_dwordx4 v[220:221], off
	v_lshl_add_u64 v[220:221], s[44:45], 0, v[128:129]
	s_mov_b32 m0, s57
	s_nop 0
	global_load_lds_dwordx4 v[220:221], off
	s_mov_b32 m0, s58
	s_nop 0
	global_load_lds_dwordx4 v[222:223], off
	s_waitcnt vmcnt(8)
	s_waitcnt lgkmcnt(0)
	s_barrier
; #define PG8_STAGE(bufoff, gbase, voff) do { _Pragma("unroll") for (int _i = 0; _i < 2; ++_i) \
;         __builtin_amdgcn_global_load_lds((const unsigned*)((const char*)(gbase) + (voff)[_i]), (LAS unsigned*)(lds + (bufoff) + ldsw + _i * 8192), 16, 0, 0); } while (0)
; #define PG8_LDA(dst, b, h) do { _Pragma("unroll") for (int m = 0; m < 4; ++m) _Pragma("unroll") for (int k = 0; k < 2; ++k) dst[m][k] = *(const LAS bf16x8*)(lds + PG8_SA(b, h) + aoff + m * 2048 + k * 1024); } while (0)
; #define PG8_LDB(dst, b, h) do { _Pragma("unroll") for (int n = 0; n < 2; ++n) _Pragma("unroll") for (int k = 0; k < 2; ++k) dst[n][k] = *(const LAS bf16x8*)(lds + PG8_SB(b, h) + boff + n * 2048 + k * 1024); } while (0)
; #define PG8_MMA(ai, bj, At, Bt) do { __builtin_amdgcn_s_setprio(1); _Pragma("unroll") for (int m = 0; m < 4; ++m) _Pragma("unroll") for (int n = 0; n < 2; ++n) _Pragma("unroll") for (int k = 0; k < 2; ++k) \
;         acc[ai][bj][m][n] = __builtin_amdgcn_mfma_f32_16x16x32_bf16(Bt[n][k], At[m][k], acc[ai][bj][m][n], 0, 0, 0); __builtin_amdgcn_s_setprio(0); } while (0)
; #define PG8_WAIT_V(n) asm volatile("s_waitcnt vmcnt(" #n ")" ::: "memory")
; #define PG8_WAIT_L(n) asm volatile("s_waitcnt lgkmcnt(" #n ")" ::: "memory")
; #define PG8_BAR __builtin_amdgcn_s_barrier()
; #define PG8_SCHED __builtin_amdgcn_sched_barrier(0)
; template <class Epi>
; __device__ __forceinline__ void gemm_phase(LAS unsigned char* lds, const Gemm g, const Sched& S, const Epi& E) {
;     ...
;             PG8_LDA(At, 0, 1); PG8_STAGE(PG8_SB(0, 0), b2, voffB); PG8_STAGE(PG8_SB(0, 1), b2 + hstepB, voffB); PG8_STAGE(PG8_SA(0, 0), a2, voffA);
;             PG8_WAIT_V(8); PG8_WAIT_L(0); PG8_BAR; PG8_MMA(1, 0, At, B0); PG8_MMA(1, 1, At, B1); PG8_BAR; PG8_SCHED;
;             PG8_LDB(B0, 1, 0); PG8_LDB(B1, 1, 1); PG8_SCHED; PG8_LDA(At, 1, 0); PG8_STAGE(PG8_SA(0, 1), a2 + hstepA, voffA);
;             PG8_WAIT_V(8); PG8_WAIT_L(0); PG8_BAR; PG8_MMA(0, 0, At, B0); PG8_MMA(0, 1, At, B1); PG8_BAR; PG8_SCHED;
	s_waitcnt lgkmcnt(0)
	v_mfma_f32_16x16x32_bf16 v[60:63], v[146:149], v[178:181], v[60:63]
	v_mfma_f32_16x16x32_bf16 v[56:59], v[154:157], v[178:181], v[56:59]
	v_mfma_f32_16x16x32_bf16 v[44:47], v[146:149], v[192:195], v[44:47]
	v_mfma_f32_16x16x32_bf16 v[40:43], v[154:157], v[192:195], v[40:43]
	v_mfma_f32_16x16x32_bf16 v[28:31], v[146:149], v[204:207], v[28:31]
	v_mfma_f32_16x16x32_bf16 v[24:27], v[154:157], v[204:207], v[24:27]
	v_mfma_f32_16x16x32_bf16 v[12:15], v[146:149], v[212:215], v[12:15]
	v_mfma_f32_16x16x32_bf16 v[8:11], v[154:157], v[212:215], v[8:11]
	v_mfma_f32_16x16x32_bf16 v[60:63], v[150:153], v[182:185], v[60:63]
	v_mfma_f32_16x16x32_bf16 v[56:59], v[158:161], v[182:185], v[56:59]
	v_mfma_f32_16x16x32_bf16 v[44:47], v[150:153], v[196:199], v[44:47]
	v_mfma_f32_16x16x32_bf16 v[40:43], v[158:161], v[196:199], v[40:43]
	v_mfma_f32_16x16x32_bf16 v[28:31], v[150:153], v[208:211], v[28:31]
	v_mfma_f32_16x16x32_bf16 v[24:27], v[158:161], v[208:211], v[24:27]
	v_mfma_f32_16x16x32_bf16 v[12:15], v[150:153], v[216:219], v[12:15]
	v_mfma_f32_16x16x32_bf16 v[8:11], v[158:161], v[216:219], v[8:11]
	v_mfma_f32_16x16x32_bf16 v[52:55], v[162:165], v[178:181], v[52:55]
	v_mfma_f32_16x16x32_bf16 v[48:51], v[170:173], v[178:181], v[48:51]
	v_mfma_f32_16x16x32_bf16 v[36:39], v[162:165], v[192:195], v[36:39]
	v_mfma_f32_16x16x32_bf16 v[32:35], v[170:173], v[192:195], v[32:35]
	v_mfma_f32_16x16x32_bf16 v[20:23], v[162:165], v[204:207], v[20:23]
	v_mfma_f32_16x16x32_bf16 v[16:19], v[170:173], v[204:207], v[16:19]
	v_mfma_f32_16x16x32_bf16 v[4:7], v[162:165], v[212:215], v[4:7]
	v_mfma_f32_16x16x32_bf16 v[0:3], v[170:173], v[212:215], v[0:3]
	v_mfma_f32_16x16x32_bf16 v[52:55], v[166:169], v[182:185], v[52:55]
	v_mfma_f32_16x16x32_bf16 v[48:51], v[174:177], v[182:185], v[48:51]
	v_mfma_f32_16x16x32_bf16 v[36:39], v[166:169], v[196:199], v[36:39]
	v_mfma_f32_16x16x32_bf16 v[32:35], v[174:177], v[196:199], v[32:35]
	v_mfma_f32_16x16x32_bf16 v[20:23], v[166:169], v[208:211], v[20:23]
	v_mfma_f32_16x16x32_bf16 v[16:19], v[174:177], v[208:211], v[16:19]
	v_mfma_f32_16x16x32_bf16 v[4:7], v[166:169], v[216:219], v[4:7]
	v_mfma_f32_16x16x32_bf16 v[0:3], v[174:177], v[216:219], v[0:3]
	s_barrier
	s_add_i32 s84, 0, 0x18000
	s_add_i32 s85, 0, 0x1c000
	v_add_u32_e32 v158, s84, v144
	v_add_u32_e32 v174, s85, v144
	ds_read_b128 v[146:149], v158
	ds_read_b128 v[150:153], v158 offset:1024
	ds_read_b128 v[154:157], v158 offset:2048
	ds_read_b128 v[158:161], v158 offset:3072
	ds_read_b128 v[162:165], v174
	ds_read_b128 v[166:169], v174 offset:1024
	ds_read_b128 v[170:173], v174 offset:2048
	ds_read_b128 v[174:177], v174 offset:3072
	s_add_u32 s44, s44, 0xb0000
	s_addc_u32 s45, s45, 0
	s_mov_b32 m0, s59
	v_lshl_add_u64 v[224:225], s[44:45], 0, v[128:129]
	ds_read_b128 v[178:181], v145 offset:32768
	ds_read_b128 v[182:185], v145 offset:33792
	ds_read_b128 v[192:195], v145 offset:34816
	ds_read_b128 v[196:199], v145 offset:35840
	ds_read_b128 v[204:207], v145 offset:36864
	ds_read_b128 v[208:211], v145 offset:37888
	ds_read_b128 v[212:215], v145 offset:38912
	ds_read_b128 v[216:219], v145 offset:39936
	global_load_lds_dwordx4 v[224:225], off
	v_lshl_add_u64 v[224:225], s[44:45], 0, v[132:133]
	s_mov_b32 m0, s60
	s_nop 0
	global_load_lds_dwordx4 v[224:225], off
	s_waitcnt vmcnt(8)
	s_waitcnt lgkmcnt(0)
	s_barrier
	s_waitcnt lgkmcnt(0)
	v_mfma_f32_16x16x32_bf16 v[124:127], v[146:149], v[178:181], v[124:127]
	v_mfma_f32_16x16x32_bf16 v[120:123], v[154:157], v[178:181], v[120:123]
	v_mfma_f32_16x16x32_bf16 v[108:111], v[146:149], v[192:195], v[108:111]
	v_mfma_f32_16x16x32_bf16 v[104:107], v[154:157], v[192:195], v[104:107]
	v_mfma_f32_16x16x32_bf16 v[92:95], v[146:149], v[204:207], v[92:95]
	v_mfma_f32_16x16x32_bf16 v[88:91], v[154:157], v[204:207], v[88:91]
	v_mfma_f32_16x16x32_bf16 v[76:79], v[146:149], v[212:215], v[76:79]
	v_mfma_f32_16x16x32_bf16 v[72:75], v[154:157], v[212:215], v[72:75]
	v_mfma_f32_16x16x32_bf16 v[124:127], v[150:153], v[182:185], v[124:127]
	v_mfma_f32_16x16x32_bf16 v[120:123], v[158:161], v[182:185], v[120:123]
	v_mfma_f32_16x16x32_bf16 v[108:111], v[150:153], v[196:199], v[108:111]
	v_mfma_f32_16x16x32_bf16 v[104:107], v[158:161], v[196:199], v[104:107]
	v_mfma_f32_16x16x32_bf16 v[92:95], v[150:153], v[208:211], v[92:95]
	v_mfma_f32_16x16x32_bf16 v[88:91], v[158:161], v[208:211], v[88:91]
	v_mfma_f32_16x16x32_bf16 v[76:79], v[150:153], v[216:219], v[76:79]
	v_mfma_f32_16x16x32_bf16 v[72:75], v[158:161], v[216:219], v[72:75]
	v_mfma_f32_16x16x32_bf16 v[116:119], v[162:165], v[178:181], v[116:119]
	v_mfma_f32_16x16x32_bf16 v[112:115], v[170:173], v[178:181], v[112:115]
	v_mfma_f32_16x16x32_bf16 v[100:103], v[162:165], v[192:195], v[100:103]
	v_mfma_f32_16x16x32_bf16 v[96:99], v[170:173], v[192:195], v[96:99]
	v_mfma_f32_16x16x32_bf16 v[84:87], v[162:165], v[204:207], v[84:87]
	v_mfma_f32_16x16x32_bf16 v[80:83], v[170:173], v[204:207], v[80:83]
	v_mfma_f32_16x16x32_bf16 v[68:71], v[162:165], v[212:215], v[68:71]
	v_mfma_f32_16x16x32_bf16 v[64:67], v[170:173], v[212:215], v[64:67]
	v_mfma_f32_16x16x32_bf16 v[116:119], v[166:169], v[182:185], v[116:119]
	v_mfma_f32_16x16x32_bf16 v[112:115], v[174:177], v[182:185], v[112:115]
	v_mfma_f32_16x16x32_bf16 v[100:103], v[166:169], v[196:199], v[100:103]
	v_mfma_f32_16x16x32_bf16 v[96:99], v[174:177], v[196:199], v[96:99]
	v_mfma_f32_16x16x32_bf16 v[84:87], v[166:169], v[208:211], v[84:87]
	v_mfma_f32_16x16x32_bf16 v[80:83], v[174:177], v[208:211], v[80:83]
	v_mfma_f32_16x16x32_bf16 v[68:71], v[166:169], v[216:219], v[68:71]
	v_mfma_f32_16x16x32_bf16 v[64:67], v[174:177], v[216:219], v[64:67]
	s_barrier
; #define PG8_STAGE(bufoff, gbase, voff) do { _Pragma("unroll") for (int _i = 0; _i < 2; ++_i) \
;         __builtin_amdgcn_global_load_lds((const unsigned*)((const char*)(gbase) + (voff)[_i]), (LAS unsigned*)(lds + (bufoff) + ldsw + _i * 8192), 16, 0, 0); } while (0)
; #define PG8_LDA(dst, b, h) do { _Pragma("unroll") for (int m = 0; m < 4; ++m) _Pragma("unroll") for (int k = 0; k < 2; ++k) dst[m][k] = *(const LAS bf16x8*)(lds + PG8_SA(b, h) + aoff + m * 2048 + k * 1024); } while (0)
; #define PG8_LDB(dst, b, h) do { _Pragma("unroll") for (int n = 0; n < 2; ++n) _Pragma("unroll") for (int k = 0; k < 2; ++k) dst[n][k] = *(const LAS bf16x8*)(lds + PG8_SB(b, h) + boff + n * 2048 + k * 1024); } while (0)
; #define PG8_MMA(ai, bj, At, Bt) do { __builtin_amdgcn_s_setprio(1); _Pragma("unroll") for (int m = 0; m < 4; ++m) _Pragma("unroll") for (int n = 0; n < 2; ++n) _Pragma("unroll") for (int k = 0; k < 2; ++k) \
;         acc[ai][bj][m][n] = __builtin_amdgcn_mfma_f32_16x16x32_bf16(Bt[n][k], At[m][k], acc[ai][bj][m][n], 0, 0, 0); __builtin_amdgcn_s_setprio(0); } while (0)
; #define PG8_WAIT_V(n) asm volatile("s_waitcnt vmcnt(" #n ")" ::: "memory")
; #define PG8_WAIT_L(n) asm volatile("s_waitcnt lgkmcnt(" #n ")" ::: "memory")
; #define PG8_BAR __builtin_amdgcn_s_barrier()
; #define PG8_SCHED __builtin_amdgcn_sched_barrier(0)
; template <class Epi>
; __device__ __forceinline__ void gemm_phase(LAS unsigned char* lds, const Gemm g, const Sched& S, const Epi& E) {
;     ...
;             PG8_LDB(B0, 1, 0); PG8_LDB(B1, 1, 1); PG8_SCHED; PG8_LDA(At, 1, 0); PG8_STAGE(PG8_SA(0, 1), a2 + hstepA, voffA);
;             PG8_WAIT_V(8); PG8_WAIT_L(0); PG8_BAR; PG8_MMA(0, 0, At, B0); PG8_MMA(0, 1, At, B1); PG8_BAR; PG8_SCHED;
;             PG8_LDA(At, 1, 1); PG8_STAGE(PG8_SB(1, 0), b3, voffB); PG8_STAGE(PG8_SB(1, 1), b3 + hstepB, voffB); PG8_STAGE(PG8_SA(1, 0), a3, voffA);
;             PG8_WAIT_V(8); PG8_WAIT_L(0); PG8_BAR; PG8_MMA(1, 0, At, B0); PG8_MMA(1, 1, At, B1); PG8_BAR; PG8_SCHED;
;         }
;         if (wr == 0) PG8_BAR;
	s_add_i32 s44, s84, s56
	v_lshl_add_u64 v[186:187], v[186:187], 0, s[8:9]
	s_mov_b32 m0, s44
	ds_read_b128 v[178:181], v145 offset:49152
	ds_read_b128 v[182:185], v145 offset:50176
	ds_read_b128 v[192:195], v145 offset:51200
	ds_read_b128 v[196:199], v145 offset:52224
	ds_read_b128 v[204:207], v145 offset:53248
	ds_read_b128 v[208:211], v145 offset:54272
	ds_read_b128 v[212:215], v145 offset:55296
	ds_read_b128 v[216:219], v145 offset:56320
	global_load_lds_dwordx4 v[186:187], off
	s_add_i32 m0, s44, 0x2000
	s_add_u32 s40, s40, 0xb0080
	v_lshl_add_u64 v[186:187], v[200:201], 0, s[8:9]
	s_addc_u32 s41, s41, 0
	s_add_i32 s44, s85, s56
	global_load_lds_dwordx4 v[186:187], off
	v_lshl_add_u64 v[186:187], s[40:41], 0, v[130:131]
	s_mov_b32 m0, s44
	s_nop 0
	global_load_lds_dwordx4 v[186:187], off
	v_lshl_add_u64 v[186:187], s[40:41], 0, v[134:135]
	s_add_i32 m0, s44, 0x2000
	s_nop 0
	global_load_lds_dwordx4 v[186:187], off
	v_lshl_add_u64 v[186:187], v[220:221], 0, s[8:9]
	s_mov_b32 m0, s62
	s_nop 0
	global_load_lds_dwordx4 v[186:187], off
	v_lshl_add_u64 v[186:187], v[222:223], 0, s[8:9]
	s_mov_b32 m0, s63
	s_nop 0
	global_load_lds_dwordx4 v[186:187], off
	s_waitcnt vmcnt(8)
	s_waitcnt lgkmcnt(0)
	s_barrier
	s_waitcnt lgkmcnt(0)
	v_mfma_f32_16x16x32_bf16 v[60:63], v[146:149], v[178:181], v[60:63]
	v_mfma_f32_16x16x32_bf16 v[56:59], v[154:157], v[178:181], v[56:59]
	v_mfma_f32_16x16x32_bf16 v[44:47], v[146:149], v[192:195], v[44:47]
	v_mfma_f32_16x16x32_bf16 v[40:43], v[154:157], v[192:195], v[40:43]
	v_mfma_f32_16x16x32_bf16 v[28:31], v[146:149], v[204:207], v[28:31]
	v_mfma_f32_16x16x32_bf16 v[24:27], v[154:157], v[204:207], v[24:27]
	v_mfma_f32_16x16x32_bf16 v[12:15], v[146:149], v[212:215], v[12:15]
	v_mfma_f32_16x16x32_bf16 v[8:11], v[154:157], v[212:215], v[8:11]
	v_mfma_f32_16x16x32_bf16 v[60:63], v[150:153], v[182:185], v[60:63]
	v_mfma_f32_16x16x32_bf16 v[56:59], v[158:161], v[182:185], v[56:59]
	v_mfma_f32_16x16x32_bf16 v[44:47], v[150:153], v[196:199], v[44:47]
	v_mfma_f32_16x16x32_bf16 v[40:43], v[158:161], v[196:199], v[40:43]
	v_mfma_f32_16x16x32_bf16 v[28:31], v[150:153], v[208:211], v[28:31]
	v_mfma_f32_16x16x32_bf16 v[24:27], v[158:161], v[208:211], v[24:27]
	v_mfma_f32_16x16x32_bf16 v[12:15], v[150:153], v[216:219], v[12:15]
	v_mfma_f32_16x16x32_bf16 v[8:11], v[158:161], v[216:219], v[8:11]
	v_mfma_f32_16x16x32_bf16 v[52:55], v[162:165], v[178:181], v[52:55]
	v_mfma_f32_16x16x32_bf16 v[48:51], v[170:173], v[178:181], v[48:51]
	v_mfma_f32_16x16x32_bf16 v[36:39], v[162:165], v[192:195], v[36:39]
	v_mfma_f32_16x16x32_bf16 v[32:35], v[170:173], v[192:195], v[32:35]
	v_mfma_f32_16x16x32_bf16 v[20:23], v[162:165], v[204:207], v[20:23]
	v_mfma_f32_16x16x32_bf16 v[16:19], v[170:173], v[204:207], v[16:19]
	v_mfma_f32_16x16x32_bf16 v[4:7], v[162:165], v[212:215], v[4:7]
	v_mfma_f32_16x16x32_bf16 v[0:3], v[170:173], v[212:215], v[0:3]
	v_mfma_f32_16x16x32_bf16 v[52:55], v[166:169], v[182:185], v[52:55]
	v_mfma_f32_16x16x32_bf16 v[48:51], v[174:177], v[182:185], v[48:51]
	v_mfma_f32_16x16x32_bf16 v[36:39], v[166:169], v[196:199], v[36:39]
	v_mfma_f32_16x16x32_bf16 v[32:35], v[174:177], v[196:199], v[32:35]
	v_mfma_f32_16x16x32_bf16 v[20:23], v[166:169], v[208:211], v[20:23]
	v_mfma_f32_16x16x32_bf16 v[16:19], v[174:177], v[208:211], v[16:19]
	v_mfma_f32_16x16x32_bf16 v[4:7], v[166:169], v[216:219], v[4:7]
	v_mfma_f32_16x16x32_bf16 v[0:3], v[174:177], v[216:219], v[0:3]
	s_barrier
	s_add_i32 s89, s89, 2
	s_add_u32 s28, s28, 0x100
	s_addc_u32 s29, s29, 0
	s_cmp_gt_u32 s89, 41
	s_cbranch_scc0 .LBB0_374
	s_and_b64 vcc, exec, s[14:15]
	s_cbranch_vccz .LBB0_377
	s_barrier

; #define PG8_STAGE(bufoff, gbase, voff) do { _Pragma("unroll") for (int _i = 0; _i < 2; ++_i) \
;         __builtin_amdgcn_global_load_lds((const unsigned*)((const char*)(gbase) + (voff)[_i]), (LAS unsigned*)(lds + (bufoff) + ldsw + _i * 8192), 16, 0, 0); } while (0)
; #define PG8_LDA(dst, b, h) do { _Pragma("unroll") for (int m = 0; m < 4; ++m) _Pragma("unroll") for (int k = 0; k < 2; ++k) dst[m][k] = *(const LAS bf16x8*)(lds + PG8_SA(b, h) + aoff + m * 2048 + k * 1024); } while (0)
; #define PG8_LDB(dst, b, h) do { _Pragma("unroll") for (int n = 0; n < 2; ++n) _Pragma("unroll") for (int k = 0; k < 2; ++k) dst[n][k] = *(const LAS bf16x8*)(lds + PG8_SB(b, h) + boff + n * 2048 + k * 1024); } while (0)
; #define PG8_MMA(ai, bj, At, Bt) do { __builtin_amdgcn_s_setprio(1); _Pragma("unroll") for (int m = 0; m < 4; ++m) _Pragma("unroll") for (int n = 0; n < 2; ++n) _Pragma("unroll") for (int k = 0; k < 2; ++k) \
;         acc[ai][bj][m][n] = __builtin_amdgcn_mfma_f32_16x16x32_bf16(Bt[n][k], At[m][k], acc[ai][bj][m][n], 0, 0, 0); __builtin_amdgcn_s_setprio(0); } while (0)
; #define PG8_WAIT_V(n) asm volatile("s_waitcnt vmcnt(" #n ")" ::: "memory")
; #define PG8_WAIT_L(n) asm volatile("s_waitcnt lgkmcnt(" #n ")" ::: "memory")
; #define PG8_BAR __builtin_amdgcn_s_barrier()
; #define PG8_SCHED __builtin_amdgcn_sched_barrier(0)
; template <class Epi>
; __device__ __forceinline__ void gemm_phase(LAS unsigned char* lds, const Gemm g, const Sched& S, const Epi& E) {
;     ...
;             PG8_LDB(B0, 0, 0); PG8_LDB(B1, 0, 1); PG8_SCHED; PG8_LDA(At, 0, 0); PG8_STAGE(PG8_SA(1, 1), a1 + hstepA, voffA);
;             PG8_WAIT_V(8); PG8_WAIT_L(0); PG8_BAR; PG8_MMA(0, 0, At, B0); PG8_MMA(0, 1, At, B1); PG8_BAR; PG8_SCHED;
;             PG8_LDA(At, 0, 1); PG8_STAGE(PG8_SB(0, 0), b2, voffB); PG8_STAGE(PG8_SB(0, 1), b2 + hstepB, voffB); PG8_STAGE(PG8_SA(0, 0), a2, voffA);
;             PG8_WAIT_V(8); PG8_WAIT_L(0); PG8_BAR; PG8_MMA(1, 0, At, B0); PG8_MMA(1, 1, At, B1); PG8_BAR; PG8_SCHED;
;             PG8_LDB(B0, 1, 0); PG8_LDB(B1, 1, 1); PG8_SCHED; PG8_LDA(At, 1, 0); PG8_STAGE(PG8_SA(0, 1), a2 + hstepA, voffA);
.LBB0_520:
	ds_read_b128 v[128:131], v160
	ds_read_b128 v[132:135], v160 offset:1024
	ds_read_b128 v[152:155], v160 offset:2048
	ds_read_b128 v[164:167], v160 offset:3072
	ds_read_b128 v[168:171], v161
	ds_read_b128 v[172:175], v161 offset:1024
	ds_read_b128 v[176:179], v161 offset:2048
	ds_read_b128 v[180:183], v161 offset:3072
	s_add_u32 s4, s2, 0xfffc0080
	s_addc_u32 s5, s3, -1
	s_cmp_eq_u32 s57, 12
	s_cselect_b32 s53, s0, s5
	s_cselect_b32 s52, s27, s4
	s_cselect_b32 s5, s25, s56
	s_cselect_b32 s4, s54, s55
	v_lshl_add_u64 v[200:201], s[2:3], 0, v[146:147]
	s_add_i32 m0, s10, 0xc000
	ds_read_b128 v[184:187], v162
	ds_read_b128 v[188:191], v162 offset:1024
	ds_read_b128 v[192:195], v162 offset:2048
	ds_read_b128 v[196:199], v162 offset:3072
	ds_read_b128 v[204:207], v162 offset:4096
	ds_read_b128 v[208:211], v162 offset:5120
	ds_read_b128 v[212:215], v162 offset:6144
	ds_read_b128 v[216:219], v162 offset:7168
	global_load_lds_dwordx4 v[200:201], off
	v_lshl_add_u64 v[200:201], s[2:3], 0, v[148:149]
	s_add_i32 m0, s10, 0xe000
	s_nop 0
	global_load_lds_dwordx4 v[200:201], off
	s_waitcnt vmcnt(8)
	s_waitcnt lgkmcnt(0)
	s_barrier
	s_waitcnt lgkmcnt(0)
	v_mfma_f32_16x16x32_bf16 v[124:127], v[128:131], v[184:187], v[124:127]
	v_mfma_f32_16x16x32_bf16 v[116:119], v[152:155], v[184:187], v[116:119]
	v_mfma_f32_16x16x32_bf16 v[108:111], v[128:131], v[192:195], v[108:111]
	v_mfma_f32_16x16x32_bf16 v[100:103], v[152:155], v[192:195], v[100:103]
	v_mfma_f32_16x16x32_bf16 v[92:95], v[128:131], v[204:207], v[92:95]
	v_mfma_f32_16x16x32_bf16 v[84:87], v[152:155], v[204:207], v[84:87]
	v_mfma_f32_16x16x32_bf16 v[76:79], v[128:131], v[212:215], v[76:79]
	v_mfma_f32_16x16x32_bf16 v[68:71], v[152:155], v[212:215], v[68:71]
	v_mfma_f32_16x16x32_bf16 v[124:127], v[132:135], v[188:191], v[124:127]
	v_mfma_f32_16x16x32_bf16 v[116:119], v[164:167], v[188:191], v[116:119]
	v_mfma_f32_16x16x32_bf16 v[108:111], v[132:135], v[196:199], v[108:111]
	v_mfma_f32_16x16x32_bf16 v[100:103], v[164:167], v[196:199], v[100:103]
	v_mfma_f32_16x16x32_bf16 v[92:95], v[132:135], v[208:211], v[92:95]
	v_mfma_f32_16x16x32_bf16 v[84:87], v[164:167], v[208:211], v[84:87]
	v_mfma_f32_16x16x32_bf16 v[76:79], v[132:135], v[216:219], v[76:79]
	v_mfma_f32_16x16x32_bf16 v[68:71], v[164:167], v[216:219], v[68:71]
	v_mfma_f32_16x16x32_bf16 v[120:123], v[168:171], v[184:187], v[120:123]
	v_mfma_f32_16x16x32_bf16 v[112:115], v[176:179], v[184:187], v[112:115]
	v_mfma_f32_16x16x32_bf16 v[104:107], v[168:171], v[192:195], v[104:107]
	v_mfma_f32_16x16x32_bf16 v[96:99], v[176:179], v[192:195], v[96:99]
	v_mfma_f32_16x16x32_bf16 v[88:91], v[168:171], v[204:207], v[88:91]
	v_mfma_f32_16x16x32_bf16 v[80:83], v[176:179], v[204:207], v[80:83]
	v_mfma_f32_16x16x32_bf16 v[72:75], v[168:171], v[212:215], v[72:75]
	v_mfma_f32_16x16x32_bf16 v[64:67], v[176:179], v[212:215], v[64:67]
	v_mfma_f32_16x16x32_bf16 v[120:123], v[172:175], v[188:191], v[120:123]
	v_mfma_f32_16x16x32_bf16 v[112:115], v[180:183], v[188:191], v[112:115]
	v_mfma_f32_16x16x32_bf16 v[104:107], v[172:175], v[196:199], v[104:107]
	v_mfma_f32_16x16x32_bf16 v[96:99], v[180:183], v[196:199], v[96:99]
	v_mfma_f32_16x16x32_bf16 v[88:91], v[172:175], v[208:211], v[88:91]
	v_mfma_f32_16x16x32_bf16 v[80:83], v[180:183], v[208:211], v[80:83]
	v_mfma_f32_16x16x32_bf16 v[72:75], v[172:175], v[216:219], v[72:75]
	v_mfma_f32_16x16x32_bf16 v[64:67], v[180:183], v[216:219], v[64:67]
	s_barrier
	s_add_i32 s58, s89, s86
	v_lshl_add_u64 v[200:201], s[4:5], 0, v[138:139]
	s_mov_b32 m0, s58
	ds_read_b128 v[184:187], v162 offset:16384
	ds_read_b128 v[188:191], v162 offset:17408
	ds_read_b128 v[192:195], v162 offset:18432
	ds_read_b128 v[196:199], v162 offset:19456
	ds_read_b128 v[204:207], v162 offset:20480
	ds_read_b128 v[208:211], v162 offset:21504
	ds_read_b128 v[212:215], v162 offset:22528
	ds_read_b128 v[216:219], v162 offset:23552
	global_load_lds_dwordx4 v[200:201], off
	s_add_i32 m0, s58, 0x2000
	s_add_u32 s58, s4, 0x40000
	v_lshl_add_u64 v[220:221], s[4:5], 0, v[142:143]
	s_addc_u32 s59, s5, 0
	s_add_i32 s60, s90, s86
	global_load_lds_dwordx4 v[220:221], off
	v_lshl_add_u64 v[222:223], s[58:59], 0, v[138:139]
	s_mov_b32 m0, s60
	v_lshl_add_u64 v[224:225], s[52:53], 0, v[140:141]
	global_load_lds_dwordx4 v[222:223], off
	v_lshl_add_u64 v[222:223], s[58:59], 0, v[142:143]
	s_add_i32 m0, s60, 0x2000
	s_nop 0
	global_load_lds_dwordx4 v[222:223], off
	v_lshl_add_u64 v[222:223], s[52:53], 0, v[136:137]
	s_mov_b32 m0, s10
	s_nop 0
	global_load_lds_dwordx4 v[222:223], off
	s_mov_b32 m0, s11
	s_nop 0
	global_load_lds_dwordx4 v[224:225], off
	s_waitcnt vmcnt(8)
	s_waitcnt lgkmcnt(0)
	s_barrier
	s_waitcnt lgkmcnt(0)
	s_cmp_eq_u32 s46, 64
	s_cbranch_scc1 .Lp4_padskip_1
	v_mfma_f32_16x16x32_bf16 v[60:63], v[128:131], v[184:187], v[60:63]
	v_mfma_f32_16x16x32_bf16 v[52:55], v[152:155], v[184:187], v[52:55]
	v_mfma_f32_16x16x32_bf16 v[44:47], v[128:131], v[192:195], v[44:47]
	v_mfma_f32_16x16x32_bf16 v[36:39], v[152:155], v[192:195], v[36:39]
	v_mfma_f32_16x16x32_bf16 v[28:31], v[128:131], v[204:207], v[28:31]
	v_mfma_f32_16x16x32_bf16 v[20:23], v[152:155], v[204:207], v[20:23]
	v_mfma_f32_16x16x32_bf16 v[12:15], v[128:131], v[212:215], v[12:15]
	v_mfma_f32_16x16x32_bf16 v[4:7], v[152:155], v[212:215], v[4:7]
	v_mfma_f32_16x16x32_bf16 v[60:63], v[132:135], v[188:191], v[60:63]
	v_mfma_f32_16x16x32_bf16 v[52:55], v[164:167], v[188:191], v[52:55]
	v_mfma_f32_16x16x32_bf16 v[44:47], v[132:135], v[196:199], v[44:47]
	v_mfma_f32_16x16x32_bf16 v[36:39], v[164:167], v[196:199], v[36:39]
	v_mfma_f32_16x16x32_bf16 v[28:31], v[132:135], v[208:211], v[28:31]
	v_mfma_f32_16x16x32_bf16 v[20:23], v[164:167], v[208:211], v[20:23]
	v_mfma_f32_16x16x32_bf16 v[12:15], v[132:135], v[216:219], v[12:15]
	v_mfma_f32_16x16x32_bf16 v[4:7], v[164:167], v[216:219], v[4:7]
	v_mfma_f32_16x16x32_bf16 v[56:59], v[168:171], v[184:187], v[56:59]
	v_mfma_f32_16x16x32_bf16 v[48:51], v[176:179], v[184:187], v[48:51]
	v_mfma_f32_16x16x32_bf16 v[40:43], v[168:171], v[192:195], v[40:43]
	v_mfma_f32_16x16x32_bf16 v[32:35], v[176:179], v[192:195], v[32:35]
	v_mfma_f32_16x16x32_bf16 v[24:27], v[168:171], v[204:207], v[24:27]
	v_mfma_f32_16x16x32_bf16 v[16:19], v[176:179], v[204:207], v[16:19]
	v_mfma_f32_16x16x32_bf16 v[8:11], v[168:171], v[212:215], v[8:11]
	v_mfma_f32_16x16x32_bf16 v[0:3], v[176:179], v[212:215], v[0:3]
	v_mfma_f32_16x16x32_bf16 v[56:59], v[172:175], v[188:191], v[56:59]
	v_mfma_f32_16x16x32_bf16 v[48:51], v[180:183], v[188:191], v[48:51]
	v_mfma_f32_16x16x32_bf16 v[40:43], v[172:175], v[196:199], v[40:43]
	v_mfma_f32_16x16x32_bf16 v[32:35], v[180:183], v[196:199], v[32:35]
	v_mfma_f32_16x16x32_bf16 v[24:27], v[172:175], v[208:211], v[24:27]
	v_mfma_f32_16x16x32_bf16 v[16:19], v[180:183], v[208:211], v[16:19]
	v_mfma_f32_16x16x32_bf16 v[8:11], v[172:175], v[216:219], v[8:11]
	v_mfma_f32_16x16x32_bf16 v[0:3], v[180:183], v[216:219], v[0:3]
; #define PG8_STAGE(bufoff, gbase, voff) do { _Pragma("unroll") for (int _i = 0; _i < 2; ++_i) \
;         __builtin_amdgcn_global_load_lds((const unsigned*)((const char*)(gbase) + (voff)[_i]), (LAS unsigned*)(lds + (bufoff) + ldsw + _i * 8192), 16, 0, 0); } while (0)
; #define PG8_LDA(dst, b, h) do { _Pragma("unroll") for (int m = 0; m < 4; ++m) _Pragma("unroll") for (int k = 0; k < 2; ++k) dst[m][k] = *(const LAS bf16x8*)(lds + PG8_SA(b, h) + aoff + m * 2048 + k * 1024); } while (0)
; #define PG8_LDB(dst, b, h) do { _Pragma("unroll") for (int n = 0; n < 2; ++n) _Pragma("unroll") for (int k = 0; k < 2; ++k) dst[n][k] = *(const LAS bf16x8*)(lds + PG8_SB(b, h) + boff + n * 2048 + k * 1024); } while (0)
; #define PG8_MMA(ai, bj, At, Bt) do { __builtin_amdgcn_s_setprio(1); _Pragma("unroll") for (int m = 0; m < 4; ++m) _Pragma("unroll") for (int n = 0; n < 2; ++n) _Pragma("unroll") for (int k = 0; k < 2; ++k) \
;         acc[ai][bj][m][n] = __builtin_amdgcn_mfma_f32_16x16x32_bf16(Bt[n][k], At[m][k], acc[ai][bj][m][n], 0, 0, 0); __builtin_amdgcn_s_setprio(0); } while (0)
; #define PG8_WAIT_V(n) asm volatile("s_waitcnt vmcnt(" #n ")" ::: "memory")
; #define PG8_WAIT_L(n) asm volatile("s_waitcnt lgkmcnt(" #n ")" ::: "memory")
; #define PG8_BAR __builtin_amdgcn_s_barrier()
; #define PG8_SCHED __builtin_amdgcn_sched_barrier(0)
; template <class Epi>
; __device__ __forceinline__ void gemm_phase(LAS unsigned char* lds, const Gemm g, const Sched& S, const Epi& E) {
;     ...
;             PG8_WAIT_V(8); PG8_WAIT_L(0); PG8_BAR; PG8_MMA(1, 0, At, B0); PG8_MMA(1, 1, At, B1); PG8_BAR; PG8_SCHED;
;             PG8_LDB(B0, 1, 0); PG8_LDB(B1, 1, 1); PG8_SCHED; PG8_LDA(At, 1, 0); PG8_STAGE(PG8_SA(0, 1), a2 + hstepA, voffA);
;             PG8_WAIT_V(8); PG8_WAIT_L(0); PG8_BAR; PG8_MMA(0, 0, At, B0); PG8_MMA(0, 1, At, B1); PG8_BAR; PG8_SCHED;
;             PG8_LDA(At, 1, 1); PG8_STAGE(PG8_SB(1, 0), b3, voffB); PG8_STAGE(PG8_SB(1, 1), b3 + hstepB, voffB); PG8_STAGE(PG8_SA(1, 0), a3, voffA);
;             PG8_WAIT_V(8); PG8_WAIT_L(0); PG8_BAR; PG8_MMA(1, 0, At, B0); PG8_MMA(1, 1, At, B1); PG8_BAR; PG8_SCHED;
.Lp4_padskip_1:
	s_barrier
	s_add_i32 s58, 0, 0x18000
	v_add_u32_e32 v144, s58, v158
	s_add_i32 s59, 0, 0x1c000
	ds_read_b128 v[128:131], v144
	ds_read_b128 v[132:135], v144 offset:1024
	ds_read_b128 v[152:155], v144 offset:2048
	ds_read_b128 v[164:167], v144 offset:3072
	v_add_u32_e32 v144, s59, v158
	ds_read_b128 v[168:171], v144
	ds_read_b128 v[172:175], v144 offset:1024
	ds_read_b128 v[176:179], v144 offset:2048
	ds_read_b128 v[180:183], v144 offset:3072
	s_add_u32 s52, s52, 0x40000
	s_addc_u32 s53, s53, 0
	s_mov_b32 m0, s45
	v_lshl_add_u64 v[226:227], s[52:53], 0, v[136:137]
	ds_read_b128 v[184:187], v162 offset:32768
	ds_read_b128 v[188:191], v162 offset:33792
	ds_read_b128 v[192:195], v162 offset:34816
	ds_read_b128 v[196:199], v162 offset:35840
	ds_read_b128 v[204:207], v162 offset:36864
	ds_read_b128 v[208:211], v162 offset:37888
	ds_read_b128 v[212:215], v162 offset:38912
	ds_read_b128 v[216:219], v162 offset:39936
	global_load_lds_dwordx4 v[226:227], off
	v_lshl_add_u64 v[226:227], s[52:53], 0, v[140:141]
	s_mov_b32 m0, s47
	s_nop 0
	global_load_lds_dwordx4 v[226:227], off
	s_waitcnt vmcnt(8)
	s_waitcnt lgkmcnt(0)
	s_barrier
	s_waitcnt lgkmcnt(0)
	v_mfma_f32_16x16x32_bf16 v[124:127], v[128:131], v[184:187], v[124:127]
	v_mfma_f32_16x16x32_bf16 v[116:119], v[152:155], v[184:187], v[116:119]
	v_mfma_f32_16x16x32_bf16 v[108:111], v[128:131], v[192:195], v[108:111]
	v_mfma_f32_16x16x32_bf16 v[100:103], v[152:155], v[192:195], v[100:103]
	v_mfma_f32_16x16x32_bf16 v[92:95], v[128:131], v[204:207], v[92:95]
	v_mfma_f32_16x16x32_bf16 v[84:87], v[152:155], v[204:207], v[84:87]
	v_mfma_f32_16x16x32_bf16 v[76:79], v[128:131], v[212:215], v[76:79]
	v_mfma_f32_16x16x32_bf16 v[68:71], v[152:155], v[212:215], v[68:71]
	v_mfma_f32_16x16x32_bf16 v[124:127], v[132:135], v[188:191], v[124:127]
	v_mfma_f32_16x16x32_bf16 v[116:119], v[164:167], v[188:191], v[116:119]
	v_mfma_f32_16x16x32_bf16 v[108:111], v[132:135], v[196:199], v[108:111]
	v_mfma_f32_16x16x32_bf16 v[100:103], v[164:167], v[196:199], v[100:103]
	v_mfma_f32_16x16x32_bf16 v[92:95], v[132:135], v[208:211], v[92:95]
	v_mfma_f32_16x16x32_bf16 v[84:87], v[164:167], v[208:211], v[84:87]
	v_mfma_f32_16x16x32_bf16 v[76:79], v[132:135], v[216:219], v[76:79]
	v_mfma_f32_16x16x32_bf16 v[68:71], v[164:167], v[216:219], v[68:71]
	v_mfma_f32_16x16x32_bf16 v[120:123], v[168:171], v[184:187], v[120:123]
	v_mfma_f32_16x16x32_bf16 v[112:115], v[176:179], v[184:187], v[112:115]
	v_mfma_f32_16x16x32_bf16 v[104:107], v[168:171], v[192:195], v[104:107]
	v_mfma_f32_16x16x32_bf16 v[96:99], v[176:179], v[192:195], v[96:99]
	v_mfma_f32_16x16x32_bf16 v[88:91], v[168:171], v[204:207], v[88:91]
	v_mfma_f32_16x16x32_bf16 v[80:83], v[176:179], v[204:207], v[80:83]
	v_mfma_f32_16x16x32_bf16 v[72:75], v[168:171], v[212:215], v[72:75]
	v_mfma_f32_16x16x32_bf16 v[64:67], v[176:179], v[212:215], v[64:67]
	v_mfma_f32_16x16x32_bf16 v[120:123], v[172:175], v[188:191], v[120:123]
	v_mfma_f32_16x16x32_bf16 v[112:115], v[180:183], v[188:191], v[112:115]
	v_mfma_f32_16x16x32_bf16 v[104:107], v[172:175], v[196:199], v[104:107]
	v_mfma_f32_16x16x32_bf16 v[96:99], v[180:183], v[196:199], v[96:99]
	v_mfma_f32_16x16x32_bf16 v[88:91], v[172:175], v[208:211], v[88:91]
	v_mfma_f32_16x16x32_bf16 v[80:83], v[180:183], v[208:211], v[80:83]
	v_mfma_f32_16x16x32_bf16 v[72:75], v[172:175], v[216:219], v[72:75]
	v_mfma_f32_16x16x32_bf16 v[64:67], v[180:183], v[216:219], v[64:67]
	s_barrier
	s_add_i32 s52, s58, s86
	v_lshl_add_u64 v[200:201], v[200:201], 0, s[14:15]
	s_mov_b32 m0, s52
	ds_read_b128 v[184:187], v162 offset:49152
	ds_read_b128 v[188:191], v162 offset:50176
	ds_read_b128 v[192:195], v162 offset:51200
	ds_read_b128 v[196:199], v162 offset:52224
	ds_read_b128 v[204:207], v162 offset:53248
	ds_read_b128 v[208:211], v162 offset:54272
	ds_read_b128 v[212:215], v162 offset:55296
	ds_read_b128 v[216:219], v162 offset:56320
	global_load_lds_dwordx4 v[200:201], off
	s_add_i32 m0, s52, 0x2000
	s_add_u32 s4, s4, 0x40080
	v_lshl_add_u64 v[200:201], v[220:221], 0, s[14:15]
	s_addc_u32 s5, s5, 0
	s_add_i32 s52, s59, s86
	global_load_lds_dwordx4 v[200:201], off
	v_lshl_add_u64 v[200:201], s[4:5], 0, v[138:139]
	s_mov_b32 m0, s52
	s_nop 0
	global_load_lds_dwordx4 v[200:201], off
	v_lshl_add_u64 v[200:201], s[4:5], 0, v[142:143]
	s_add_i32 m0, s52, 0x2000
	s_nop 0
	global_load_lds_dwordx4 v[200:201], off
	v_lshl_add_u64 v[200:201], v[222:223], 0, s[14:15]
	s_mov_b32 m0, s87
	s_nop 0
	global_load_lds_dwordx4 v[200:201], off
	v_lshl_add_u64 v[200:201], v[224:225], 0, s[14:15]
	s_mov_b32 m0, s88
	s_nop 0
	global_load_lds_dwordx4 v[200:201], off
	s_waitcnt vmcnt(8)
	s_waitcnt lgkmcnt(0)
	s_barrier
	s_waitcnt lgkmcnt(0)
	s_cmp_eq_u32 s46, 64
	s_cbranch_scc1 .Lp4_padskip_3
	v_mfma_f32_16x16x32_bf16 v[60:63], v[128:131], v[184:187], v[60:63]
	v_mfma_f32_16x16x32_bf16 v[52:55], v[152:155], v[184:187], v[52:55]
	v_mfma_f32_16x16x32_bf16 v[44:47], v[128:131], v[192:195], v[44:47]
	v_mfma_f32_16x16x32_bf16 v[36:39], v[152:155], v[192:195], v[36:39]
	v_mfma_f32_16x16x32_bf16 v[28:31], v[128:131], v[204:207], v[28:31]
	v_mfma_f32_16x16x32_bf16 v[20:23], v[152:155], v[204:207], v[20:23]
	v_mfma_f32_16x16x32_bf16 v[12:15], v[128:131], v[212:215], v[12:15]
	v_mfma_f32_16x16x32_bf16 v[4:7], v[152:155], v[212:215], v[4:7]
	v_mfma_f32_16x16x32_bf16 v[60:63], v[132:135], v[188:191], v[60:63]
	v_mfma_f32_16x16x32_bf16 v[52:55], v[164:167], v[188:191], v[52:55]
	v_mfma_f32_16x16x32_bf16 v[44:47], v[132:135], v[196:199], v[44:47]
	v_mfma_f32_16x16x32_bf16 v[36:39], v[164:167], v[196:199], v[36:39]
	v_mfma_f32_16x16x32_bf16 v[28:31], v[132:135], v[208:211], v[28:31]
	v_mfma_f32_16x16x32_bf16 v[20:23], v[164:167], v[208:211], v[20:23]
	v_mfma_f32_16x16x32_bf16 v[12:15], v[132:135], v[216:219], v[12:15]
	v_mfma_f32_16x16x32_bf16 v[4:7], v[164:167], v[216:219], v[4:7]
	v_mfma_f32_16x16x32_bf16 v[56:59], v[168:171], v[184:187], v[56:59]
	v_mfma_f32_16x16x32_bf16 v[48:51], v[176:179], v[184:187], v[48:51]
	v_mfma_f32_16x16x32_bf16 v[40:43], v[168:171], v[192:195], v[40:43]
	v_mfma_f32_16x16x32_bf16 v[32:35], v[176:179], v[192:195], v[32:35]
	v_mfma_f32_16x16x32_bf16 v[24:27], v[168:171], v[204:207], v[24:27]
	v_mfma_f32_16x16x32_bf16 v[16:19], v[176:179], v[204:207], v[16:19]
	v_mfma_f32_16x16x32_bf16 v[8:11], v[168:171], v[212:215], v[8:11]
	v_mfma_f32_16x16x32_bf16 v[0:3], v[176:179], v[212:215], v[0:3]
	v_mfma_f32_16x16x32_bf16 v[56:59], v[172:175], v[188:191], v[56:59]
	v_mfma_f32_16x16x32_bf16 v[48:51], v[180:183], v[188:191], v[48:51]
	v_mfma_f32_16x16x32_bf16 v[40:43], v[172:175], v[196:199], v[40:43]
	v_mfma_f32_16x16x32_bf16 v[32:35], v[180:183], v[196:199], v[32:35]
	v_mfma_f32_16x16x32_bf16 v[24:27], v[172:175], v[208:211], v[24:27]
	v_mfma_f32_16x16x32_bf16 v[16:19], v[180:183], v[208:211], v[16:19]
	v_mfma_f32_16x16x32_bf16 v[8:11], v[172:175], v[216:219], v[8:11]
	v_mfma_f32_16x16x32_bf16 v[0:3], v[180:183], v[216:219], v[0:3]
; #define PG8_MMA(ai, bj, At, Bt) do { __builtin_amdgcn_s_setprio(1); _Pragma("unroll") for (int m = 0; m < 4; ++m) _Pragma("unroll") for (int n = 0; n < 2; ++n) _Pragma("unroll") for (int k = 0; k < 2; ++k) \
;         acc[ai][bj][m][n] = __builtin_amdgcn_mfma_f32_16x16x32_bf16(Bt[n][k], At[m][k], acc[ai][bj][m][n], 0, 0, 0); __builtin_amdgcn_s_setprio(0); } while (0)
; #define PG8_WAIT_V(n) asm volatile("s_waitcnt vmcnt(" #n ")" ::: "memory")
; #define PG8_WAIT_L(n) asm volatile("s_waitcnt lgkmcnt(" #n ")" ::: "memory")
; #define PG8_BAR __builtin_amdgcn_s_barrier()
; #define PG8_SCHED __builtin_amdgcn_sched_barrier(0)
; template <class Epi>
; __device__ __forceinline__ void gemm_phase(LAS unsigned char* lds, const Gemm g, const Sched& S, const Epi& E) {
;     ...
;             PG8_WAIT_V(8); PG8_WAIT_L(0); PG8_BAR; PG8_MMA(1, 0, At, B0); PG8_MMA(1, 1, At, B1); PG8_BAR; PG8_SCHED;
;         }
;         if (wr == 0) PG8_BAR;
;     __device__ __forceinline__ void operator()(AccRef acc, const Unit& u, int wr, int wc, int fr, int fq) const {
;         const int pn = u.pn, cw = wc * 32 + 8 * fq;
;         if (pn >= 17 && pn < 25) {
.Lp4_padskip_3:
	s_barrier
	s_add_i32 s57, s57, 2
	s_add_u32 s2, s2, 0x100
	s_addc_u32 s3, s3, 0
	s_add_u32 s55, s55, 0x100
	s_addc_u32 s56, s56, 0
	s_cmp_gt_u32 s57, 13
	s_cbranch_scc0 .LBB0_520
	s_and_b64 vcc, exec, s[20:21]
	s_cbranch_vccnz .LBB0_525
	s_sub_i32 s0, s44, 17
	s_cmp_gt_u32 s0, 7
	s_mov_b64 s[2:3], -1
	s_cbranch_scc1 .LBB0_526

; #define PG8_STAGE(bufoff, gbase, voff) do { _Pragma("unroll") for (int _i = 0; _i < 2; ++_i) \
;         __builtin_amdgcn_global_load_lds((const unsigned*)((const char*)(gbase) + (voff)[_i]), (LAS unsigned*)(lds + (bufoff) + ldsw + _i * 8192), 16, 0, 0); } while (0)
; #define PG8_LDA(dst, b, h) do { _Pragma("unroll") for (int m = 0; m < 4; ++m) _Pragma("unroll") for (int k = 0; k < 2; ++k) dst[m][k] = *(const LAS bf16x8*)(lds + PG8_SA(b, h) + aoff + m * 2048 + k * 1024); } while (0)
; #define PG8_LDB(dst, b, h) do { _Pragma("unroll") for (int n = 0; n < 2; ++n) _Pragma("unroll") for (int k = 0; k < 2; ++k) dst[n][k] = *(const LAS bf16x8*)(lds + PG8_SB(b, h) + boff + n * 2048 + k * 1024); } while (0)
; #define PG8_MMA(ai, bj, At, Bt) do { __builtin_amdgcn_s_setprio(1); _Pragma("unroll") for (int m = 0; m < 4; ++m) _Pragma("unroll") for (int n = 0; n < 2; ++n) _Pragma("unroll") for (int k = 0; k < 2; ++k) \
;         acc[ai][bj][m][n] = __builtin_amdgcn_mfma_f32_16x16x32_bf16(Bt[n][k], At[m][k], acc[ai][bj][m][n], 0, 0, 0); __builtin_amdgcn_s_setprio(0); } while (0)
; #define PG8_WAIT_V(n) asm volatile("s_waitcnt vmcnt(" #n ")" ::: "memory")
; #define PG8_WAIT_L(n) asm volatile("s_waitcnt lgkmcnt(" #n ")" ::: "memory")
; #define PG8_BAR __builtin_amdgcn_s_barrier()
; #define PG8_SCHED __builtin_amdgcn_sched_barrier(0)
; template <class Epi>
; __device__ __forceinline__ void gemm_phase(LAS unsigned char* lds, const Gemm g, const Sched& S, const Epi& E) {
;     ...
;         for (int t = 0; t < nt; t += 2) {
;             const bool last = (t == nt - 2);
;             const char* a1 = cA + (size_t)(t + 1) * kstep;
;             const char* a2 = last ? nA : cA + (size_t)(t + 2) * kstep; const char* b2 = last ? nB : cB + (size_t)(t + 2) * kstep;
;             const char* a3 = a2 + kstep; const char* b3 = b2 + kstep;
;             PG8_LDB(B0, 0, 0); PG8_LDB(B1, 0, 1); PG8_SCHED; PG8_LDA(At, 0, 0); PG8_STAGE(PG8_SA(1, 1), a1 + hstepA, voffA);
;             PG8_WAIT_V(8); PG8_WAIT_L(0); PG8_BAR; PG8_MMA(0, 0, At, B0); PG8_MMA(0, 1, At, B1); PG8_BAR; PG8_SCHED;
;             PG8_LDA(At, 0, 1); PG8_STAGE(PG8_SB(0, 0), b2, voffB); PG8_STAGE(PG8_SB(0, 1), b2 + hstepB, voffB); PG8_STAGE(PG8_SA(0, 0), a2, voffA);
.LBB0_773:
	s_add_u32 s60, s46, s74
	s_addc_u32 s61, s47, s75
	s_add_u32 s62, s60, 0x100
	s_addc_u32 s63, s61, 0
	s_and_b64 s[58:59], s[56:57], exec
	s_cselect_b32 s77, s3, s63
	s_cselect_b32 s76, s5, s62
	s_add_u32 s58, s52, s74
	s_addc_u32 s59, s53, s75
	s_add_u32 s58, s58, 0x100
	s_addc_u32 s59, s59, 0
	s_and_b64 s[56:57], s[56:57], exec
	s_cselect_b32 s79, s25, s59
	s_cselect_b32 s78, s27, s58
	s_add_u32 s86, s60, 0x10080
	ds_read_b128 v[80:83], v162
	ds_read_b128 v[84:87], v162 offset:1024
	ds_read_b128 v[136:139], v162 offset:2048
	ds_read_b128 v[140:143], v162 offset:3072
	ds_read_b128 v[154:157], v163
	ds_read_b128 v[166:169], v163 offset:1024
	ds_read_b128 v[170:173], v163 offset:2048
	ds_read_b128 v[174:177], v163 offset:3072
	s_addc_u32 s87, s61, 0
	s_add_i32 s67, s96, s15
	s_add_i32 s64, s67, 0x2000
	s_add_u32 s82, s78, 0x10000
	s_addc_u32 s83, s79, 0
	s_add_i32 s66, s97, s15
	s_add_i32 s65, s66, 0x2000
	s_add_i32 s63, 0, 0x18000
	s_add_i32 s62, 0, 0x1c000
	s_add_u32 s74, s76, 0x10000
	s_addc_u32 s75, s77, 0
	s_add_i32 s61, s63, s15
	s_add_i32 s59, s61, 0x2000
	s_add_u32 s56, s78, 0x10080
	s_addc_u32 s57, s79, 0
	s_add_i32 s60, s62, s15
	s_add_i32 s58, s60, 0x2000
	s_mov_b32 m0, s88
	v_lshl_add_u64 v[212:213], s[86:87], 0, v[144:145]
	ds_read_b128 v[178:181], v164
	ds_read_b128 v[182:185], v164 offset:1024
	ds_read_b128 v[186:189], v164 offset:2048
	ds_read_b128 v[190:193], v164 offset:3072
	ds_read_b128 v[194:197], v164 offset:4096
	ds_read_b128 v[198:201], v164 offset:5120
	ds_read_b128 v[204:207], v164 offset:6144
	ds_read_b128 v[208:211], v164 offset:7168
	global_load_lds_dwordx4 v[212:213], off
	v_lshl_add_u64 v[212:213], s[86:87], 0, v[148:149]
	s_mov_b32 m0, s11
	s_nop 0
	global_load_lds_dwordx4 v[212:213], off
	s_waitcnt vmcnt(8)
	s_waitcnt lgkmcnt(0)
	s_barrier
	s_waitcnt lgkmcnt(0)
	v_mfma_f32_16x16x32_bf16 v[132:135], v[80:83], v[178:181], v[132:135]
	v_mfma_f32_16x16x32_bf16 v[128:131], v[136:139], v[178:181], v[128:131]
	v_mfma_f32_16x16x32_bf16 v[124:127], v[80:83], v[186:189], v[124:127]
	v_mfma_f32_16x16x32_bf16 v[120:123], v[136:139], v[186:189], v[120:123]
	v_mfma_f32_16x16x32_bf16 v[116:119], v[80:83], v[194:197], v[116:119]
	v_mfma_f32_16x16x32_bf16 v[112:115], v[136:139], v[194:197], v[112:115]
	v_mfma_f32_16x16x32_bf16 v[108:111], v[80:83], v[204:207], v[108:111]
	v_mfma_f32_16x16x32_bf16 v[104:107], v[136:139], v[204:207], v[104:107]
	v_mfma_f32_16x16x32_bf16 v[132:135], v[84:87], v[182:185], v[132:135]
	v_mfma_f32_16x16x32_bf16 v[128:131], v[140:143], v[182:185], v[128:131]
	v_mfma_f32_16x16x32_bf16 v[124:127], v[84:87], v[190:193], v[124:127]
	v_mfma_f32_16x16x32_bf16 v[120:123], v[140:143], v[190:193], v[120:123]
	v_mfma_f32_16x16x32_bf16 v[116:119], v[84:87], v[198:201], v[116:119]
	v_mfma_f32_16x16x32_bf16 v[112:115], v[140:143], v[198:201], v[112:115]
	v_mfma_f32_16x16x32_bf16 v[108:111], v[84:87], v[208:211], v[108:111]
	v_mfma_f32_16x16x32_bf16 v[104:107], v[140:143], v[208:211], v[104:107]
	v_mfma_f32_16x16x32_bf16 v[60:63], v[154:157], v[178:181], v[60:63]
	v_mfma_f32_16x16x32_bf16 v[56:59], v[170:173], v[178:181], v[56:59]
	v_mfma_f32_16x16x32_bf16 v[52:55], v[154:157], v[186:189], v[52:55]
	v_mfma_f32_16x16x32_bf16 v[48:51], v[170:173], v[186:189], v[48:51]
	v_mfma_f32_16x16x32_bf16 v[44:47], v[154:157], v[194:197], v[44:47]
	v_mfma_f32_16x16x32_bf16 v[40:43], v[170:173], v[194:197], v[40:43]
	v_mfma_f32_16x16x32_bf16 v[36:39], v[154:157], v[204:207], v[36:39]
	v_mfma_f32_16x16x32_bf16 v[32:35], v[170:173], v[204:207], v[32:35]
	v_mfma_f32_16x16x32_bf16 v[60:63], v[166:169], v[182:185], v[60:63]
	v_mfma_f32_16x16x32_bf16 v[56:59], v[174:177], v[182:185], v[56:59]
	v_mfma_f32_16x16x32_bf16 v[52:55], v[166:169], v[190:193], v[52:55]
	v_mfma_f32_16x16x32_bf16 v[48:51], v[174:177], v[190:193], v[48:51]
	v_mfma_f32_16x16x32_bf16 v[44:47], v[166:169], v[198:201], v[44:47]
	v_mfma_f32_16x16x32_bf16 v[40:43], v[174:177], v[198:201], v[40:43]
	v_mfma_f32_16x16x32_bf16 v[36:39], v[166:169], v[208:211], v[36:39]
	v_mfma_f32_16x16x32_bf16 v[32:35], v[174:177], v[208:211], v[32:35]
	s_barrier
	s_mov_b32 m0, s67
	v_lshl_add_u64 v[212:213], s[78:79], 0, v[146:147]
	ds_read_b128 v[178:181], v164 offset:16384
	ds_read_b128 v[182:185], v164 offset:17408
	ds_read_b128 v[186:189], v164 offset:18432
	ds_read_b128 v[190:193], v164 offset:19456
	ds_read_b128 v[194:197], v164 offset:20480
	ds_read_b128 v[198:201], v164 offset:21504
	ds_read_b128 v[204:207], v164 offset:22528
	ds_read_b128 v[208:211], v164 offset:23552
	global_load_lds_dwordx4 v[212:213], off
	v_lshl_add_u64 v[214:215], s[78:79], 0, v[150:151]
	s_mov_b32 m0, s64
	v_lshl_add_u64 v[216:217], s[82:83], 0, v[146:147]
	global_load_lds_dwordx4 v[214:215], off
	s_mov_b32 m0, s66
	v_lshl_add_u64 v[218:219], s[76:77], 0, v[148:149]
	global_load_lds_dwordx4 v[216:217], off
	v_lshl_add_u64 v[216:217], s[82:83], 0, v[150:151]
	s_mov_b32 m0, s65
	s_nop 0
	global_load_lds_dwordx4 v[216:217], off
	v_lshl_add_u64 v[216:217], s[76:77], 0, v[144:145]
	s_mov_b32 m0, s10
	s_nop 0
	global_load_lds_dwordx4 v[216:217], off
	s_mov_b32 m0, s89
	s_nop 0
	global_load_lds_dwordx4 v[218:219], off
	s_waitcnt vmcnt(8)
	s_waitcnt lgkmcnt(0)
	s_barrier
; #define PG8_STAGE(bufoff, gbase, voff) do { _Pragma("unroll") for (int _i = 0; _i < 2; ++_i) \
;         __builtin_amdgcn_global_load_lds((const unsigned*)((const char*)(gbase) + (voff)[_i]), (LAS unsigned*)(lds + (bufoff) + ldsw + _i * 8192), 16, 0, 0); } while (0)
; #define PG8_LDA(dst, b, h) do { _Pragma("unroll") for (int m = 0; m < 4; ++m) _Pragma("unroll") for (int k = 0; k < 2; ++k) dst[m][k] = *(const LAS bf16x8*)(lds + PG8_SA(b, h) + aoff + m * 2048 + k * 1024); } while (0)
; #define PG8_LDB(dst, b, h) do { _Pragma("unroll") for (int n = 0; n < 2; ++n) _Pragma("unroll") for (int k = 0; k < 2; ++k) dst[n][k] = *(const LAS bf16x8*)(lds + PG8_SB(b, h) + boff + n * 2048 + k * 1024); } while (0)
; #define PG8_MMA(ai, bj, At, Bt) do { __builtin_amdgcn_s_setprio(1); _Pragma("unroll") for (int m = 0; m < 4; ++m) _Pragma("unroll") for (int n = 0; n < 2; ++n) _Pragma("unroll") for (int k = 0; k < 2; ++k) \
;         acc[ai][bj][m][n] = __builtin_amdgcn_mfma_f32_16x16x32_bf16(Bt[n][k], At[m][k], acc[ai][bj][m][n], 0, 0, 0); __builtin_amdgcn_s_setprio(0); } while (0)
; #define PG8_WAIT_V(n) asm volatile("s_waitcnt vmcnt(" #n ")" ::: "memory")
; #define PG8_WAIT_L(n) asm volatile("s_waitcnt lgkmcnt(" #n ")" ::: "memory")
; #define PG8_BAR __builtin_amdgcn_s_barrier()
; #define PG8_SCHED __builtin_amdgcn_sched_barrier(0)
; template <class Epi>
; __device__ __forceinline__ void gemm_phase(LAS unsigned char* lds, const Gemm g, const Sched& S, const Epi& E) {
;     ...
;             PG8_WAIT_V(8); PG8_WAIT_L(0); PG8_BAR; PG8_MMA(1, 0, At, B0); PG8_MMA(1, 1, At, B1); PG8_BAR; PG8_SCHED;
;             PG8_LDB(B0, 1, 0); PG8_LDB(B1, 1, 1); PG8_SCHED; PG8_LDA(At, 1, 0); PG8_STAGE(PG8_SA(0, 1), a2 + hstepA, voffA);
;             PG8_WAIT_V(8); PG8_WAIT_L(0); PG8_BAR; PG8_MMA(0, 0, At, B0); PG8_MMA(0, 1, At, B1); PG8_BAR; PG8_SCHED;
	s_waitcnt lgkmcnt(0)
	v_mfma_f32_16x16x32_bf16 v[100:103], v[80:83], v[178:181], v[100:103]
	v_mfma_f32_16x16x32_bf16 v[96:99], v[136:139], v[178:181], v[96:99]
	v_mfma_f32_16x16x32_bf16 v[92:95], v[80:83], v[186:189], v[92:95]
	v_mfma_f32_16x16x32_bf16 v[88:91], v[136:139], v[186:189], v[88:91]
	v_mfma_f32_16x16x32_bf16 v[76:79], v[80:83], v[194:197], v[76:79]
	v_mfma_f32_16x16x32_bf16 v[72:75], v[136:139], v[194:197], v[72:75]
	v_mfma_f32_16x16x32_bf16 v[68:71], v[80:83], v[204:207], v[68:71]
	v_mfma_f32_16x16x32_bf16 v[64:67], v[136:139], v[204:207], v[64:67]
	v_mfma_f32_16x16x32_bf16 v[100:103], v[84:87], v[182:185], v[100:103]
	v_mfma_f32_16x16x32_bf16 v[96:99], v[140:143], v[182:185], v[96:99]
	v_mfma_f32_16x16x32_bf16 v[92:95], v[84:87], v[190:193], v[92:95]
	v_mfma_f32_16x16x32_bf16 v[88:91], v[140:143], v[190:193], v[88:91]
	v_mfma_f32_16x16x32_bf16 v[76:79], v[84:87], v[198:201], v[76:79]
	v_mfma_f32_16x16x32_bf16 v[72:75], v[140:143], v[198:201], v[72:75]
	v_mfma_f32_16x16x32_bf16 v[68:71], v[84:87], v[208:211], v[68:71]
	v_mfma_f32_16x16x32_bf16 v[64:67], v[140:143], v[208:211], v[64:67]
	v_mfma_f32_16x16x32_bf16 v[28:31], v[154:157], v[178:181], v[28:31]
	v_mfma_f32_16x16x32_bf16 v[24:27], v[170:173], v[178:181], v[24:27]
	v_mfma_f32_16x16x32_bf16 v[20:23], v[154:157], v[186:189], v[20:23]
	v_mfma_f32_16x16x32_bf16 v[16:19], v[170:173], v[186:189], v[16:19]
	v_mfma_f32_16x16x32_bf16 v[12:15], v[154:157], v[194:197], v[12:15]
	v_mfma_f32_16x16x32_bf16 v[8:11], v[170:173], v[194:197], v[8:11]
	v_mfma_f32_16x16x32_bf16 v[4:7], v[154:157], v[204:207], v[4:7]
	v_mfma_f32_16x16x32_bf16 v[0:3], v[170:173], v[204:207], v[0:3]
	v_mfma_f32_16x16x32_bf16 v[28:31], v[166:169], v[182:185], v[28:31]
	v_mfma_f32_16x16x32_bf16 v[24:27], v[174:177], v[182:185], v[24:27]
	v_mfma_f32_16x16x32_bf16 v[20:23], v[166:169], v[190:193], v[20:23]
	v_mfma_f32_16x16x32_bf16 v[16:19], v[174:177], v[190:193], v[16:19]
	v_mfma_f32_16x16x32_bf16 v[12:15], v[166:169], v[198:201], v[12:15]
	v_mfma_f32_16x16x32_bf16 v[8:11], v[174:177], v[198:201], v[8:11]
	v_mfma_f32_16x16x32_bf16 v[4:7], v[166:169], v[208:211], v[4:7]
	v_mfma_f32_16x16x32_bf16 v[0:3], v[174:177], v[208:211], v[0:3]
	s_barrier
	v_add_u32_e32 v140, s63, v160
	v_add_u32_e32 v152, s62, v160
	ds_read_b128 v[80:83], v140
	ds_read_b128 v[84:87], v140 offset:1024
	ds_read_b128 v[136:139], v140 offset:2048
	ds_read_b128 v[140:143], v140 offset:3072
	ds_read_b128 v[154:157], v152
	ds_read_b128 v[166:169], v152 offset:1024
	ds_read_b128 v[170:173], v152 offset:2048
	ds_read_b128 v[174:177], v152 offset:3072
	s_mov_b32 m0, s90
	v_lshl_add_u64 v[220:221], s[74:75], 0, v[144:145]
	ds_read_b128 v[178:181], v164 offset:32768
	ds_read_b128 v[182:185], v164 offset:33792
	ds_read_b128 v[186:189], v164 offset:34816
	ds_read_b128 v[190:193], v164 offset:35840
	ds_read_b128 v[194:197], v164 offset:36864
	ds_read_b128 v[198:201], v164 offset:37888
	ds_read_b128 v[204:207], v164 offset:38912
	ds_read_b128 v[208:211], v164 offset:39936
	global_load_lds_dwordx4 v[220:221], off
	v_lshl_add_u64 v[220:221], s[74:75], 0, v[148:149]
	s_mov_b32 m0, s91
	s_nop 0
	global_load_lds_dwordx4 v[220:221], off
	s_waitcnt vmcnt(8)
	s_waitcnt lgkmcnt(0)
	s_barrier
	s_waitcnt lgkmcnt(0)
	v_mfma_f32_16x16x32_bf16 v[132:135], v[80:83], v[178:181], v[132:135]
	v_mfma_f32_16x16x32_bf16 v[128:131], v[136:139], v[178:181], v[128:131]
	v_mfma_f32_16x16x32_bf16 v[124:127], v[80:83], v[186:189], v[124:127]
	v_mfma_f32_16x16x32_bf16 v[120:123], v[136:139], v[186:189], v[120:123]
	v_mfma_f32_16x16x32_bf16 v[116:119], v[80:83], v[194:197], v[116:119]
	v_mfma_f32_16x16x32_bf16 v[112:115], v[136:139], v[194:197], v[112:115]
	v_mfma_f32_16x16x32_bf16 v[108:111], v[80:83], v[204:207], v[108:111]
	v_mfma_f32_16x16x32_bf16 v[104:107], v[136:139], v[204:207], v[104:107]
	v_mfma_f32_16x16x32_bf16 v[132:135], v[84:87], v[182:185], v[132:135]
	v_mfma_f32_16x16x32_bf16 v[128:131], v[140:143], v[182:185], v[128:131]
	v_mfma_f32_16x16x32_bf16 v[124:127], v[84:87], v[190:193], v[124:127]
	v_mfma_f32_16x16x32_bf16 v[120:123], v[140:143], v[190:193], v[120:123]
	v_mfma_f32_16x16x32_bf16 v[116:119], v[84:87], v[198:201], v[116:119]
	v_mfma_f32_16x16x32_bf16 v[112:115], v[140:143], v[198:201], v[112:115]
	v_mfma_f32_16x16x32_bf16 v[108:111], v[84:87], v[208:211], v[108:111]
	v_mfma_f32_16x16x32_bf16 v[104:107], v[140:143], v[208:211], v[104:107]
	v_mfma_f32_16x16x32_bf16 v[60:63], v[154:157], v[178:181], v[60:63]
	v_mfma_f32_16x16x32_bf16 v[56:59], v[170:173], v[178:181], v[56:59]
	v_mfma_f32_16x16x32_bf16 v[52:55], v[154:157], v[186:189], v[52:55]
	v_mfma_f32_16x16x32_bf16 v[48:51], v[170:173], v[186:189], v[48:51]
	v_mfma_f32_16x16x32_bf16 v[44:47], v[154:157], v[194:197], v[44:47]
	v_mfma_f32_16x16x32_bf16 v[40:43], v[170:173], v[194:197], v[40:43]
	v_mfma_f32_16x16x32_bf16 v[36:39], v[154:157], v[204:207], v[36:39]
	v_mfma_f32_16x16x32_bf16 v[32:35], v[170:173], v[204:207], v[32:35]
	v_mfma_f32_16x16x32_bf16 v[60:63], v[166:169], v[182:185], v[60:63]
	v_mfma_f32_16x16x32_bf16 v[56:59], v[174:177], v[182:185], v[56:59]
	v_mfma_f32_16x16x32_bf16 v[52:55], v[166:169], v[190:193], v[52:55]
	v_mfma_f32_16x16x32_bf16 v[48:51], v[174:177], v[190:193], v[48:51]
	v_mfma_f32_16x16x32_bf16 v[44:47], v[166:169], v[198:201], v[44:47]
	v_mfma_f32_16x16x32_bf16 v[40:43], v[174:177], v[198:201], v[40:43]
	v_mfma_f32_16x16x32_bf16 v[36:39], v[166:169], v[208:211], v[36:39]
	v_mfma_f32_16x16x32_bf16 v[32:35], v[174:177], v[208:211], v[32:35]
	s_barrier
; #define PG8_STAGE(bufoff, gbase, voff) do { _Pragma("unroll") for (int _i = 0; _i < 2; ++_i) \
;         __builtin_amdgcn_global_load_lds((const unsigned*)((const char*)(gbase) + (voff)[_i]), (LAS unsigned*)(lds + (bufoff) + ldsw + _i * 8192), 16, 0, 0); } while (0)
; #define PG8_LDA(dst, b, h) do { _Pragma("unroll") for (int m = 0; m < 4; ++m) _Pragma("unroll") for (int k = 0; k < 2; ++k) dst[m][k] = *(const LAS bf16x8*)(lds + PG8_SA(b, h) + aoff + m * 2048 + k * 1024); } while (0)
; #define PG8_MMA(ai, bj, At, Bt) do { __builtin_amdgcn_s_setprio(1); _Pragma("unroll") for (int m = 0; m < 4; ++m) _Pragma("unroll") for (int n = 0; n < 2; ++n) _Pragma("unroll") for (int k = 0; k < 2; ++k) \
;         acc[ai][bj][m][n] = __builtin_amdgcn_mfma_f32_16x16x32_bf16(Bt[n][k], At[m][k], acc[ai][bj][m][n], 0, 0, 0); __builtin_amdgcn_s_setprio(0); } while (0)
; #define PG8_WAIT_V(n) asm volatile("s_waitcnt vmcnt(" #n ")" ::: "memory")
; #define PG8_WAIT_L(n) asm volatile("s_waitcnt lgkmcnt(" #n ")" ::: "memory")
; #define PG8_BAR __builtin_amdgcn_s_barrier()
; #define PG8_SCHED __builtin_amdgcn_sched_barrier(0)
; template <class Epi>
; __device__ __forceinline__ void gemm_phase(LAS unsigned char* lds, const Gemm g, const Sched& S, const Epi& E) {
;     ...
;             PG8_LDA(At, 1, 1); PG8_STAGE(PG8_SB(1, 0), b3, voffB); PG8_STAGE(PG8_SB(1, 1), b3 + hstepB, voffB); PG8_STAGE(PG8_SA(1, 0), a3, voffA);
;             PG8_WAIT_V(8); PG8_WAIT_L(0); PG8_BAR; PG8_MMA(1, 0, At, B0); PG8_MMA(1, 1, At, B1); PG8_BAR; PG8_SCHED;
;         }
;         if (wr == 0) PG8_BAR;
	s_mov_b32 m0, s61
	v_lshl_add_u64 v[212:213], v[212:213], 0, s[6:7]
	ds_read_b128 v[178:181], v164 offset:49152
	ds_read_b128 v[182:185], v164 offset:50176
	ds_read_b128 v[186:189], v164 offset:51200
	ds_read_b128 v[190:193], v164 offset:52224
	ds_read_b128 v[194:197], v164 offset:53248
	ds_read_b128 v[198:201], v164 offset:54272
	ds_read_b128 v[204:207], v164 offset:55296
	ds_read_b128 v[208:211], v164 offset:56320
	global_load_lds_dwordx4 v[212:213], off
	v_lshl_add_u64 v[212:213], v[214:215], 0, s[6:7]
	s_mov_b32 m0, s59
	s_nop 0
	global_load_lds_dwordx4 v[212:213], off
	v_lshl_add_u64 v[212:213], s[56:57], 0, v[146:147]
	s_mov_b32 m0, s60
	s_nop 0
	global_load_lds_dwordx4 v[212:213], off
	v_lshl_add_u64 v[212:213], s[56:57], 0, v[150:151]
	s_mov_b32 m0, s58
	s_nop 0
	global_load_lds_dwordx4 v[212:213], off
	v_lshl_add_u64 v[212:213], v[216:217], 0, s[6:7]
	s_mov_b32 m0, s94
	s_nop 0
	global_load_lds_dwordx4 v[212:213], off
	v_lshl_add_u64 v[212:213], v[218:219], 0, s[6:7]
	s_mov_b32 m0, s95
	s_nop 0
	global_load_lds_dwordx4 v[212:213], off
	s_waitcnt vmcnt(8)
	s_waitcnt lgkmcnt(0)
	s_barrier
	s_waitcnt lgkmcnt(0)
	v_mfma_f32_16x16x32_bf16 v[100:103], v[80:83], v[178:181], v[100:103]
	v_mfma_f32_16x16x32_bf16 v[96:99], v[136:139], v[178:181], v[96:99]
	v_mfma_f32_16x16x32_bf16 v[92:95], v[80:83], v[186:189], v[92:95]
	v_mfma_f32_16x16x32_bf16 v[88:91], v[136:139], v[186:189], v[88:91]
	v_mfma_f32_16x16x32_bf16 v[76:79], v[80:83], v[194:197], v[76:79]
	v_mfma_f32_16x16x32_bf16 v[72:75], v[136:139], v[194:197], v[72:75]
	v_mfma_f32_16x16x32_bf16 v[68:71], v[80:83], v[204:207], v[68:71]
	v_mfma_f32_16x16x32_bf16 v[64:67], v[136:139], v[204:207], v[64:67]
	v_mfma_f32_16x16x32_bf16 v[100:103], v[84:87], v[182:185], v[100:103]
	v_mfma_f32_16x16x32_bf16 v[96:99], v[140:143], v[182:185], v[96:99]
	v_mfma_f32_16x16x32_bf16 v[92:95], v[84:87], v[190:193], v[92:95]
	v_mfma_f32_16x16x32_bf16 v[88:91], v[140:143], v[190:193], v[88:91]
	v_mfma_f32_16x16x32_bf16 v[76:79], v[84:87], v[198:201], v[76:79]
	v_mfma_f32_16x16x32_bf16 v[72:75], v[140:143], v[198:201], v[72:75]
	v_mfma_f32_16x16x32_bf16 v[68:71], v[84:87], v[208:211], v[68:71]
	v_mfma_f32_16x16x32_bf16 v[64:67], v[140:143], v[208:211], v[64:67]
	v_mfma_f32_16x16x32_bf16 v[28:31], v[154:157], v[178:181], v[28:31]
	v_mfma_f32_16x16x32_bf16 v[24:27], v[170:173], v[178:181], v[24:27]
	v_mfma_f32_16x16x32_bf16 v[20:23], v[154:157], v[186:189], v[20:23]
	v_mfma_f32_16x16x32_bf16 v[16:19], v[170:173], v[186:189], v[16:19]
	v_mfma_f32_16x16x32_bf16 v[12:15], v[154:157], v[194:197], v[12:15]
	v_mfma_f32_16x16x32_bf16 v[8:11], v[170:173], v[194:197], v[8:11]
	v_mfma_f32_16x16x32_bf16 v[4:7], v[154:157], v[204:207], v[4:7]
	v_mfma_f32_16x16x32_bf16 v[0:3], v[170:173], v[204:207], v[0:3]
	v_mfma_f32_16x16x32_bf16 v[28:31], v[166:169], v[182:185], v[28:31]
	v_mfma_f32_16x16x32_bf16 v[24:27], v[174:177], v[182:185], v[24:27]
	v_mfma_f32_16x16x32_bf16 v[20:23], v[166:169], v[190:193], v[20:23]
	v_mfma_f32_16x16x32_bf16 v[16:19], v[174:177], v[190:193], v[16:19]
	v_mfma_f32_16x16x32_bf16 v[12:15], v[166:169], v[198:201], v[12:15]
	v_mfma_f32_16x16x32_bf16 v[8:11], v[174:177], v[198:201], v[8:11]
	v_mfma_f32_16x16x32_bf16 v[4:7], v[166:169], v[208:211], v[4:7]
	v_mfma_f32_16x16x32_bf16 v[0:3], v[174:177], v[208:211], v[0:3]
	s_barrier
	s_andn2_b64 vcc, exec, s[54:55]
	s_mov_b64 s[56:57], -1
	s_mov_b64 s[54:55], 0
	s_mov_b64 s[74:75], 0x100
	s_cbranch_vccz .LBB0_773
	s_and_b64 vcc, exec, s[8:9]
	s_cbranch_vccz .LBB0_776
	s_barrier

; #define PG8_STAGE(bufoff, gbase, voff) do { _Pragma("unroll") for (int _i = 0; _i < 2; ++_i) \
;         __builtin_amdgcn_global_load_lds((const unsigned*)((const char*)(gbase) + (voff)[_i]), (LAS unsigned*)(lds + (bufoff) + ldsw + _i * 8192), 16, 0, 0); } while (0)
; #define PG8_LDA(dst, b, h) do { _Pragma("unroll") for (int m = 0; m < 4; ++m) _Pragma("unroll") for (int k = 0; k < 2; ++k) dst[m][k] = *(const LAS bf16x8*)(lds + PG8_SA(b, h) + aoff + m * 2048 + k * 1024); } while (0)
; #define PG8_LDB(dst, b, h) do { _Pragma("unroll") for (int n = 0; n < 2; ++n) _Pragma("unroll") for (int k = 0; k < 2; ++k) dst[n][k] = *(const LAS bf16x8*)(lds + PG8_SB(b, h) + boff + n * 2048 + k * 1024); } while (0)
; #define PG8_MMA(ai, bj, At, Bt) do { __builtin_amdgcn_s_setprio(1); _Pragma("unroll") for (int m = 0; m < 4; ++m) _Pragma("unroll") for (int n = 0; n < 2; ++n) _Pragma("unroll") for (int k = 0; k < 2; ++k) \
;         acc[ai][bj][m][n] = __builtin_amdgcn_mfma_f32_16x16x32_bf16(Bt[n][k], At[m][k], acc[ai][bj][m][n], 0, 0, 0); __builtin_amdgcn_s_setprio(0); } while (0)
; #define PG8_WAIT_V(n) asm volatile("s_waitcnt vmcnt(" #n ")" ::: "memory")
; #define PG8_WAIT_L(n) asm volatile("s_waitcnt lgkmcnt(" #n ")" ::: "memory")
; #define PG8_BAR __builtin_amdgcn_s_barrier()
; #define PG8_SCHED __builtin_amdgcn_sched_barrier(0)
; template <class Epi>
; __device__ __forceinline__ void gemm_phase(LAS unsigned char* lds, const Gemm g, const Sched& S, const Epi& E) {
;     ...
;         for (int t = 0; t < nt; t += 2) {
;             const bool last = (t == nt - 2);
;             const char* a1 = cA + (size_t)(t + 1) * kstep;
;             const char* a2 = last ? nA : cA + (size_t)(t + 2) * kstep; const char* b2 = last ? nB : cB + (size_t)(t + 2) * kstep;
;             const char* a3 = a2 + kstep; const char* b3 = b2 + kstep;
;             PG8_LDB(B0, 0, 0); PG8_LDB(B1, 0, 1); PG8_SCHED; PG8_LDA(At, 0, 0); PG8_STAGE(PG8_SA(1, 1), a1 + hstepA, voffA);
;             PG8_WAIT_V(8); PG8_WAIT_L(0); PG8_BAR; PG8_MMA(0, 0, At, B0); PG8_MMA(0, 1, At, B1); PG8_BAR; PG8_SCHED;
;             PG8_LDA(At, 0, 1); PG8_STAGE(PG8_SB(0, 0), b2, voffB); PG8_STAGE(PG8_SB(0, 1), b2 + hstepB, voffB); PG8_STAGE(PG8_SA(0, 0), a2, voffA);
.LBB0_900:
	s_add_u32 s57, s4, s78
	s_addc_u32 s64, s5, s79
	s_add_u32 s65, s57, 0x100
	s_addc_u32 s66, s64, 0
	s_and_b64 s[62:63], s[14:15], exec
	s_cselect_b32 s83, s75, s66
	s_cselect_b32 s82, s74, s65
	s_add_u32 s62, s6, s78
	s_addc_u32 s63, s7, s79
	s_add_u32 s62, s62, 0x100
	s_addc_u32 s63, s63, 0
	s_and_b64 s[14:15], s[14:15], exec
	s_cselect_b32 s87, s1, s63
	s_cselect_b32 s86, s55, s62
	s_add_u32 s90, s57, 0x40080
	ds_read_b128 v[96:99], v155
	ds_read_b128 v[100:103], v155 offset:1024
	ds_read_b128 v[144:147], v155 offset:2048
	ds_read_b128 v[148:151], v155 offset:3072
	ds_read_b128 v[160:163], v156
	ds_read_b128 v[164:167], v156 offset:1024
	ds_read_b128 v[168:171], v156 offset:2048
	ds_read_b128 v[172:175], v156 offset:3072
	s_addc_u32 s91, s64, 0
	s_add_i32 s67, s59, s10
	s_add_i32 m0, s11, 0xc000
	s_add_i32 s85, s11, 0xe000
	s_add_i32 s84, s67, 0x2000
	s_add_u32 s88, s86, 0x10000
	s_addc_u32 s89, s87, 0
	s_add_i32 vcc_hi, s60, s10
	s_add_i32 vcc_lo, vcc_hi, 0x2000
	s_add_i32 s66, 0, 0x18000
	s_add_i32 s65, 0, 0x1c000
	s_add_u32 s78, s82, 0x40000
	s_addc_u32 s79, s83, 0
	s_add_i32 s64, s66, s10
	s_add_i32 s62, s64, 0x2000
	s_add_u32 s14, s86, 0x10080
	s_addc_u32 s15, s87, 0
	s_add_i32 s63, s65, s10
	s_add_i32 s57, s63, 0x2000
	v_lshl_add_u64 v[200:201], s[90:91], 0, v[136:137]
	ds_read_b128 v[176:179], v157
	ds_read_b128 v[180:183], v157 offset:1024
	ds_read_b128 v[184:187], v157 offset:2048
	ds_read_b128 v[188:191], v157 offset:3072
	ds_read_b128 v[192:195], v157 offset:4096
	ds_read_b128 v[196:199], v157 offset:5120
	ds_read_b128 v[204:207], v157 offset:6144
	ds_read_b128 v[208:211], v157 offset:7168
	global_load_lds_dwordx4 v[200:201], off
	v_lshl_add_u64 v[200:201], s[90:91], 0, v[140:141]
	s_mov_b32 m0, s85
	s_nop 0
	global_load_lds_dwordx4 v[200:201], off
	s_waitcnt vmcnt(8)
	s_waitcnt lgkmcnt(0)
	s_barrier
	s_waitcnt lgkmcnt(0)
	v_mfma_f32_16x16x32_bf16 v[132:135], v[96:99], v[176:179], v[132:135]
	v_mfma_f32_16x16x32_bf16 v[128:131], v[144:147], v[176:179], v[128:131]
	v_mfma_f32_16x16x32_bf16 v[124:127], v[96:99], v[184:187], v[124:127]
	v_mfma_f32_16x16x32_bf16 v[120:123], v[144:147], v[184:187], v[120:123]
	v_mfma_f32_16x16x32_bf16 v[116:119], v[96:99], v[192:195], v[116:119]
	v_mfma_f32_16x16x32_bf16 v[112:115], v[144:147], v[192:195], v[112:115]
	v_mfma_f32_16x16x32_bf16 v[108:111], v[96:99], v[204:207], v[108:111]
	v_mfma_f32_16x16x32_bf16 v[104:107], v[144:147], v[204:207], v[104:107]
	v_mfma_f32_16x16x32_bf16 v[132:135], v[100:103], v[180:183], v[132:135]
	v_mfma_f32_16x16x32_bf16 v[128:131], v[148:151], v[180:183], v[128:131]
	v_mfma_f32_16x16x32_bf16 v[124:127], v[100:103], v[188:191], v[124:127]
	v_mfma_f32_16x16x32_bf16 v[120:123], v[148:151], v[188:191], v[120:123]
	v_mfma_f32_16x16x32_bf16 v[116:119], v[100:103], v[196:199], v[116:119]
	v_mfma_f32_16x16x32_bf16 v[112:115], v[148:151], v[196:199], v[112:115]
	v_mfma_f32_16x16x32_bf16 v[108:111], v[100:103], v[208:211], v[108:111]
	v_mfma_f32_16x16x32_bf16 v[104:107], v[148:151], v[208:211], v[104:107]
	v_mfma_f32_16x16x32_bf16 v[60:63], v[160:163], v[176:179], v[60:63]
	v_mfma_f32_16x16x32_bf16 v[56:59], v[168:171], v[176:179], v[56:59]
	v_mfma_f32_16x16x32_bf16 v[52:55], v[160:163], v[184:187], v[52:55]
	v_mfma_f32_16x16x32_bf16 v[48:51], v[168:171], v[184:187], v[48:51]
	v_mfma_f32_16x16x32_bf16 v[44:47], v[160:163], v[192:195], v[44:47]
	v_mfma_f32_16x16x32_bf16 v[40:43], v[168:171], v[192:195], v[40:43]
	v_mfma_f32_16x16x32_bf16 v[36:39], v[160:163], v[204:207], v[36:39]
	v_mfma_f32_16x16x32_bf16 v[32:35], v[168:171], v[204:207], v[32:35]
	v_mfma_f32_16x16x32_bf16 v[60:63], v[164:167], v[180:183], v[60:63]
	v_mfma_f32_16x16x32_bf16 v[56:59], v[172:175], v[180:183], v[56:59]
	v_mfma_f32_16x16x32_bf16 v[52:55], v[164:167], v[188:191], v[52:55]
	v_mfma_f32_16x16x32_bf16 v[48:51], v[172:175], v[188:191], v[48:51]
	v_mfma_f32_16x16x32_bf16 v[44:47], v[164:167], v[196:199], v[44:47]
	v_mfma_f32_16x16x32_bf16 v[40:43], v[172:175], v[196:199], v[40:43]
	v_mfma_f32_16x16x32_bf16 v[36:39], v[164:167], v[208:211], v[36:39]
	v_mfma_f32_16x16x32_bf16 v[32:35], v[172:175], v[208:211], v[32:35]
	s_barrier
	s_mov_b32 m0, s67
	v_lshl_add_u64 v[200:201], s[86:87], 0, v[138:139]
	ds_read_b128 v[176:179], v157 offset:16384
	ds_read_b128 v[180:183], v157 offset:17408
	ds_read_b128 v[184:187], v157 offset:18432
	ds_read_b128 v[188:191], v157 offset:19456
	ds_read_b128 v[192:195], v157 offset:20480
	ds_read_b128 v[196:199], v157 offset:21504
	ds_read_b128 v[204:207], v157 offset:22528
	ds_read_b128 v[208:211], v157 offset:23552
	global_load_lds_dwordx4 v[200:201], off
	v_lshl_add_u64 v[212:213], s[86:87], 0, v[142:143]
	s_mov_b32 m0, s84
	v_lshl_add_u64 v[214:215], s[88:89], 0, v[138:139]
	global_load_lds_dwordx4 v[212:213], off
	s_mov_b32 m0, vcc_hi
	v_lshl_add_u64 v[216:217], s[82:83], 0, v[140:141]
	global_load_lds_dwordx4 v[214:215], off
	v_lshl_add_u64 v[214:215], s[88:89], 0, v[142:143]
	s_mov_b32 m0, vcc_lo
	s_nop 0
	global_load_lds_dwordx4 v[214:215], off
	v_lshl_add_u64 v[214:215], s[82:83], 0, v[136:137]
	s_mov_b32 m0, s11
	s_nop 0
	global_load_lds_dwordx4 v[214:215], off
	s_mov_b32 m0, s93
	s_nop 0
	global_load_lds_dwordx4 v[216:217], off
	s_waitcnt vmcnt(8)
	s_waitcnt lgkmcnt(0)
	s_barrier
; #define PG8_STAGE(bufoff, gbase, voff) do { _Pragma("unroll") for (int _i = 0; _i < 2; ++_i) \
;         __builtin_amdgcn_global_load_lds((const unsigned*)((const char*)(gbase) + (voff)[_i]), (LAS unsigned*)(lds + (bufoff) + ldsw + _i * 8192), 16, 0, 0); } while (0)
; #define PG8_LDA(dst, b, h) do { _Pragma("unroll") for (int m = 0; m < 4; ++m) _Pragma("unroll") for (int k = 0; k < 2; ++k) dst[m][k] = *(const LAS bf16x8*)(lds + PG8_SA(b, h) + aoff + m * 2048 + k * 1024); } while (0)
; #define PG8_LDB(dst, b, h) do { _Pragma("unroll") for (int n = 0; n < 2; ++n) _Pragma("unroll") for (int k = 0; k < 2; ++k) dst[n][k] = *(const LAS bf16x8*)(lds + PG8_SB(b, h) + boff + n * 2048 + k * 1024); } while (0)
; #define PG8_MMA(ai, bj, At, Bt) do { __builtin_amdgcn_s_setprio(1); _Pragma("unroll") for (int m = 0; m < 4; ++m) _Pragma("unroll") for (int n = 0; n < 2; ++n) _Pragma("unroll") for (int k = 0; k < 2; ++k) \
;         acc[ai][bj][m][n] = __builtin_amdgcn_mfma_f32_16x16x32_bf16(Bt[n][k], At[m][k], acc[ai][bj][m][n], 0, 0, 0); __builtin_amdgcn_s_setprio(0); } while (0)
; #define PG8_WAIT_V(n) asm volatile("s_waitcnt vmcnt(" #n ")" ::: "memory")
; #define PG8_WAIT_L(n) asm volatile("s_waitcnt lgkmcnt(" #n ")" ::: "memory")
; #define PG8_BAR __builtin_amdgcn_s_barrier()
; #define PG8_SCHED __builtin_amdgcn_sched_barrier(0)
; template <class Epi>
; __device__ __forceinline__ void gemm_phase(LAS unsigned char* lds, const Gemm g, const Sched& S, const Epi& E) {
;     ...
;             PG8_WAIT_V(8); PG8_WAIT_L(0); PG8_BAR; PG8_MMA(1, 0, At, B0); PG8_MMA(1, 1, At, B1); PG8_BAR; PG8_SCHED;
;             PG8_LDB(B0, 1, 0); PG8_LDB(B1, 1, 1); PG8_SCHED; PG8_LDA(At, 1, 0); PG8_STAGE(PG8_SA(0, 1), a2 + hstepA, voffA);
;             PG8_WAIT_V(8); PG8_WAIT_L(0); PG8_BAR; PG8_MMA(0, 0, At, B0); PG8_MMA(0, 1, At, B1); PG8_BAR; PG8_SCHED;
	s_waitcnt lgkmcnt(0)
	v_mfma_f32_16x16x32_bf16 v[92:95], v[96:99], v[176:179], v[92:95]
	v_mfma_f32_16x16x32_bf16 v[88:91], v[144:147], v[176:179], v[88:91]
	v_mfma_f32_16x16x32_bf16 v[84:87], v[96:99], v[184:187], v[84:87]
	v_mfma_f32_16x16x32_bf16 v[80:83], v[144:147], v[184:187], v[80:83]
	v_mfma_f32_16x16x32_bf16 v[76:79], v[96:99], v[192:195], v[76:79]
	v_mfma_f32_16x16x32_bf16 v[72:75], v[144:147], v[192:195], v[72:75]
	v_mfma_f32_16x16x32_bf16 v[68:71], v[96:99], v[204:207], v[68:71]
	v_mfma_f32_16x16x32_bf16 v[64:67], v[144:147], v[204:207], v[64:67]
	v_mfma_f32_16x16x32_bf16 v[92:95], v[100:103], v[180:183], v[92:95]
	v_mfma_f32_16x16x32_bf16 v[88:91], v[148:151], v[180:183], v[88:91]
	v_mfma_f32_16x16x32_bf16 v[84:87], v[100:103], v[188:191], v[84:87]
	v_mfma_f32_16x16x32_bf16 v[80:83], v[148:151], v[188:191], v[80:83]
	v_mfma_f32_16x16x32_bf16 v[76:79], v[100:103], v[196:199], v[76:79]
	v_mfma_f32_16x16x32_bf16 v[72:75], v[148:151], v[196:199], v[72:75]
	v_mfma_f32_16x16x32_bf16 v[68:71], v[100:103], v[208:211], v[68:71]
	v_mfma_f32_16x16x32_bf16 v[64:67], v[148:151], v[208:211], v[64:67]
	v_mfma_f32_16x16x32_bf16 v[28:31], v[160:163], v[176:179], v[28:31]
	v_mfma_f32_16x16x32_bf16 v[24:27], v[168:171], v[176:179], v[24:27]
	v_mfma_f32_16x16x32_bf16 v[20:23], v[160:163], v[184:187], v[20:23]
	v_mfma_f32_16x16x32_bf16 v[16:19], v[168:171], v[184:187], v[16:19]
	v_mfma_f32_16x16x32_bf16 v[12:15], v[160:163], v[192:195], v[12:15]
	v_mfma_f32_16x16x32_bf16 v[8:11], v[168:171], v[192:195], v[8:11]
	v_mfma_f32_16x16x32_bf16 v[4:7], v[160:163], v[204:207], v[4:7]
	v_mfma_f32_16x16x32_bf16 v[0:3], v[168:171], v[204:207], v[0:3]
	v_mfma_f32_16x16x32_bf16 v[28:31], v[164:167], v[180:183], v[28:31]
	v_mfma_f32_16x16x32_bf16 v[24:27], v[172:175], v[180:183], v[24:27]
	v_mfma_f32_16x16x32_bf16 v[20:23], v[164:167], v[188:191], v[20:23]
	v_mfma_f32_16x16x32_bf16 v[16:19], v[172:175], v[188:191], v[16:19]
	v_mfma_f32_16x16x32_bf16 v[12:15], v[164:167], v[196:199], v[12:15]
	v_mfma_f32_16x16x32_bf16 v[8:11], v[172:175], v[196:199], v[8:11]
	v_mfma_f32_16x16x32_bf16 v[4:7], v[164:167], v[208:211], v[4:7]
	v_mfma_f32_16x16x32_bf16 v[0:3], v[172:175], v[208:211], v[0:3]
	s_barrier
	v_add_u32_e32 v148, s66, v153
	v_add_u32_e32 v159, s65, v153
	ds_read_b128 v[96:99], v148
	ds_read_b128 v[100:103], v148 offset:1024
	ds_read_b128 v[144:147], v148 offset:2048
	ds_read_b128 v[148:151], v148 offset:3072
	ds_read_b128 v[160:163], v159
	ds_read_b128 v[164:167], v159 offset:1024
	ds_read_b128 v[168:171], v159 offset:2048
	ds_read_b128 v[172:175], v159 offset:3072
	s_mov_b32 m0, s94
	v_lshl_add_u64 v[218:219], s[78:79], 0, v[136:137]
	ds_read_b128 v[176:179], v157 offset:32768
	ds_read_b128 v[180:183], v157 offset:33792
	ds_read_b128 v[184:187], v157 offset:34816
	ds_read_b128 v[188:191], v157 offset:35840
	ds_read_b128 v[192:195], v157 offset:36864
	ds_read_b128 v[196:199], v157 offset:37888
	ds_read_b128 v[204:207], v157 offset:38912
	ds_read_b128 v[208:211], v157 offset:39936
	global_load_lds_dwordx4 v[218:219], off
	v_lshl_add_u64 v[218:219], s[78:79], 0, v[140:141]
	s_mov_b32 m0, s95
	s_nop 0
	global_load_lds_dwordx4 v[218:219], off
	s_waitcnt vmcnt(8)
	s_waitcnt lgkmcnt(0)
	s_barrier
	s_waitcnt lgkmcnt(0)
	v_mfma_f32_16x16x32_bf16 v[132:135], v[96:99], v[176:179], v[132:135]
	v_mfma_f32_16x16x32_bf16 v[128:131], v[144:147], v[176:179], v[128:131]
	v_mfma_f32_16x16x32_bf16 v[124:127], v[96:99], v[184:187], v[124:127]
	v_mfma_f32_16x16x32_bf16 v[120:123], v[144:147], v[184:187], v[120:123]
	v_mfma_f32_16x16x32_bf16 v[116:119], v[96:99], v[192:195], v[116:119]
	v_mfma_f32_16x16x32_bf16 v[112:115], v[144:147], v[192:195], v[112:115]
	v_mfma_f32_16x16x32_bf16 v[108:111], v[96:99], v[204:207], v[108:111]
	v_mfma_f32_16x16x32_bf16 v[104:107], v[144:147], v[204:207], v[104:107]
	v_mfma_f32_16x16x32_bf16 v[132:135], v[100:103], v[180:183], v[132:135]
	v_mfma_f32_16x16x32_bf16 v[128:131], v[148:151], v[180:183], v[128:131]
	v_mfma_f32_16x16x32_bf16 v[124:127], v[100:103], v[188:191], v[124:127]
	v_mfma_f32_16x16x32_bf16 v[120:123], v[148:151], v[188:191], v[120:123]
	v_mfma_f32_16x16x32_bf16 v[116:119], v[100:103], v[196:199], v[116:119]
	v_mfma_f32_16x16x32_bf16 v[112:115], v[148:151], v[196:199], v[112:115]
	v_mfma_f32_16x16x32_bf16 v[108:111], v[100:103], v[208:211], v[108:111]
	v_mfma_f32_16x16x32_bf16 v[104:107], v[148:151], v[208:211], v[104:107]
	v_mfma_f32_16x16x32_bf16 v[60:63], v[160:163], v[176:179], v[60:63]
	v_mfma_f32_16x16x32_bf16 v[56:59], v[168:171], v[176:179], v[56:59]
	v_mfma_f32_16x16x32_bf16 v[52:55], v[160:163], v[184:187], v[52:55]
	v_mfma_f32_16x16x32_bf16 v[48:51], v[168:171], v[184:187], v[48:51]
	v_mfma_f32_16x16x32_bf16 v[44:47], v[160:163], v[192:195], v[44:47]
	v_mfma_f32_16x16x32_bf16 v[40:43], v[168:171], v[192:195], v[40:43]
	v_mfma_f32_16x16x32_bf16 v[36:39], v[160:163], v[204:207], v[36:39]
	v_mfma_f32_16x16x32_bf16 v[32:35], v[168:171], v[204:207], v[32:35]
	v_mfma_f32_16x16x32_bf16 v[60:63], v[164:167], v[180:183], v[60:63]
	v_mfma_f32_16x16x32_bf16 v[56:59], v[172:175], v[180:183], v[56:59]
	v_mfma_f32_16x16x32_bf16 v[52:55], v[164:167], v[188:191], v[52:55]
	v_mfma_f32_16x16x32_bf16 v[48:51], v[172:175], v[188:191], v[48:51]
	v_mfma_f32_16x16x32_bf16 v[44:47], v[164:167], v[196:199], v[44:47]
	v_mfma_f32_16x16x32_bf16 v[40:43], v[172:175], v[196:199], v[40:43]
	v_mfma_f32_16x16x32_bf16 v[36:39], v[164:167], v[208:211], v[36:39]
	v_mfma_f32_16x16x32_bf16 v[32:35], v[172:175], v[208:211], v[32:35]
	s_barrier
; #define PG8_STAGE(bufoff, gbase, voff) do { _Pragma("unroll") for (int _i = 0; _i < 2; ++_i) \
;         __builtin_amdgcn_global_load_lds((const unsigned*)((const char*)(gbase) + (voff)[_i]), (LAS unsigned*)(lds + (bufoff) + ldsw + _i * 8192), 16, 0, 0); } while (0)
; #define PG8_LDA(dst, b, h) do { _Pragma("unroll") for (int m = 0; m < 4; ++m) _Pragma("unroll") for (int k = 0; k < 2; ++k) dst[m][k] = *(const LAS bf16x8*)(lds + PG8_SA(b, h) + aoff + m * 2048 + k * 1024); } while (0)
; #define PG8_MMA(ai, bj, At, Bt) do { __builtin_amdgcn_s_setprio(1); _Pragma("unroll") for (int m = 0; m < 4; ++m) _Pragma("unroll") for (int n = 0; n < 2; ++n) _Pragma("unroll") for (int k = 0; k < 2; ++k) \
;         acc[ai][bj][m][n] = __builtin_amdgcn_mfma_f32_16x16x32_bf16(Bt[n][k], At[m][k], acc[ai][bj][m][n], 0, 0, 0); __builtin_amdgcn_s_setprio(0); } while (0)
; #define PG8_WAIT_V(n) asm volatile("s_waitcnt vmcnt(" #n ")" ::: "memory")
; #define PG8_WAIT_L(n) asm volatile("s_waitcnt lgkmcnt(" #n ")" ::: "memory")
; #define PG8_BAR __builtin_amdgcn_s_barrier()
; #define PG8_SCHED __builtin_amdgcn_sched_barrier(0)
; template <class Epi>
; __device__ __forceinline__ void gemm_phase(LAS unsigned char* lds, const Gemm g, const Sched& S, const Epi& E) {
;     ...
;             PG8_LDA(At, 1, 1); PG8_STAGE(PG8_SB(1, 0), b3, voffB); PG8_STAGE(PG8_SB(1, 1), b3 + hstepB, voffB); PG8_STAGE(PG8_SA(1, 0), a3, voffA);
;             PG8_WAIT_V(8); PG8_WAIT_L(0); PG8_BAR; PG8_MMA(1, 0, At, B0); PG8_MMA(1, 1, At, B1); PG8_BAR; PG8_SCHED;
;         }
;         if (wr == 0) PG8_BAR;
	s_mov_b32 m0, s64
	v_lshl_add_u64 v[200:201], v[200:201], 0, s[46:47]
	ds_read_b128 v[176:179], v157 offset:49152
	ds_read_b128 v[180:183], v157 offset:50176
	ds_read_b128 v[184:187], v157 offset:51200
	ds_read_b128 v[188:191], v157 offset:52224
	ds_read_b128 v[192:195], v157 offset:53248
	ds_read_b128 v[196:199], v157 offset:54272
	ds_read_b128 v[204:207], v157 offset:55296
	ds_read_b128 v[208:211], v157 offset:56320
	global_load_lds_dwordx4 v[200:201], off
	v_lshl_add_u64 v[200:201], v[212:213], 0, s[46:47]
	s_mov_b32 m0, s62
	s_nop 0
	global_load_lds_dwordx4 v[200:201], off
	v_lshl_add_u64 v[200:201], s[14:15], 0, v[138:139]
	s_mov_b32 m0, s63
	s_nop 0
	global_load_lds_dwordx4 v[200:201], off
	v_lshl_add_u64 v[200:201], s[14:15], 0, v[142:143]
	s_mov_b32 m0, s57
	s_nop 0
	global_load_lds_dwordx4 v[200:201], off
	v_lshl_add_u64 v[200:201], v[214:215], 0, s[46:47]
	s_mov_b32 m0, s97
	s_nop 0
	global_load_lds_dwordx4 v[200:201], off
	v_lshl_add_u64 v[200:201], v[216:217], 0, s[46:47]
	s_mov_b32 m0, s58
	s_nop 0
	global_load_lds_dwordx4 v[200:201], off
	s_waitcnt vmcnt(8)
	s_waitcnt lgkmcnt(0)
	s_barrier
	s_waitcnt lgkmcnt(0)
	v_mfma_f32_16x16x32_bf16 v[92:95], v[96:99], v[176:179], v[92:95]
	v_mfma_f32_16x16x32_bf16 v[88:91], v[144:147], v[176:179], v[88:91]
	v_mfma_f32_16x16x32_bf16 v[84:87], v[96:99], v[184:187], v[84:87]
	v_mfma_f32_16x16x32_bf16 v[80:83], v[144:147], v[184:187], v[80:83]
	v_mfma_f32_16x16x32_bf16 v[76:79], v[96:99], v[192:195], v[76:79]
	v_mfma_f32_16x16x32_bf16 v[72:75], v[144:147], v[192:195], v[72:75]
	v_mfma_f32_16x16x32_bf16 v[68:71], v[96:99], v[204:207], v[68:71]
	v_mfma_f32_16x16x32_bf16 v[64:67], v[144:147], v[204:207], v[64:67]
	v_mfma_f32_16x16x32_bf16 v[92:95], v[100:103], v[180:183], v[92:95]
	v_mfma_f32_16x16x32_bf16 v[88:91], v[148:151], v[180:183], v[88:91]
	v_mfma_f32_16x16x32_bf16 v[84:87], v[100:103], v[188:191], v[84:87]
	v_mfma_f32_16x16x32_bf16 v[80:83], v[148:151], v[188:191], v[80:83]
	v_mfma_f32_16x16x32_bf16 v[76:79], v[100:103], v[196:199], v[76:79]
	v_mfma_f32_16x16x32_bf16 v[72:75], v[148:151], v[196:199], v[72:75]
	v_mfma_f32_16x16x32_bf16 v[68:71], v[100:103], v[208:211], v[68:71]
	v_mfma_f32_16x16x32_bf16 v[64:67], v[148:151], v[208:211], v[64:67]
	v_mfma_f32_16x16x32_bf16 v[28:31], v[160:163], v[176:179], v[28:31]
	v_mfma_f32_16x16x32_bf16 v[24:27], v[168:171], v[176:179], v[24:27]
	v_mfma_f32_16x16x32_bf16 v[20:23], v[160:163], v[184:187], v[20:23]
	v_mfma_f32_16x16x32_bf16 v[16:19], v[168:171], v[184:187], v[16:19]
	v_mfma_f32_16x16x32_bf16 v[12:15], v[160:163], v[192:195], v[12:15]
	v_mfma_f32_16x16x32_bf16 v[8:11], v[168:171], v[192:195], v[8:11]
	v_mfma_f32_16x16x32_bf16 v[4:7], v[160:163], v[204:207], v[4:7]
	v_mfma_f32_16x16x32_bf16 v[0:3], v[168:171], v[204:207], v[0:3]
	v_mfma_f32_16x16x32_bf16 v[28:31], v[164:167], v[180:183], v[28:31]
	v_mfma_f32_16x16x32_bf16 v[24:27], v[172:175], v[180:183], v[24:27]
	v_mfma_f32_16x16x32_bf16 v[20:23], v[164:167], v[188:191], v[20:23]
	v_mfma_f32_16x16x32_bf16 v[16:19], v[172:175], v[188:191], v[16:19]
	v_mfma_f32_16x16x32_bf16 v[12:15], v[164:167], v[196:199], v[12:15]
	v_mfma_f32_16x16x32_bf16 v[8:11], v[172:175], v[196:199], v[8:11]
	v_mfma_f32_16x16x32_bf16 v[4:7], v[164:167], v[208:211], v[4:7]
	v_mfma_f32_16x16x32_bf16 v[0:3], v[172:175], v[208:211], v[0:3]
	s_barrier
	s_andn2_b64 vcc, exec, s[8:9]
	s_mov_b64 s[14:15], -1
	s_mov_b64 s[8:9], 0
	s_mov_b64 s[78:79], 0x100
	s_cbranch_vccz .LBB0_900
	s_and_b64 vcc, exec, s[52:53]
	s_cbranch_vccz .LBB0_903
	s_barrier

; #define LAS __attribute__((address_space(3)))
; #define RUN(k) if (lo <= (k) && (k) < hi) { if ((k) == DUPK) { run_phase<k>(args, lds, G, bx, false); GSYNC(); } run_phase<k>(args, lds, G, bx); if ((k) + 1 < hi) GSYNC(); }
; template <int ph>
; __device__ __forceinline__ void run_phase(const Args& args, LAS unsigned char* lds, const int G, const int bx, const bool fin = true) {
;     ...
;     case 7: if (PHSEL(7)) { PH_IDS
;         const float *state_rwkv = INP(5), *state_shift = INP(6), *state_lru = INP(7), *shift_mu = INP(16), *k_k = INP(22), *k_a = INP(23), *lru_lambda = INP(33);
;         constexpr int TC = 32, VB = 6 * TC * 64;
;         LAS float* VECb = (LAS float*)lds;
;         LAS float* SCb = (LAS float*)(lds + 2 * VB * 4);
;         LAS float* YBb = (LAS float*)(lds + 2 * VB * 4 + 512);
;         for (int unit = bx; unit < 256; unit += G) {
;             const int b = unit >> 5, h = (unit >> 1) & 15, half = unit & 1;
;             const bool producer = wave >= 4;
;             const int ptid = tid & 255, tt0 = ptid >> 4, cgq = ptid & 15, chb = h * 64 + 4 * cgq;
; __global__ void __launch_bounds__(NTHR, 2) mega(Args args) {
;     ...
;     RUN(0) RUN(1) RUN(2) RUN(4) RUN(5) RUN(6) RUN(7) RUN(8) RUN(9) RUN(11) RUN(12) RUN(14) RUN(16) RUN(17)
.LBB0_987:
	s_cmp_lt_i32 s96, 8
	s_cselect_b64 s[0:1], -1, 0
	s_cmp_gt_i32 s97, 7
	s_cselect_b64 s[2:3], -1, 0
	s_and_b64 s[0:1], s[0:1], s[2:3]
	s_andn2_b64 vcc, exec, s[0:1]
	s_cbranch_vccnz .LBB0_1137
	s_setprio 0
	s_add_u32 s8, s34, 0x9e00000
	s_addc_u32 s9, s35, 0
	s_add_u32 s20, s34, 0x18b00000
	s_addc_u32 s21, s35, 0
	s_add_u32 s22, s34, 0x1ac00000
	v_mov_b32_e32 v68, v202
	s_addc_u32 s23, s35, 0
	s_cmpk_lt_i32 s81, 0x100
	v_readfirstlane_b32 s4, v68
	s_cbranch_scc1 .LBB0_990
	v_and_b32_e32 v71, 15, v68
	s_mov_b64 s[0:1], 0
	s_branch .LBB0_991

; #define RUN(k) if (lo <= (k) && (k) < hi) { if ((k) == DUPK) { run_phase<k>(args, lds, G, bx, false); GSYNC(); } run_phase<k>(args, lds, G, bx); if ((k) + 1 < hi) GSYNC(); }
; __global__ void __launch_bounds__(NTHR, 2) mega(Args args) {
;     ...
;     RUN(0) RUN(1) RUN(2) RUN(4) RUN(5) RUN(6) RUN(7) RUN(8) RUN(9) RUN(11) RUN(12) RUN(14) RUN(16) RUN(17)
.LBB0_1083:
	v_readfirstlane_b32 s98, v202
	s_nop 3
	s_bfe_u32 s98, s98, 0x40006
	s_cmp_ge_u32 s98, 4
	s_cbranch_scc0 .Lprio_static_b
	s_setprio 1

; #define PG8_STAGE(bufoff, gbase, voff) do { _Pragma("unroll") for (int _i = 0; _i < 2; ++_i) \
;         __builtin_amdgcn_global_load_lds((const unsigned*)((const char*)(gbase) + (voff)[_i]), (LAS unsigned*)(lds + (bufoff) + ldsw + _i * 8192), 16, 0, 0); } while (0)
; #define PG8_LDA(dst, b, h) do { _Pragma("unroll") for (int m = 0; m < 4; ++m) _Pragma("unroll") for (int k = 0; k < 2; ++k) dst[m][k] = *(const LAS bf16x8*)(lds + PG8_SA(b, h) + aoff + m * 2048 + k * 1024); } while (0)
; #define PG8_LDB(dst, b, h) do { _Pragma("unroll") for (int n = 0; n < 2; ++n) _Pragma("unroll") for (int k = 0; k < 2; ++k) dst[n][k] = *(const LAS bf16x8*)(lds + PG8_SB(b, h) + boff + n * 2048 + k * 1024); } while (0)
; #define PG8_MMA(ai, bj, At, Bt) do { __builtin_amdgcn_s_setprio(1); _Pragma("unroll") for (int m = 0; m < 4; ++m) _Pragma("unroll") for (int n = 0; n < 2; ++n) _Pragma("unroll") for (int k = 0; k < 2; ++k) \
;         acc[ai][bj][m][n] = __builtin_amdgcn_mfma_f32_16x16x32_bf16(Bt[n][k], At[m][k], acc[ai][bj][m][n], 0, 0, 0); __builtin_amdgcn_s_setprio(0); } while (0)
; #define PG8_WAIT_V(n) asm volatile("s_waitcnt vmcnt(" #n ")" ::: "memory")
; #define PG8_WAIT_L(n) asm volatile("s_waitcnt lgkmcnt(" #n ")" ::: "memory")
; #define PG8_BAR __builtin_amdgcn_s_barrier()
; #define PG8_SCHED __builtin_amdgcn_sched_barrier(0)
; template <class Epi>
; __device__ __forceinline__ void gemm_phase(LAS unsigned char* lds, const Gemm g, const Sched& S, const Epi& E) {
;     ...
;         for (int t = 0; t < nt; t += 2) {
;             const bool last = (t == nt - 2);
;             const char* a1 = cA + (size_t)(t + 1) * kstep;
;             const char* a2 = last ? nA : cA + (size_t)(t + 2) * kstep; const char* b2 = last ? nB : cB + (size_t)(t + 2) * kstep;
;             const char* a3 = a2 + kstep; const char* b3 = b2 + kstep;
;             PG8_LDB(B0, 0, 0); PG8_LDB(B1, 0, 1); PG8_SCHED; PG8_LDA(At, 0, 0); PG8_STAGE(PG8_SA(1, 1), a1 + hstepA, voffA);
;             PG8_WAIT_V(8); PG8_WAIT_L(0); PG8_BAR; PG8_MMA(0, 0, At, B0); PG8_MMA(0, 1, At, B1); PG8_BAR; PG8_SCHED;
;             PG8_LDA(At, 0, 1); PG8_STAGE(PG8_SB(0, 0), b2, voffB); PG8_STAGE(PG8_SB(0, 1), b2 + hstepB, voffB); PG8_STAGE(PG8_SA(0, 0), a2, voffA);
.LBB0_1214:
	v_add_u32_e32 v158, s58, v144
	v_add_u32_e32 v174, s59, v144
	s_add_u32 s46, s40, s44
	ds_read_b128 v[146:149], v158
	ds_read_b128 v[150:153], v158 offset:1024
	ds_read_b128 v[154:157], v158 offset:2048
	ds_read_b128 v[158:161], v158 offset:3072
	ds_read_b128 v[162:165], v174
	ds_read_b128 v[166:169], v174 offset:1024
	ds_read_b128 v[170:173], v174 offset:2048
	ds_read_b128 v[174:177], v174 offset:3072
	s_addc_u32 s47, s41, s45
	s_add_u32 s46, s46, 0x100
	s_addc_u32 s47, s47, 0
	s_add_u32 s67, s62, s44
	s_addc_u32 s68, s63, s45
	s_cmpk_eq_i32 s44, 0x700
	s_cselect_b32 s49, s25, s47
	s_cselect_b32 s48, s64, s46
	s_cselect_b32 s47, s27, s68
	s_cselect_b32 s46, s65, s67
	v_lshl_add_u64 v[186:187], v[140:141], 0, s[44:45]
	s_add_i32 m0, s51, 0xc000
	ds_read_b128 v[178:181], v145
	ds_read_b128 v[182:185], v145 offset:1024
	ds_read_b128 v[192:195], v145 offset:2048
	ds_read_b128 v[196:199], v145 offset:3072
	ds_read_b128 v[204:207], v145 offset:4096
	ds_read_b128 v[208:211], v145 offset:5120
	ds_read_b128 v[212:215], v145 offset:6144
	ds_read_b128 v[216:219], v145 offset:7168
	global_load_lds_dwordx4 v[186:187], off
	v_lshl_add_u64 v[186:187], v[142:143], 0, s[44:45]
	s_add_i32 m0, s51, 0xe000
	s_nop 0
	global_load_lds_dwordx4 v[186:187], off
	s_waitcnt vmcnt(8)
	s_waitcnt lgkmcnt(0)
	s_barrier
	s_waitcnt lgkmcnt(0)
	v_mfma_f32_16x16x32_bf16 v[124:127], v[146:149], v[178:181], v[124:127]
	v_mfma_f32_16x16x32_bf16 v[120:123], v[154:157], v[178:181], v[120:123]
	v_mfma_f32_16x16x32_bf16 v[108:111], v[146:149], v[192:195], v[108:111]
	v_mfma_f32_16x16x32_bf16 v[104:107], v[154:157], v[192:195], v[104:107]
	v_mfma_f32_16x16x32_bf16 v[92:95], v[146:149], v[204:207], v[92:95]
	v_mfma_f32_16x16x32_bf16 v[88:91], v[154:157], v[204:207], v[88:91]
	v_mfma_f32_16x16x32_bf16 v[76:79], v[146:149], v[212:215], v[76:79]
	v_mfma_f32_16x16x32_bf16 v[72:75], v[154:157], v[212:215], v[72:75]
	v_mfma_f32_16x16x32_bf16 v[124:127], v[150:153], v[182:185], v[124:127]
	v_mfma_f32_16x16x32_bf16 v[120:123], v[158:161], v[182:185], v[120:123]
	v_mfma_f32_16x16x32_bf16 v[108:111], v[150:153], v[196:199], v[108:111]
	v_mfma_f32_16x16x32_bf16 v[104:107], v[158:161], v[196:199], v[104:107]
	v_mfma_f32_16x16x32_bf16 v[92:95], v[150:153], v[208:211], v[92:95]
	v_mfma_f32_16x16x32_bf16 v[88:91], v[158:161], v[208:211], v[88:91]
	v_mfma_f32_16x16x32_bf16 v[76:79], v[150:153], v[216:219], v[76:79]
	v_mfma_f32_16x16x32_bf16 v[72:75], v[158:161], v[216:219], v[72:75]
	v_mfma_f32_16x16x32_bf16 v[116:119], v[162:165], v[178:181], v[116:119]
	v_mfma_f32_16x16x32_bf16 v[112:115], v[170:173], v[178:181], v[112:115]
	v_mfma_f32_16x16x32_bf16 v[100:103], v[162:165], v[192:195], v[100:103]
	v_mfma_f32_16x16x32_bf16 v[96:99], v[170:173], v[192:195], v[96:99]
	v_mfma_f32_16x16x32_bf16 v[84:87], v[162:165], v[204:207], v[84:87]
	v_mfma_f32_16x16x32_bf16 v[80:83], v[170:173], v[204:207], v[80:83]
	v_mfma_f32_16x16x32_bf16 v[68:71], v[162:165], v[212:215], v[68:71]
	v_mfma_f32_16x16x32_bf16 v[64:67], v[170:173], v[212:215], v[64:67]
	v_mfma_f32_16x16x32_bf16 v[116:119], v[166:169], v[182:185], v[116:119]
	v_mfma_f32_16x16x32_bf16 v[112:115], v[174:177], v[182:185], v[112:115]
	v_mfma_f32_16x16x32_bf16 v[100:103], v[166:169], v[196:199], v[100:103]
	v_mfma_f32_16x16x32_bf16 v[96:99], v[174:177], v[196:199], v[96:99]
	v_mfma_f32_16x16x32_bf16 v[84:87], v[166:169], v[208:211], v[84:87]
	v_mfma_f32_16x16x32_bf16 v[80:83], v[174:177], v[208:211], v[80:83]
	v_mfma_f32_16x16x32_bf16 v[68:71], v[166:169], v[216:219], v[68:71]
	v_mfma_f32_16x16x32_bf16 v[64:67], v[174:177], v[216:219], v[64:67]
	s_barrier
	s_add_i32 s67, s58, s50
	v_lshl_add_u64 v[186:187], s[46:47], 0, v[130:131]
	s_mov_b32 m0, s67
	ds_read_b128 v[178:181], v145 offset:16384
	ds_read_b128 v[182:185], v145 offset:17408
	ds_read_b128 v[192:195], v145 offset:18432
	ds_read_b128 v[196:199], v145 offset:19456
	ds_read_b128 v[204:207], v145 offset:20480
	ds_read_b128 v[208:211], v145 offset:21504
	ds_read_b128 v[212:215], v145 offset:22528
	ds_read_b128 v[216:219], v145 offset:23552
	global_load_lds_dwordx4 v[186:187], off
	s_add_i32 m0, s67, 0x2000
	s_add_u32 s68, s46, 0x40000
	v_lshl_add_u64 v[200:201], s[46:47], 0, v[134:135]
	s_addc_u32 s69, s47, 0
	s_add_i32 s67, s59, s50
	global_load_lds_dwordx4 v[200:201], off
	v_lshl_add_u64 v[220:221], s[68:69], 0, v[130:131]
	s_mov_b32 m0, s67
	v_lshl_add_u64 v[222:223], s[48:49], 0, v[132:133]
	global_load_lds_dwordx4 v[220:221], off
	v_lshl_add_u64 v[220:221], s[68:69], 0, v[134:135]
	s_add_i32 m0, s67, 0x2000
	s_nop 0
	global_load_lds_dwordx4 v[220:221], off
	v_lshl_add_u64 v[220:221], s[48:49], 0, v[128:129]
	s_mov_b32 m0, s51
	s_nop 0
	global_load_lds_dwordx4 v[220:221], off
	s_mov_b32 m0, s52
	s_nop 0
	global_load_lds_dwordx4 v[222:223], off
	s_waitcnt vmcnt(8)
	s_waitcnt lgkmcnt(0)
	s_barrier
; #define PG8_STAGE(bufoff, gbase, voff) do { _Pragma("unroll") for (int _i = 0; _i < 2; ++_i) \
;         __builtin_amdgcn_global_load_lds((const unsigned*)((const char*)(gbase) + (voff)[_i]), (LAS unsigned*)(lds + (bufoff) + ldsw + _i * 8192), 16, 0, 0); } while (0)
; #define PG8_LDA(dst, b, h) do { _Pragma("unroll") for (int m = 0; m < 4; ++m) _Pragma("unroll") for (int k = 0; k < 2; ++k) dst[m][k] = *(const LAS bf16x8*)(lds + PG8_SA(b, h) + aoff + m * 2048 + k * 1024); } while (0)
; #define PG8_LDB(dst, b, h) do { _Pragma("unroll") for (int n = 0; n < 2; ++n) _Pragma("unroll") for (int k = 0; k < 2; ++k) dst[n][k] = *(const LAS bf16x8*)(lds + PG8_SB(b, h) + boff + n * 2048 + k * 1024); } while (0)
; #define PG8_MMA(ai, bj, At, Bt) do { __builtin_amdgcn_s_setprio(1); _Pragma("unroll") for (int m = 0; m < 4; ++m) _Pragma("unroll") for (int n = 0; n < 2; ++n) _Pragma("unroll") for (int k = 0; k < 2; ++k) \
;         acc[ai][bj][m][n] = __builtin_amdgcn_mfma_f32_16x16x32_bf16(Bt[n][k], At[m][k], acc[ai][bj][m][n], 0, 0, 0); __builtin_amdgcn_s_setprio(0); } while (0)
; #define PG8_WAIT_V(n) asm volatile("s_waitcnt vmcnt(" #n ")" ::: "memory")
; #define PG8_WAIT_L(n) asm volatile("s_waitcnt lgkmcnt(" #n ")" ::: "memory")
; #define PG8_BAR __builtin_amdgcn_s_barrier()
; #define PG8_SCHED __builtin_amdgcn_sched_barrier(0)
; template <class Epi>
; __device__ __forceinline__ void gemm_phase(LAS unsigned char* lds, const Gemm g, const Sched& S, const Epi& E) {
;     ...
;             PG8_WAIT_V(8); PG8_WAIT_L(0); PG8_BAR; PG8_MMA(1, 0, At, B0); PG8_MMA(1, 1, At, B1); PG8_BAR; PG8_SCHED;
;             PG8_LDB(B0, 1, 0); PG8_LDB(B1, 1, 1); PG8_SCHED; PG8_LDA(At, 1, 0); PG8_STAGE(PG8_SA(0, 1), a2 + hstepA, voffA);
;             PG8_WAIT_V(8); PG8_WAIT_L(0); PG8_BAR; PG8_MMA(0, 0, At, B0); PG8_MMA(0, 1, At, B1); PG8_BAR; PG8_SCHED;
	s_waitcnt lgkmcnt(0)
	v_mfma_f32_16x16x32_bf16 v[60:63], v[146:149], v[178:181], v[60:63]
	v_mfma_f32_16x16x32_bf16 v[56:59], v[154:157], v[178:181], v[56:59]
	v_mfma_f32_16x16x32_bf16 v[44:47], v[146:149], v[192:195], v[44:47]
	v_mfma_f32_16x16x32_bf16 v[40:43], v[154:157], v[192:195], v[40:43]
	v_mfma_f32_16x16x32_bf16 v[28:31], v[146:149], v[204:207], v[28:31]
	v_mfma_f32_16x16x32_bf16 v[24:27], v[154:157], v[204:207], v[24:27]
	v_mfma_f32_16x16x32_bf16 v[12:15], v[146:149], v[212:215], v[12:15]
	v_mfma_f32_16x16x32_bf16 v[8:11], v[154:157], v[212:215], v[8:11]
	v_mfma_f32_16x16x32_bf16 v[60:63], v[150:153], v[182:185], v[60:63]
	v_mfma_f32_16x16x32_bf16 v[56:59], v[158:161], v[182:185], v[56:59]
	v_mfma_f32_16x16x32_bf16 v[44:47], v[150:153], v[196:199], v[44:47]
	v_mfma_f32_16x16x32_bf16 v[40:43], v[158:161], v[196:199], v[40:43]
	v_mfma_f32_16x16x32_bf16 v[28:31], v[150:153], v[208:211], v[28:31]
	v_mfma_f32_16x16x32_bf16 v[24:27], v[158:161], v[208:211], v[24:27]
	v_mfma_f32_16x16x32_bf16 v[12:15], v[150:153], v[216:219], v[12:15]
	v_mfma_f32_16x16x32_bf16 v[8:11], v[158:161], v[216:219], v[8:11]
	v_mfma_f32_16x16x32_bf16 v[52:55], v[162:165], v[178:181], v[52:55]
	v_mfma_f32_16x16x32_bf16 v[48:51], v[170:173], v[178:181], v[48:51]
	v_mfma_f32_16x16x32_bf16 v[36:39], v[162:165], v[192:195], v[36:39]
	v_mfma_f32_16x16x32_bf16 v[32:35], v[170:173], v[192:195], v[32:35]
	v_mfma_f32_16x16x32_bf16 v[20:23], v[162:165], v[204:207], v[20:23]
	v_mfma_f32_16x16x32_bf16 v[16:19], v[170:173], v[204:207], v[16:19]
	v_mfma_f32_16x16x32_bf16 v[4:7], v[162:165], v[212:215], v[4:7]
	v_mfma_f32_16x16x32_bf16 v[0:3], v[170:173], v[212:215], v[0:3]
	v_mfma_f32_16x16x32_bf16 v[52:55], v[166:169], v[182:185], v[52:55]
	v_mfma_f32_16x16x32_bf16 v[48:51], v[174:177], v[182:185], v[48:51]
	v_mfma_f32_16x16x32_bf16 v[36:39], v[166:169], v[196:199], v[36:39]
	v_mfma_f32_16x16x32_bf16 v[32:35], v[174:177], v[196:199], v[32:35]
	v_mfma_f32_16x16x32_bf16 v[20:23], v[166:169], v[208:211], v[20:23]
	v_mfma_f32_16x16x32_bf16 v[16:19], v[174:177], v[208:211], v[16:19]
	v_mfma_f32_16x16x32_bf16 v[4:7], v[166:169], v[216:219], v[4:7]
	v_mfma_f32_16x16x32_bf16 v[0:3], v[174:177], v[216:219], v[0:3]
	s_barrier
	s_add_i32 s67, 0, 0x18000
	s_add_i32 s68, 0, 0x1c000
	v_add_u32_e32 v158, s67, v144
	v_add_u32_e32 v174, s68, v144
	ds_read_b128 v[146:149], v158
	ds_read_b128 v[150:153], v158 offset:1024
	ds_read_b128 v[154:157], v158 offset:2048
	ds_read_b128 v[158:161], v158 offset:3072
	ds_read_b128 v[162:165], v174
	ds_read_b128 v[166:169], v174 offset:1024
	ds_read_b128 v[170:173], v174 offset:2048
	ds_read_b128 v[174:177], v174 offset:3072
	s_add_u32 s48, s48, 0x40000
	s_addc_u32 s49, s49, 0
	s_mov_b32 m0, s53
	v_lshl_add_u64 v[224:225], s[48:49], 0, v[128:129]
	ds_read_b128 v[178:181], v145 offset:32768
	ds_read_b128 v[182:185], v145 offset:33792
	ds_read_b128 v[192:195], v145 offset:34816
	ds_read_b128 v[196:199], v145 offset:35840
	ds_read_b128 v[204:207], v145 offset:36864
	ds_read_b128 v[208:211], v145 offset:37888
	ds_read_b128 v[212:215], v145 offset:38912
	ds_read_b128 v[216:219], v145 offset:39936
	global_load_lds_dwordx4 v[224:225], off
	v_lshl_add_u64 v[224:225], s[48:49], 0, v[132:133]
	s_mov_b32 m0, s54
	s_nop 0
	global_load_lds_dwordx4 v[224:225], off
	s_waitcnt vmcnt(8)
	s_waitcnt lgkmcnt(0)
	s_barrier
	s_waitcnt lgkmcnt(0)
	v_mfma_f32_16x16x32_bf16 v[124:127], v[146:149], v[178:181], v[124:127]
	v_mfma_f32_16x16x32_bf16 v[120:123], v[154:157], v[178:181], v[120:123]
	v_mfma_f32_16x16x32_bf16 v[108:111], v[146:149], v[192:195], v[108:111]
	v_mfma_f32_16x16x32_bf16 v[104:107], v[154:157], v[192:195], v[104:107]
	v_mfma_f32_16x16x32_bf16 v[92:95], v[146:149], v[204:207], v[92:95]
	v_mfma_f32_16x16x32_bf16 v[88:91], v[154:157], v[204:207], v[88:91]
	v_mfma_f32_16x16x32_bf16 v[76:79], v[146:149], v[212:215], v[76:79]
	v_mfma_f32_16x16x32_bf16 v[72:75], v[154:157], v[212:215], v[72:75]
	v_mfma_f32_16x16x32_bf16 v[124:127], v[150:153], v[182:185], v[124:127]
	v_mfma_f32_16x16x32_bf16 v[120:123], v[158:161], v[182:185], v[120:123]
	v_mfma_f32_16x16x32_bf16 v[108:111], v[150:153], v[196:199], v[108:111]
	v_mfma_f32_16x16x32_bf16 v[104:107], v[158:161], v[196:199], v[104:107]
	v_mfma_f32_16x16x32_bf16 v[92:95], v[150:153], v[208:211], v[92:95]
	v_mfma_f32_16x16x32_bf16 v[88:91], v[158:161], v[208:211], v[88:91]
	v_mfma_f32_16x16x32_bf16 v[76:79], v[150:153], v[216:219], v[76:79]
	v_mfma_f32_16x16x32_bf16 v[72:75], v[158:161], v[216:219], v[72:75]
	v_mfma_f32_16x16x32_bf16 v[116:119], v[162:165], v[178:181], v[116:119]
	v_mfma_f32_16x16x32_bf16 v[112:115], v[170:173], v[178:181], v[112:115]
	v_mfma_f32_16x16x32_bf16 v[100:103], v[162:165], v[192:195], v[100:103]
	v_mfma_f32_16x16x32_bf16 v[96:99], v[170:173], v[192:195], v[96:99]
	v_mfma_f32_16x16x32_bf16 v[84:87], v[162:165], v[204:207], v[84:87]
	v_mfma_f32_16x16x32_bf16 v[80:83], v[170:173], v[204:207], v[80:83]
	v_mfma_f32_16x16x32_bf16 v[68:71], v[162:165], v[212:215], v[68:71]
	v_mfma_f32_16x16x32_bf16 v[64:67], v[170:173], v[212:215], v[64:67]
	v_mfma_f32_16x16x32_bf16 v[116:119], v[166:169], v[182:185], v[116:119]
	v_mfma_f32_16x16x32_bf16 v[112:115], v[174:177], v[182:185], v[112:115]
	v_mfma_f32_16x16x32_bf16 v[100:103], v[166:169], v[196:199], v[100:103]
	v_mfma_f32_16x16x32_bf16 v[96:99], v[174:177], v[196:199], v[96:99]
	v_mfma_f32_16x16x32_bf16 v[84:87], v[166:169], v[208:211], v[84:87]
	v_mfma_f32_16x16x32_bf16 v[80:83], v[174:177], v[208:211], v[80:83]
	v_mfma_f32_16x16x32_bf16 v[68:71], v[166:169], v[216:219], v[68:71]
	v_mfma_f32_16x16x32_bf16 v[64:67], v[174:177], v[216:219], v[64:67]
	s_barrier
; #define PG8_STAGE(bufoff, gbase, voff) do { _Pragma("unroll") for (int _i = 0; _i < 2; ++_i) \
;         __builtin_amdgcn_global_load_lds((const unsigned*)((const char*)(gbase) + (voff)[_i]), (LAS unsigned*)(lds + (bufoff) + ldsw + _i * 8192), 16, 0, 0); } while (0)
; #define PG8_LDA(dst, b, h) do { _Pragma("unroll") for (int m = 0; m < 4; ++m) _Pragma("unroll") for (int k = 0; k < 2; ++k) dst[m][k] = *(const LAS bf16x8*)(lds + PG8_SA(b, h) + aoff + m * 2048 + k * 1024); } while (0)
; #define PG8_MMA(ai, bj, At, Bt) do { __builtin_amdgcn_s_setprio(1); _Pragma("unroll") for (int m = 0; m < 4; ++m) _Pragma("unroll") for (int n = 0; n < 2; ++n) _Pragma("unroll") for (int k = 0; k < 2; ++k) \
;         acc[ai][bj][m][n] = __builtin_amdgcn_mfma_f32_16x16x32_bf16(Bt[n][k], At[m][k], acc[ai][bj][m][n], 0, 0, 0); __builtin_amdgcn_s_setprio(0); } while (0)
; #define PG8_WAIT_V(n) asm volatile("s_waitcnt vmcnt(" #n ")" ::: "memory")
; #define PG8_WAIT_L(n) asm volatile("s_waitcnt lgkmcnt(" #n ")" ::: "memory")
; #define PG8_BAR __builtin_amdgcn_s_barrier()
; #define PG8_SCHED __builtin_amdgcn_sched_barrier(0)
; template <class Epi>
; __device__ __forceinline__ void gemm_phase(LAS unsigned char* lds, const Gemm g, const Sched& S, const Epi& E) {
;     ...
;             PG8_LDA(At, 1, 1); PG8_STAGE(PG8_SB(1, 0), b3, voffB); PG8_STAGE(PG8_SB(1, 1), b3 + hstepB, voffB); PG8_STAGE(PG8_SA(1, 0), a3, voffA);
;             PG8_WAIT_V(8); PG8_WAIT_L(0); PG8_BAR; PG8_MMA(1, 0, At, B0); PG8_MMA(1, 1, At, B1); PG8_BAR; PG8_SCHED;
;         }
;         if (wr == 0) PG8_BAR;
	s_add_i32 s48, s67, s50
	v_lshl_add_u64 v[186:187], v[186:187], 0, s[4:5]
	s_mov_b32 m0, s48
	ds_read_b128 v[178:181], v145 offset:49152
	ds_read_b128 v[182:185], v145 offset:50176
	ds_read_b128 v[192:195], v145 offset:51200
	ds_read_b128 v[196:199], v145 offset:52224
	ds_read_b128 v[204:207], v145 offset:53248
	ds_read_b128 v[208:211], v145 offset:54272
	ds_read_b128 v[212:215], v145 offset:55296
	ds_read_b128 v[216:219], v145 offset:56320
	global_load_lds_dwordx4 v[186:187], off
	s_add_i32 m0, s48, 0x2000
	s_add_u32 s46, s46, 0x40080
	v_lshl_add_u64 v[186:187], v[200:201], 0, s[4:5]
	s_addc_u32 s47, s47, 0
	s_add_i32 s48, s68, s50
	global_load_lds_dwordx4 v[186:187], off
	v_lshl_add_u64 v[186:187], s[46:47], 0, v[130:131]
	s_mov_b32 m0, s48
	s_nop 0
	global_load_lds_dwordx4 v[186:187], off
	v_lshl_add_u64 v[186:187], s[46:47], 0, v[134:135]
	s_add_i32 m0, s48, 0x2000
	s_nop 0
	global_load_lds_dwordx4 v[186:187], off
	v_lshl_add_u64 v[186:187], v[220:221], 0, s[4:5]
	s_mov_b32 m0, s56
	s_nop 0
	global_load_lds_dwordx4 v[186:187], off
	v_lshl_add_u64 v[186:187], v[222:223], 0, s[4:5]
	s_mov_b32 m0, s57
	s_nop 0
	global_load_lds_dwordx4 v[186:187], off
	s_waitcnt vmcnt(8)
	s_waitcnt lgkmcnt(0)
	s_barrier
	s_waitcnt lgkmcnt(0)
	v_mfma_f32_16x16x32_bf16 v[60:63], v[146:149], v[178:181], v[60:63]
	v_mfma_f32_16x16x32_bf16 v[56:59], v[154:157], v[178:181], v[56:59]
	v_mfma_f32_16x16x32_bf16 v[44:47], v[146:149], v[192:195], v[44:47]
	v_mfma_f32_16x16x32_bf16 v[40:43], v[154:157], v[192:195], v[40:43]
	v_mfma_f32_16x16x32_bf16 v[28:31], v[146:149], v[204:207], v[28:31]
	v_mfma_f32_16x16x32_bf16 v[24:27], v[154:157], v[204:207], v[24:27]
	v_mfma_f32_16x16x32_bf16 v[12:15], v[146:149], v[212:215], v[12:15]
	v_mfma_f32_16x16x32_bf16 v[8:11], v[154:157], v[212:215], v[8:11]
	v_mfma_f32_16x16x32_bf16 v[60:63], v[150:153], v[182:185], v[60:63]
	v_mfma_f32_16x16x32_bf16 v[56:59], v[158:161], v[182:185], v[56:59]
	v_mfma_f32_16x16x32_bf16 v[44:47], v[150:153], v[196:199], v[44:47]
	v_mfma_f32_16x16x32_bf16 v[40:43], v[158:161], v[196:199], v[40:43]
	v_mfma_f32_16x16x32_bf16 v[28:31], v[150:153], v[208:211], v[28:31]
	v_mfma_f32_16x16x32_bf16 v[24:27], v[158:161], v[208:211], v[24:27]
	v_mfma_f32_16x16x32_bf16 v[12:15], v[150:153], v[216:219], v[12:15]
	v_mfma_f32_16x16x32_bf16 v[8:11], v[158:161], v[216:219], v[8:11]
	v_mfma_f32_16x16x32_bf16 v[52:55], v[162:165], v[178:181], v[52:55]
	v_mfma_f32_16x16x32_bf16 v[48:51], v[170:173], v[178:181], v[48:51]
	v_mfma_f32_16x16x32_bf16 v[36:39], v[162:165], v[192:195], v[36:39]
	v_mfma_f32_16x16x32_bf16 v[32:35], v[170:173], v[192:195], v[32:35]
	v_mfma_f32_16x16x32_bf16 v[20:23], v[162:165], v[204:207], v[20:23]
	v_mfma_f32_16x16x32_bf16 v[16:19], v[170:173], v[204:207], v[16:19]
	v_mfma_f32_16x16x32_bf16 v[4:7], v[162:165], v[212:215], v[4:7]
	v_mfma_f32_16x16x32_bf16 v[0:3], v[170:173], v[212:215], v[0:3]
	v_mfma_f32_16x16x32_bf16 v[52:55], v[166:169], v[182:185], v[52:55]
	v_mfma_f32_16x16x32_bf16 v[48:51], v[174:177], v[182:185], v[48:51]
	v_mfma_f32_16x16x32_bf16 v[36:39], v[166:169], v[196:199], v[36:39]
	v_mfma_f32_16x16x32_bf16 v[32:35], v[174:177], v[196:199], v[32:35]
	v_mfma_f32_16x16x32_bf16 v[20:23], v[166:169], v[208:211], v[20:23]
	v_mfma_f32_16x16x32_bf16 v[16:19], v[174:177], v[208:211], v[16:19]
	v_mfma_f32_16x16x32_bf16 v[4:7], v[166:169], v[216:219], v[4:7]
	v_mfma_f32_16x16x32_bf16 v[0:3], v[174:177], v[216:219], v[0:3]
	s_barrier
	s_add_i32 s66, s66, 2
	s_add_u32 s44, s44, 0x100
	s_addc_u32 s45, s45, 0
	s_cmp_gt_u32 s66, 13
	s_cbranch_scc0 .LBB0_1214
	s_and_b64 vcc, exec, s[22:23]
	s_cbranch_vccz .LBB0_1217
	s_barrier

; #define PG8_STAGE(bufoff, gbase, voff) do { _Pragma("unroll") for (int _i = 0; _i < 2; ++_i) \
;         __builtin_amdgcn_global_load_lds((const unsigned*)((const char*)(gbase) + (voff)[_i]), (LAS unsigned*)(lds + (bufoff) + ldsw + _i * 8192), 16, 0, 0); } while (0)
; #define PG8_LDA(dst, b, h) do { _Pragma("unroll") for (int m = 0; m < 4; ++m) _Pragma("unroll") for (int k = 0; k < 2; ++k) dst[m][k] = *(const LAS bf16x8*)(lds + PG8_SA(b, h) + aoff + m * 2048 + k * 1024); } while (0)
; #define PG8_LDB(dst, b, h) do { _Pragma("unroll") for (int n = 0; n < 2; ++n) _Pragma("unroll") for (int k = 0; k < 2; ++k) dst[n][k] = *(const LAS bf16x8*)(lds + PG8_SB(b, h) + boff + n * 2048 + k * 1024); } while (0)
; #define PG8_MMA(ai, bj, At, Bt) do { __builtin_amdgcn_s_setprio(1); _Pragma("unroll") for (int m = 0; m < 4; ++m) _Pragma("unroll") for (int n = 0; n < 2; ++n) _Pragma("unroll") for (int k = 0; k < 2; ++k) \
;         acc[ai][bj][m][n] = __builtin_amdgcn_mfma_f32_16x16x32_bf16(Bt[n][k], At[m][k], acc[ai][bj][m][n], 0, 0, 0); __builtin_amdgcn_s_setprio(0); } while (0)
; #define PG8_WAIT_V(n) asm volatile("s_waitcnt vmcnt(" #n ")" ::: "memory")
; #define PG8_WAIT_L(n) asm volatile("s_waitcnt lgkmcnt(" #n ")" ::: "memory")
; #define PG8_BAR __builtin_amdgcn_s_barrier()
; #define PG8_SCHED __builtin_amdgcn_sched_barrier(0)
; template <class Epi>
; __device__ __forceinline__ void gemm_phase(LAS unsigned char* lds, const Gemm g, const Sched& S, const Epi& E) {
;     ...
;         for (int t = 0; t < nt; t += 2) {
;             const bool last = (t == nt - 2);
;             const char* a1 = cA + (size_t)(t + 1) * kstep;
;             const char* a2 = last ? nA : cA + (size_t)(t + 2) * kstep; const char* b2 = last ? nB : cB + (size_t)(t + 2) * kstep;
;             const char* a3 = a2 + kstep; const char* b3 = b2 + kstep;
;             PG8_LDB(B0, 0, 0); PG8_LDB(B1, 0, 1); PG8_SCHED; PG8_LDA(At, 0, 0); PG8_STAGE(PG8_SA(1, 1), a1 + hstepA, voffA);
;             PG8_WAIT_V(8); PG8_WAIT_L(0); PG8_BAR; PG8_MMA(0, 0, At, B0); PG8_MMA(0, 1, At, B1); PG8_BAR; PG8_SCHED;
;             PG8_LDA(At, 0, 1); PG8_STAGE(PG8_SB(0, 0), b2, voffB); PG8_STAGE(PG8_SB(0, 1), b2 + hstepB, voffB); PG8_STAGE(PG8_SA(0, 0), a2, voffA);
.LBB0_1355:
	ds_read_b128 v[140:143], v148
	ds_read_b128 v[152:155], v148 offset:1024
	ds_read_b128 v[156:159], v148 offset:2048
	ds_read_b128 v[160:163], v148 offset:3072
	ds_read_b128 v[164:167], v149
	ds_read_b128 v[168:171], v149 offset:1024
	ds_read_b128 v[172:175], v149 offset:2048
	ds_read_b128 v[176:179], v149 offset:3072
	s_add_u32 s40, s38, 0xfffc0080
	s_addc_u32 s41, s39, -1
	s_cmp_eq_u32 s54, 12
	s_cselect_b32 s43, s23, s41
	s_cselect_b32 s42, s50, s40
	s_cselect_b32 s41, s25, s53
	s_cselect_b32 s40, s51, s52
	v_lshl_add_u64 v[200:201], s[38:39], 0, v[136:137]
	s_add_i32 m0, s11, 0xc000
	ds_read_b128 v[180:183], v150
	ds_read_b128 v[184:187], v150 offset:1024
	ds_read_b128 v[188:191], v150 offset:2048
	ds_read_b128 v[192:195], v150 offset:3072
	ds_read_b128 v[196:199], v150 offset:4096
	ds_read_b128 v[204:207], v150 offset:5120
	ds_read_b128 v[208:211], v150 offset:6144
	ds_read_b128 v[212:215], v150 offset:7168
	global_load_lds_dwordx4 v[200:201], off
	v_lshl_add_u64 v[200:201], s[38:39], 0, v[138:139]
	s_add_i32 m0, s11, 0xe000
	s_nop 0
	global_load_lds_dwordx4 v[200:201], off
	s_waitcnt vmcnt(8)
	s_waitcnt lgkmcnt(0)
	s_barrier
	s_waitcnt lgkmcnt(0)
	v_mfma_f32_16x16x32_bf16 v[124:127], v[140:143], v[180:183], v[124:127]
	v_mfma_f32_16x16x32_bf16 v[120:123], v[156:159], v[180:183], v[120:123]
	v_mfma_f32_16x16x32_bf16 v[116:119], v[140:143], v[188:191], v[116:119]
	v_mfma_f32_16x16x32_bf16 v[108:111], v[156:159], v[188:191], v[108:111]
	v_mfma_f32_16x16x32_bf16 v[100:103], v[140:143], v[196:199], v[100:103]
	v_mfma_f32_16x16x32_bf16 v[92:95], v[156:159], v[196:199], v[92:95]
	v_mfma_f32_16x16x32_bf16 v[84:87], v[140:143], v[208:211], v[84:87]
	v_mfma_f32_16x16x32_bf16 v[76:79], v[156:159], v[208:211], v[76:79]
	v_mfma_f32_16x16x32_bf16 v[124:127], v[152:155], v[184:187], v[124:127]
	v_mfma_f32_16x16x32_bf16 v[120:123], v[160:163], v[184:187], v[120:123]
	v_mfma_f32_16x16x32_bf16 v[116:119], v[152:155], v[192:195], v[116:119]
	v_mfma_f32_16x16x32_bf16 v[108:111], v[160:163], v[192:195], v[108:111]
	v_mfma_f32_16x16x32_bf16 v[100:103], v[152:155], v[204:207], v[100:103]
	v_mfma_f32_16x16x32_bf16 v[92:95], v[160:163], v[204:207], v[92:95]
	v_mfma_f32_16x16x32_bf16 v[84:87], v[152:155], v[212:215], v[84:87]
	v_mfma_f32_16x16x32_bf16 v[76:79], v[160:163], v[212:215], v[76:79]
	v_mfma_f32_16x16x32_bf16 v[112:115], v[164:167], v[180:183], v[112:115]
	v_mfma_f32_16x16x32_bf16 v[104:107], v[172:175], v[180:183], v[104:107]
	v_mfma_f32_16x16x32_bf16 v[96:99], v[164:167], v[188:191], v[96:99]
	v_mfma_f32_16x16x32_bf16 v[88:91], v[172:175], v[188:191], v[88:91]
	v_mfma_f32_16x16x32_bf16 v[80:83], v[164:167], v[196:199], v[80:83]
	v_mfma_f32_16x16x32_bf16 v[72:75], v[172:175], v[196:199], v[72:75]
	v_mfma_f32_16x16x32_bf16 v[68:71], v[164:167], v[208:211], v[68:71]
	v_mfma_f32_16x16x32_bf16 v[64:67], v[172:175], v[208:211], v[64:67]
	v_mfma_f32_16x16x32_bf16 v[112:115], v[168:171], v[184:187], v[112:115]
	v_mfma_f32_16x16x32_bf16 v[104:107], v[176:179], v[184:187], v[104:107]
	v_mfma_f32_16x16x32_bf16 v[96:99], v[168:171], v[192:195], v[96:99]
	v_mfma_f32_16x16x32_bf16 v[88:91], v[176:179], v[192:195], v[88:91]
	v_mfma_f32_16x16x32_bf16 v[80:83], v[168:171], v[204:207], v[80:83]
	v_mfma_f32_16x16x32_bf16 v[72:75], v[176:179], v[204:207], v[72:75]
	v_mfma_f32_16x16x32_bf16 v[68:71], v[168:171], v[212:215], v[68:71]
	v_mfma_f32_16x16x32_bf16 v[64:67], v[176:179], v[212:215], v[64:67]
	s_barrier
	s_add_i32 s55, s47, s10
	v_lshl_add_u64 v[200:201], s[40:41], 0, v[130:131]
	s_mov_b32 m0, s55
	ds_read_b128 v[180:183], v150 offset:16384
	ds_read_b128 v[184:187], v150 offset:17408
	ds_read_b128 v[188:191], v150 offset:18432
	ds_read_b128 v[192:195], v150 offset:19456
	ds_read_b128 v[196:199], v150 offset:20480
	ds_read_b128 v[204:207], v150 offset:21504
	ds_read_b128 v[208:211], v150 offset:22528
	ds_read_b128 v[212:215], v150 offset:23552
	global_load_lds_dwordx4 v[200:201], off
	s_add_i32 m0, s55, 0x2000
	s_add_u32 s56, s40, 0x40000
	v_lshl_add_u64 v[216:217], s[40:41], 0, v[134:135]
	s_addc_u32 s57, s41, 0
	s_add_i32 s55, s48, s10
	global_load_lds_dwordx4 v[216:217], off
	v_lshl_add_u64 v[218:219], s[56:57], 0, v[130:131]
	s_mov_b32 m0, s55
	v_lshl_add_u64 v[220:221], s[42:43], 0, v[132:133]
	global_load_lds_dwordx4 v[218:219], off
	v_lshl_add_u64 v[218:219], s[56:57], 0, v[134:135]
	s_add_i32 m0, s55, 0x2000
	s_nop 0
	global_load_lds_dwordx4 v[218:219], off
	v_lshl_add_u64 v[218:219], s[42:43], 0, v[128:129]
	s_mov_b32 m0, s11
	s_nop 0
	global_load_lds_dwordx4 v[218:219], off
	s_mov_b32 m0, s13
	s_nop 0
	global_load_lds_dwordx4 v[220:221], off
	s_waitcnt vmcnt(8)
	s_waitcnt lgkmcnt(0)
	s_barrier
; #define PG8_STAGE(bufoff, gbase, voff) do { _Pragma("unroll") for (int _i = 0; _i < 2; ++_i) \
;         __builtin_amdgcn_global_load_lds((const unsigned*)((const char*)(gbase) + (voff)[_i]), (LAS unsigned*)(lds + (bufoff) + ldsw + _i * 8192), 16, 0, 0); } while (0)
; #define PG8_LDA(dst, b, h) do { _Pragma("unroll") for (int m = 0; m < 4; ++m) _Pragma("unroll") for (int k = 0; k < 2; ++k) dst[m][k] = *(const LAS bf16x8*)(lds + PG8_SA(b, h) + aoff + m * 2048 + k * 1024); } while (0)
; #define PG8_LDB(dst, b, h) do { _Pragma("unroll") for (int n = 0; n < 2; ++n) _Pragma("unroll") for (int k = 0; k < 2; ++k) dst[n][k] = *(const LAS bf16x8*)(lds + PG8_SB(b, h) + boff + n * 2048 + k * 1024); } while (0)
; #define PG8_MMA(ai, bj, At, Bt) do { __builtin_amdgcn_s_setprio(1); _Pragma("unroll") for (int m = 0; m < 4; ++m) _Pragma("unroll") for (int n = 0; n < 2; ++n) _Pragma("unroll") for (int k = 0; k < 2; ++k) \
;         acc[ai][bj][m][n] = __builtin_amdgcn_mfma_f32_16x16x32_bf16(Bt[n][k], At[m][k], acc[ai][bj][m][n], 0, 0, 0); __builtin_amdgcn_s_setprio(0); } while (0)
; #define PG8_WAIT_V(n) asm volatile("s_waitcnt vmcnt(" #n ")" ::: "memory")
; #define PG8_WAIT_L(n) asm volatile("s_waitcnt lgkmcnt(" #n ")" ::: "memory")
; #define PG8_BAR __builtin_amdgcn_s_barrier()
; #define PG8_SCHED __builtin_amdgcn_sched_barrier(0)
; template <class Epi>
; __device__ __forceinline__ void gemm_phase(LAS unsigned char* lds, const Gemm g, const Sched& S, const Epi& E) {
;     ...
;             PG8_WAIT_V(8); PG8_WAIT_L(0); PG8_BAR; PG8_MMA(1, 0, At, B0); PG8_MMA(1, 1, At, B1); PG8_BAR; PG8_SCHED;
;             PG8_LDB(B0, 1, 0); PG8_LDB(B1, 1, 1); PG8_SCHED; PG8_LDA(At, 1, 0); PG8_STAGE(PG8_SA(0, 1), a2 + hstepA, voffA);
;             PG8_WAIT_V(8); PG8_WAIT_L(0); PG8_BAR; PG8_MMA(0, 0, At, B0); PG8_MMA(0, 1, At, B1); PG8_BAR; PG8_SCHED;
	s_waitcnt lgkmcnt(0)
	v_mfma_f32_16x16x32_bf16 v[60:63], v[140:143], v[180:183], v[60:63]
	v_mfma_f32_16x16x32_bf16 v[56:59], v[156:159], v[180:183], v[56:59]
	v_mfma_f32_16x16x32_bf16 v[52:55], v[140:143], v[188:191], v[52:55]
	v_mfma_f32_16x16x32_bf16 v[44:47], v[156:159], v[188:191], v[44:47]
	v_mfma_f32_16x16x32_bf16 v[36:39], v[140:143], v[196:199], v[36:39]
	v_mfma_f32_16x16x32_bf16 v[28:31], v[156:159], v[196:199], v[28:31]
	v_mfma_f32_16x16x32_bf16 v[20:23], v[140:143], v[208:211], v[20:23]
	v_mfma_f32_16x16x32_bf16 v[12:15], v[156:159], v[208:211], v[12:15]
	v_mfma_f32_16x16x32_bf16 v[60:63], v[152:155], v[184:187], v[60:63]
	v_mfma_f32_16x16x32_bf16 v[56:59], v[160:163], v[184:187], v[56:59]
	v_mfma_f32_16x16x32_bf16 v[52:55], v[152:155], v[192:195], v[52:55]
	v_mfma_f32_16x16x32_bf16 v[44:47], v[160:163], v[192:195], v[44:47]
	v_mfma_f32_16x16x32_bf16 v[36:39], v[152:155], v[204:207], v[36:39]
	v_mfma_f32_16x16x32_bf16 v[28:31], v[160:163], v[204:207], v[28:31]
	v_mfma_f32_16x16x32_bf16 v[20:23], v[152:155], v[212:215], v[20:23]
	v_mfma_f32_16x16x32_bf16 v[12:15], v[160:163], v[212:215], v[12:15]
	v_mfma_f32_16x16x32_bf16 v[48:51], v[164:167], v[180:183], v[48:51]
	v_mfma_f32_16x16x32_bf16 v[40:43], v[172:175], v[180:183], v[40:43]
	v_mfma_f32_16x16x32_bf16 v[32:35], v[164:167], v[188:191], v[32:35]
	v_mfma_f32_16x16x32_bf16 v[24:27], v[172:175], v[188:191], v[24:27]
	v_mfma_f32_16x16x32_bf16 v[16:19], v[164:167], v[196:199], v[16:19]
	v_mfma_f32_16x16x32_bf16 v[8:11], v[172:175], v[196:199], v[8:11]
	v_mfma_f32_16x16x32_bf16 v[4:7], v[164:167], v[208:211], v[4:7]
	v_mfma_f32_16x16x32_bf16 v[0:3], v[172:175], v[208:211], v[0:3]
	v_mfma_f32_16x16x32_bf16 v[48:51], v[168:171], v[184:187], v[48:51]
	v_mfma_f32_16x16x32_bf16 v[40:43], v[176:179], v[184:187], v[40:43]
	v_mfma_f32_16x16x32_bf16 v[32:35], v[168:171], v[192:195], v[32:35]
	v_mfma_f32_16x16x32_bf16 v[24:27], v[176:179], v[192:195], v[24:27]
	v_mfma_f32_16x16x32_bf16 v[16:19], v[168:171], v[204:207], v[16:19]
	v_mfma_f32_16x16x32_bf16 v[8:11], v[176:179], v[204:207], v[8:11]
	v_mfma_f32_16x16x32_bf16 v[4:7], v[168:171], v[212:215], v[4:7]
	v_mfma_f32_16x16x32_bf16 v[0:3], v[176:179], v[212:215], v[0:3]
	s_barrier
	s_add_i32 s55, 0, 0x18000
	v_add_u32_e32 v151, s55, v146
	s_add_i32 s56, 0, 0x1c000
	ds_read_b128 v[140:143], v151
	ds_read_b128 v[152:155], v151 offset:1024
	ds_read_b128 v[156:159], v151 offset:2048
	ds_read_b128 v[160:163], v151 offset:3072
	v_add_u32_e32 v151, s56, v146
	ds_read_b128 v[164:167], v151
	ds_read_b128 v[168:171], v151 offset:1024
	ds_read_b128 v[172:175], v151 offset:2048
	ds_read_b128 v[176:179], v151 offset:3072
	s_add_u32 s42, s42, 0x40000
	s_addc_u32 s43, s43, 0
	s_mov_b32 m0, s19
	v_lshl_add_u64 v[222:223], s[42:43], 0, v[128:129]
	ds_read_b128 v[180:183], v150 offset:32768
	ds_read_b128 v[184:187], v150 offset:33792
	ds_read_b128 v[188:191], v150 offset:34816
	ds_read_b128 v[192:195], v150 offset:35840
	ds_read_b128 v[196:199], v150 offset:36864
	ds_read_b128 v[204:207], v150 offset:37888
	ds_read_b128 v[208:211], v150 offset:38912
	ds_read_b128 v[212:215], v150 offset:39936
	global_load_lds_dwordx4 v[222:223], off
	v_lshl_add_u64 v[222:223], s[42:43], 0, v[132:133]
	s_mov_b32 m0, s37
	s_nop 0
	global_load_lds_dwordx4 v[222:223], off
	s_waitcnt vmcnt(8)
	s_waitcnt lgkmcnt(0)
	s_barrier
	s_waitcnt lgkmcnt(0)
	v_mfma_f32_16x16x32_bf16 v[124:127], v[140:143], v[180:183], v[124:127]
	v_mfma_f32_16x16x32_bf16 v[120:123], v[156:159], v[180:183], v[120:123]
	v_mfma_f32_16x16x32_bf16 v[116:119], v[140:143], v[188:191], v[116:119]
	v_mfma_f32_16x16x32_bf16 v[108:111], v[156:159], v[188:191], v[108:111]
	v_mfma_f32_16x16x32_bf16 v[100:103], v[140:143], v[196:199], v[100:103]
	v_mfma_f32_16x16x32_bf16 v[92:95], v[156:159], v[196:199], v[92:95]
	v_mfma_f32_16x16x32_bf16 v[84:87], v[140:143], v[208:211], v[84:87]
	v_mfma_f32_16x16x32_bf16 v[76:79], v[156:159], v[208:211], v[76:79]
	v_mfma_f32_16x16x32_bf16 v[124:127], v[152:155], v[184:187], v[124:127]
	v_mfma_f32_16x16x32_bf16 v[120:123], v[160:163], v[184:187], v[120:123]
	v_mfma_f32_16x16x32_bf16 v[116:119], v[152:155], v[192:195], v[116:119]
	v_mfma_f32_16x16x32_bf16 v[108:111], v[160:163], v[192:195], v[108:111]
	v_mfma_f32_16x16x32_bf16 v[100:103], v[152:155], v[204:207], v[100:103]
	v_mfma_f32_16x16x32_bf16 v[92:95], v[160:163], v[204:207], v[92:95]
	v_mfma_f32_16x16x32_bf16 v[84:87], v[152:155], v[212:215], v[84:87]
	v_mfma_f32_16x16x32_bf16 v[76:79], v[160:163], v[212:215], v[76:79]
	v_mfma_f32_16x16x32_bf16 v[112:115], v[164:167], v[180:183], v[112:115]
	v_mfma_f32_16x16x32_bf16 v[104:107], v[172:175], v[180:183], v[104:107]
	v_mfma_f32_16x16x32_bf16 v[96:99], v[164:167], v[188:191], v[96:99]
	v_mfma_f32_16x16x32_bf16 v[88:91], v[172:175], v[188:191], v[88:91]
	v_mfma_f32_16x16x32_bf16 v[80:83], v[164:167], v[196:199], v[80:83]
	v_mfma_f32_16x16x32_bf16 v[72:75], v[172:175], v[196:199], v[72:75]
	v_mfma_f32_16x16x32_bf16 v[68:71], v[164:167], v[208:211], v[68:71]
	v_mfma_f32_16x16x32_bf16 v[64:67], v[172:175], v[208:211], v[64:67]
	v_mfma_f32_16x16x32_bf16 v[112:115], v[168:171], v[184:187], v[112:115]
	v_mfma_f32_16x16x32_bf16 v[104:107], v[176:179], v[184:187], v[104:107]
	v_mfma_f32_16x16x32_bf16 v[96:99], v[168:171], v[192:195], v[96:99]
	v_mfma_f32_16x16x32_bf16 v[88:91], v[176:179], v[192:195], v[88:91]
	v_mfma_f32_16x16x32_bf16 v[80:83], v[168:171], v[204:207], v[80:83]
	v_mfma_f32_16x16x32_bf16 v[72:75], v[176:179], v[204:207], v[72:75]
	v_mfma_f32_16x16x32_bf16 v[68:71], v[168:171], v[212:215], v[68:71]
	v_mfma_f32_16x16x32_bf16 v[64:67], v[176:179], v[212:215], v[64:67]
	s_barrier
; #define PG8_STAGE(bufoff, gbase, voff) do { _Pragma("unroll") for (int _i = 0; _i < 2; ++_i) \
;         __builtin_amdgcn_global_load_lds((const unsigned*)((const char*)(gbase) + (voff)[_i]), (LAS unsigned*)(lds + (bufoff) + ldsw + _i * 8192), 16, 0, 0); } while (0)
; #define PG8_LDA(dst, b, h) do { _Pragma("unroll") for (int m = 0; m < 4; ++m) _Pragma("unroll") for (int k = 0; k < 2; ++k) dst[m][k] = *(const LAS bf16x8*)(lds + PG8_SA(b, h) + aoff + m * 2048 + k * 1024); } while (0)
; #define PG8_MMA(ai, bj, At, Bt) do { __builtin_amdgcn_s_setprio(1); _Pragma("unroll") for (int m = 0; m < 4; ++m) _Pragma("unroll") for (int n = 0; n < 2; ++n) _Pragma("unroll") for (int k = 0; k < 2; ++k) \
;         acc[ai][bj][m][n] = __builtin_amdgcn_mfma_f32_16x16x32_bf16(Bt[n][k], At[m][k], acc[ai][bj][m][n], 0, 0, 0); __builtin_amdgcn_s_setprio(0); } while (0)
; #define PG8_WAIT_V(n) asm volatile("s_waitcnt vmcnt(" #n ")" ::: "memory")
; #define PG8_WAIT_L(n) asm volatile("s_waitcnt lgkmcnt(" #n ")" ::: "memory")
; #define PG8_BAR __builtin_amdgcn_s_barrier()
; #define PG8_SCHED __builtin_amdgcn_sched_barrier(0)
; template <class Epi>
; __device__ __forceinline__ void gemm_phase(LAS unsigned char* lds, const Gemm g, const Sched& S, const Epi& E) {
;     ...
;             PG8_LDA(At, 1, 1); PG8_STAGE(PG8_SB(1, 0), b3, voffB); PG8_STAGE(PG8_SB(1, 1), b3 + hstepB, voffB); PG8_STAGE(PG8_SA(1, 0), a3, voffA);
;             PG8_WAIT_V(8); PG8_WAIT_L(0); PG8_BAR; PG8_MMA(1, 0, At, B0); PG8_MMA(1, 1, At, B1); PG8_BAR; PG8_SCHED;
;         }
;         if (wr == 0) PG8_BAR;
	s_add_i32 s42, s55, s10
	v_lshl_add_u64 v[200:201], v[200:201], 0, s[14:15]
	s_mov_b32 m0, s42
	ds_read_b128 v[180:183], v150 offset:49152
	ds_read_b128 v[184:187], v150 offset:50176
	ds_read_b128 v[188:191], v150 offset:51200
	ds_read_b128 v[192:195], v150 offset:52224
	ds_read_b128 v[196:199], v150 offset:53248
	ds_read_b128 v[204:207], v150 offset:54272
	ds_read_b128 v[208:211], v150 offset:55296
	ds_read_b128 v[212:215], v150 offset:56320
	global_load_lds_dwordx4 v[200:201], off
	s_add_i32 m0, s42, 0x2000
	s_add_u32 s40, s40, 0x40080
	v_lshl_add_u64 v[200:201], v[216:217], 0, s[14:15]
	s_addc_u32 s41, s41, 0
	s_add_i32 s42, s56, s10
	global_load_lds_dwordx4 v[200:201], off
	v_lshl_add_u64 v[200:201], s[40:41], 0, v[130:131]
	s_mov_b32 m0, s42
	s_nop 0
	global_load_lds_dwordx4 v[200:201], off
	v_lshl_add_u64 v[200:201], s[40:41], 0, v[134:135]
	s_add_i32 m0, s42, 0x2000
	s_nop 0
	global_load_lds_dwordx4 v[200:201], off
	v_lshl_add_u64 v[200:201], v[218:219], 0, s[14:15]
	s_mov_b32 m0, s45
	s_nop 0
	global_load_lds_dwordx4 v[200:201], off
	v_lshl_add_u64 v[200:201], v[220:221], 0, s[14:15]
	s_mov_b32 m0, s46
	s_nop 0
	global_load_lds_dwordx4 v[200:201], off
	s_waitcnt vmcnt(8)
	s_waitcnt lgkmcnt(0)
	s_barrier
	s_waitcnt lgkmcnt(0)
	v_mfma_f32_16x16x32_bf16 v[60:63], v[140:143], v[180:183], v[60:63]
	v_mfma_f32_16x16x32_bf16 v[56:59], v[156:159], v[180:183], v[56:59]
	v_mfma_f32_16x16x32_bf16 v[52:55], v[140:143], v[188:191], v[52:55]
	v_mfma_f32_16x16x32_bf16 v[44:47], v[156:159], v[188:191], v[44:47]
	v_mfma_f32_16x16x32_bf16 v[36:39], v[140:143], v[196:199], v[36:39]
	v_mfma_f32_16x16x32_bf16 v[28:31], v[156:159], v[196:199], v[28:31]
	v_mfma_f32_16x16x32_bf16 v[20:23], v[140:143], v[208:211], v[20:23]
	v_mfma_f32_16x16x32_bf16 v[12:15], v[156:159], v[208:211], v[12:15]
	v_mfma_f32_16x16x32_bf16 v[60:63], v[152:155], v[184:187], v[60:63]
	v_mfma_f32_16x16x32_bf16 v[56:59], v[160:163], v[184:187], v[56:59]
	v_mfma_f32_16x16x32_bf16 v[52:55], v[152:155], v[192:195], v[52:55]
	v_mfma_f32_16x16x32_bf16 v[44:47], v[160:163], v[192:195], v[44:47]
	v_mfma_f32_16x16x32_bf16 v[36:39], v[152:155], v[204:207], v[36:39]
	v_mfma_f32_16x16x32_bf16 v[28:31], v[160:163], v[204:207], v[28:31]
	v_mfma_f32_16x16x32_bf16 v[20:23], v[152:155], v[212:215], v[20:23]
	v_mfma_f32_16x16x32_bf16 v[12:15], v[160:163], v[212:215], v[12:15]
	v_mfma_f32_16x16x32_bf16 v[48:51], v[164:167], v[180:183], v[48:51]
	v_mfma_f32_16x16x32_bf16 v[40:43], v[172:175], v[180:183], v[40:43]
	v_mfma_f32_16x16x32_bf16 v[32:35], v[164:167], v[188:191], v[32:35]
	v_mfma_f32_16x16x32_bf16 v[24:27], v[172:175], v[188:191], v[24:27]
	v_mfma_f32_16x16x32_bf16 v[16:19], v[164:167], v[196:199], v[16:19]
	v_mfma_f32_16x16x32_bf16 v[8:11], v[172:175], v[196:199], v[8:11]
	v_mfma_f32_16x16x32_bf16 v[4:7], v[164:167], v[208:211], v[4:7]
	v_mfma_f32_16x16x32_bf16 v[0:3], v[172:175], v[208:211], v[0:3]
	v_mfma_f32_16x16x32_bf16 v[48:51], v[168:171], v[184:187], v[48:51]
	v_mfma_f32_16x16x32_bf16 v[40:43], v[176:179], v[184:187], v[40:43]
	v_mfma_f32_16x16x32_bf16 v[32:35], v[168:171], v[192:195], v[32:35]
	v_mfma_f32_16x16x32_bf16 v[24:27], v[176:179], v[192:195], v[24:27]
	v_mfma_f32_16x16x32_bf16 v[16:19], v[168:171], v[204:207], v[16:19]
	v_mfma_f32_16x16x32_bf16 v[8:11], v[176:179], v[204:207], v[8:11]
	v_mfma_f32_16x16x32_bf16 v[4:7], v[168:171], v[212:215], v[4:7]
	v_mfma_f32_16x16x32_bf16 v[0:3], v[176:179], v[212:215], v[0:3]
	s_barrier
	s_add_i32 s54, s54, 2
	s_add_u32 s38, s38, 0x100
	s_addc_u32 s39, s39, 0
	s_add_u32 s52, s52, 0x100
	s_addc_u32 s53, s53, 0
	s_cmp_gt_u32 s54, 13
	s_cbranch_scc0 .LBB0_1355
	s_and_b64 vcc, exec, s[16:17]
	s_cbranch_vccz .LBB0_1358
	s_barrier

; #define PG8_STAGE(bufoff, gbase, voff) do { _Pragma("unroll") for (int _i = 0; _i < 2; ++_i) \
;         __builtin_amdgcn_global_load_lds((const unsigned*)((const char*)(gbase) + (voff)[_i]), (LAS unsigned*)(lds + (bufoff) + ldsw + _i * 8192), 16, 0, 0); } while (0)
; #define PG8_LDA(dst, b, h) do { _Pragma("unroll") for (int m = 0; m < 4; ++m) _Pragma("unroll") for (int k = 0; k < 2; ++k) dst[m][k] = *(const LAS bf16x8*)(lds + PG8_SA(b, h) + aoff + m * 2048 + k * 1024); } while (0)
; #define PG8_LDB(dst, b, h) do { _Pragma("unroll") for (int n = 0; n < 2; ++n) _Pragma("unroll") for (int k = 0; k < 2; ++k) dst[n][k] = *(const LAS bf16x8*)(lds + PG8_SB(b, h) + boff + n * 2048 + k * 1024); } while (0)
; #define PG8_MMA(ai, bj, At, Bt) do { __builtin_amdgcn_s_setprio(1); _Pragma("unroll") for (int m = 0; m < 4; ++m) _Pragma("unroll") for (int n = 0; n < 2; ++n) _Pragma("unroll") for (int k = 0; k < 2; ++k) \
;         acc[ai][bj][m][n] = __builtin_amdgcn_mfma_f32_16x16x32_bf16(Bt[n][k], At[m][k], acc[ai][bj][m][n], 0, 0, 0); __builtin_amdgcn_s_setprio(0); } while (0)
; #define PG8_WAIT_V(n) asm volatile("s_waitcnt vmcnt(" #n ")" ::: "memory")
; #define PG8_WAIT_L(n) asm volatile("s_waitcnt lgkmcnt(" #n ")" ::: "memory")
; #define PG8_BAR __builtin_amdgcn_s_barrier()
; #define PG8_SCHED __builtin_amdgcn_sched_barrier(0)
; template <class Epi>
; __device__ __forceinline__ void gemm_phase(LAS unsigned char* lds, const Gemm g, const Sched& S, const Epi& E) {
;     ...
;         for (int t = 0; t < nt; t += 2) {
;             const bool last = (t == nt - 2);
;             const char* a1 = cA + (size_t)(t + 1) * kstep;
;             const char* a2 = last ? nA : cA + (size_t)(t + 2) * kstep; const char* b2 = last ? nB : cB + (size_t)(t + 2) * kstep;
;             const char* a3 = a2 + kstep; const char* b3 = b2 + kstep;
;             PG8_LDB(B0, 0, 0); PG8_LDB(B1, 0, 1); PG8_SCHED; PG8_LDA(At, 0, 0); PG8_STAGE(PG8_SA(1, 1), a1 + hstepA, voffA);
;             PG8_WAIT_V(8); PG8_WAIT_L(0); PG8_BAR; PG8_MMA(0, 0, At, B0); PG8_MMA(0, 1, At, B1); PG8_BAR; PG8_SCHED;
;             PG8_LDA(At, 0, 1); PG8_STAGE(PG8_SB(0, 0), b2, voffB); PG8_STAGE(PG8_SB(0, 1), b2 + hstepB, voffB); PG8_STAGE(PG8_SA(0, 0), a2, voffA);
.LBB0_1381:
	s_add_u32 s52, s18, s46
	s_addc_u32 s53, s19, s47
	s_add_u32 s50, s52, 0x100
	s_addc_u32 s51, s53, 0
	s_and_b64 s[48:49], s[44:45], exec
	s_cselect_b32 s49, s29, s51
	s_cselect_b32 s48, s70, s50
	s_add_u32 s46, s20, s46
	s_addc_u32 s47, s21, s47
	s_add_u32 s46, s46, 0x100
	s_addc_u32 s47, s47, 0
	s_and_b64 s[44:45], s[44:45], exec
	s_cselect_b32 s51, s39, s47
	s_cselect_b32 s50, s38, s46
	s_add_u32 s54, s52, 0x40080
	s_addc_u32 s55, s53, 0
	s_add_i32 s78, s66, s57
	s_add_i32 m0, s17, 0xc000
	s_add_i32 s81, s17, 0xe000
	s_add_i32 s75, s78, 0x2000
	v_add_u32_e32 v142, s66, v140
	s_add_u32 s52, s50, 0x40000
	ds_read_b128 v[146:149], v142
	ds_read_b128 v[150:153], v142 offset:1024
	ds_read_b128 v[154:157], v142 offset:2048
	ds_read_b128 v[158:161], v142 offset:3072
	v_add_u32_e32 v142, s67, v140
	s_addc_u32 s53, s51, 0
	s_add_i32 s77, s67, s57
	ds_read_b128 v[162:165], v142
	ds_read_b128 v[166:169], v142 offset:1024
	ds_read_b128 v[170:173], v142 offset:2048
	ds_read_b128 v[174:177], v142 offset:3072
	s_add_i32 s76, s77, 0x2000
	s_add_i32 s74, 0, 0x18000
	s_add_i32 s73, 0, 0x1c000
	s_add_u32 s46, s48, 0x40000
	s_addc_u32 s47, s49, 0
	s_add_i32 s72, s74, s57
	s_add_i32 s71, s72, 0x2000
	s_add_u32 s44, s50, 0x40080
	s_addc_u32 s45, s51, 0
	s_add_i32 s80, s73, s57
	s_add_i32 s79, s80, 0x2000
	v_lshl_add_u64 v[142:143], s[54:55], 0, v[128:129]
	ds_read_b128 v[178:181], v141
	ds_read_b128 v[182:185], v141 offset:1024
	ds_read_b128 v[186:189], v141 offset:2048
	ds_read_b128 v[190:193], v141 offset:3072
	ds_read_b128 v[194:197], v141 offset:4096
	ds_read_b128 v[198:201], v141 offset:5120
	ds_read_b128 v[204:207], v141 offset:6144
	ds_read_b128 v[208:211], v141 offset:7168
	global_load_lds_dwordx4 v[142:143], off
	v_lshl_add_u64 v[142:143], s[54:55], 0, v[132:133]
	s_mov_b32 m0, s81
	s_nop 0
	global_load_lds_dwordx4 v[142:143], off
	s_waitcnt vmcnt(8)
	s_waitcnt lgkmcnt(0)
	s_barrier
	s_waitcnt lgkmcnt(0)
	v_mfma_f32_16x16x32_bf16 v[124:127], v[146:149], v[178:181], v[124:127]
	v_mfma_f32_16x16x32_bf16 v[120:123], v[154:157], v[178:181], v[120:123]
	v_mfma_f32_16x16x32_bf16 v[112:115], v[146:149], v[186:189], v[112:115]
	v_mfma_f32_16x16x32_bf16 v[108:111], v[154:157], v[186:189], v[108:111]
	v_mfma_f32_16x16x32_bf16 v[100:103], v[146:149], v[194:197], v[100:103]
	v_mfma_f32_16x16x32_bf16 v[92:95], v[154:157], v[194:197], v[92:95]
	v_mfma_f32_16x16x32_bf16 v[84:87], v[146:149], v[204:207], v[84:87]
	v_mfma_f32_16x16x32_bf16 v[76:79], v[154:157], v[204:207], v[76:79]
	v_mfma_f32_16x16x32_bf16 v[124:127], v[150:153], v[182:185], v[124:127]
	v_mfma_f32_16x16x32_bf16 v[120:123], v[158:161], v[182:185], v[120:123]
	v_mfma_f32_16x16x32_bf16 v[112:115], v[150:153], v[190:193], v[112:115]
	v_mfma_f32_16x16x32_bf16 v[108:111], v[158:161], v[190:193], v[108:111]
	v_mfma_f32_16x16x32_bf16 v[100:103], v[150:153], v[198:201], v[100:103]
	v_mfma_f32_16x16x32_bf16 v[92:95], v[158:161], v[198:201], v[92:95]
	v_mfma_f32_16x16x32_bf16 v[84:87], v[150:153], v[208:211], v[84:87]
	v_mfma_f32_16x16x32_bf16 v[76:79], v[158:161], v[208:211], v[76:79]
	v_mfma_f32_16x16x32_bf16 v[116:119], v[162:165], v[178:181], v[116:119]
	v_mfma_f32_16x16x32_bf16 v[104:107], v[170:173], v[178:181], v[104:107]
	v_mfma_f32_16x16x32_bf16 v[96:99], v[162:165], v[186:189], v[96:99]
	v_mfma_f32_16x16x32_bf16 v[88:91], v[170:173], v[186:189], v[88:91]
	v_mfma_f32_16x16x32_bf16 v[80:83], v[162:165], v[194:197], v[80:83]
	v_mfma_f32_16x16x32_bf16 v[72:75], v[170:173], v[194:197], v[72:75]
	v_mfma_f32_16x16x32_bf16 v[68:71], v[162:165], v[204:207], v[68:71]
	v_mfma_f32_16x16x32_bf16 v[64:67], v[170:173], v[204:207], v[64:67]
	v_mfma_f32_16x16x32_bf16 v[116:119], v[166:169], v[182:185], v[116:119]
	v_mfma_f32_16x16x32_bf16 v[104:107], v[174:177], v[182:185], v[104:107]
	v_mfma_f32_16x16x32_bf16 v[96:99], v[166:169], v[190:193], v[96:99]
	v_mfma_f32_16x16x32_bf16 v[88:91], v[174:177], v[190:193], v[88:91]
	v_mfma_f32_16x16x32_bf16 v[80:83], v[166:169], v[198:201], v[80:83]
	v_mfma_f32_16x16x32_bf16 v[72:75], v[174:177], v[198:201], v[72:75]
	v_mfma_f32_16x16x32_bf16 v[68:71], v[166:169], v[208:211], v[68:71]
	v_mfma_f32_16x16x32_bf16 v[64:67], v[174:177], v[208:211], v[64:67]
	s_barrier
	s_mov_b32 m0, s78
	v_lshl_add_u64 v[142:143], s[50:51], 0, v[130:131]
	ds_read_b128 v[178:181], v141 offset:16384
	ds_read_b128 v[182:185], v141 offset:17408
	ds_read_b128 v[186:189], v141 offset:18432
	ds_read_b128 v[190:193], v141 offset:19456
	ds_read_b128 v[194:197], v141 offset:20480
	ds_read_b128 v[198:201], v141 offset:21504
	ds_read_b128 v[204:207], v141 offset:22528
	ds_read_b128 v[208:211], v141 offset:23552
	global_load_lds_dwordx4 v[142:143], off
	v_lshl_add_u64 v[212:213], s[50:51], 0, v[134:135]
	s_mov_b32 m0, s75
	v_lshl_add_u64 v[214:215], s[52:53], 0, v[130:131]
	global_load_lds_dwordx4 v[212:213], off
	s_mov_b32 m0, s77
	v_lshl_add_u64 v[216:217], s[48:49], 0, v[132:133]
	global_load_lds_dwordx4 v[214:215], off
	v_lshl_add_u64 v[214:215], s[52:53], 0, v[134:135]
	s_mov_b32 m0, s76
	s_nop 0
	global_load_lds_dwordx4 v[214:215], off
	v_lshl_add_u64 v[214:215], s[48:49], 0, v[128:129]
	s_mov_b32 m0, s17
	s_nop 0
	global_load_lds_dwordx4 v[214:215], off
	s_mov_b32 m0, s60
	s_nop 0
	global_load_lds_dwordx4 v[216:217], off
	s_waitcnt vmcnt(8)
	s_waitcnt lgkmcnt(0)
	s_barrier
; #define PG8_STAGE(bufoff, gbase, voff) do { _Pragma("unroll") for (int _i = 0; _i < 2; ++_i) \
;         __builtin_amdgcn_global_load_lds((const unsigned*)((const char*)(gbase) + (voff)[_i]), (LAS unsigned*)(lds + (bufoff) + ldsw + _i * 8192), 16, 0, 0); } while (0)
; #define PG8_LDA(dst, b, h) do { _Pragma("unroll") for (int m = 0; m < 4; ++m) _Pragma("unroll") for (int k = 0; k < 2; ++k) dst[m][k] = *(const LAS bf16x8*)(lds + PG8_SA(b, h) + aoff + m * 2048 + k * 1024); } while (0)
; #define PG8_LDB(dst, b, h) do { _Pragma("unroll") for (int n = 0; n < 2; ++n) _Pragma("unroll") for (int k = 0; k < 2; ++k) dst[n][k] = *(const LAS bf16x8*)(lds + PG8_SB(b, h) + boff + n * 2048 + k * 1024); } while (0)
; #define PG8_MMA(ai, bj, At, Bt) do { __builtin_amdgcn_s_setprio(1); _Pragma("unroll") for (int m = 0; m < 4; ++m) _Pragma("unroll") for (int n = 0; n < 2; ++n) _Pragma("unroll") for (int k = 0; k < 2; ++k) \
;         acc[ai][bj][m][n] = __builtin_amdgcn_mfma_f32_16x16x32_bf16(Bt[n][k], At[m][k], acc[ai][bj][m][n], 0, 0, 0); __builtin_amdgcn_s_setprio(0); } while (0)
; #define PG8_WAIT_V(n) asm volatile("s_waitcnt vmcnt(" #n ")" ::: "memory")
; #define PG8_WAIT_L(n) asm volatile("s_waitcnt lgkmcnt(" #n ")" ::: "memory")
; #define PG8_BAR __builtin_amdgcn_s_barrier()
; #define PG8_SCHED __builtin_amdgcn_sched_barrier(0)
; template <class Epi>
; __device__ __forceinline__ void gemm_phase(LAS unsigned char* lds, const Gemm g, const Sched& S, const Epi& E) {
;     ...
;             PG8_WAIT_V(8); PG8_WAIT_L(0); PG8_BAR; PG8_MMA(1, 0, At, B0); PG8_MMA(1, 1, At, B1); PG8_BAR; PG8_SCHED;
;             PG8_LDB(B0, 1, 0); PG8_LDB(B1, 1, 1); PG8_SCHED; PG8_LDA(At, 1, 0); PG8_STAGE(PG8_SA(0, 1), a2 + hstepA, voffA);
;             PG8_WAIT_V(8); PG8_WAIT_L(0); PG8_BAR; PG8_MMA(0, 0, At, B0); PG8_MMA(0, 1, At, B1); PG8_BAR; PG8_SCHED;
	s_waitcnt lgkmcnt(0)
	v_mfma_f32_16x16x32_bf16 v[60:63], v[146:149], v[178:181], v[60:63]
	v_mfma_f32_16x16x32_bf16 v[56:59], v[154:157], v[178:181], v[56:59]
	v_mfma_f32_16x16x32_bf16 v[52:55], v[146:149], v[186:189], v[52:55]
	v_mfma_f32_16x16x32_bf16 v[44:47], v[154:157], v[186:189], v[44:47]
	v_mfma_f32_16x16x32_bf16 v[36:39], v[146:149], v[194:197], v[36:39]
	v_mfma_f32_16x16x32_bf16 v[28:31], v[154:157], v[194:197], v[28:31]
	v_mfma_f32_16x16x32_bf16 v[20:23], v[146:149], v[204:207], v[20:23]
	v_mfma_f32_16x16x32_bf16 v[12:15], v[154:157], v[204:207], v[12:15]
	v_mfma_f32_16x16x32_bf16 v[60:63], v[150:153], v[182:185], v[60:63]
	v_mfma_f32_16x16x32_bf16 v[56:59], v[158:161], v[182:185], v[56:59]
	v_mfma_f32_16x16x32_bf16 v[52:55], v[150:153], v[190:193], v[52:55]
	v_mfma_f32_16x16x32_bf16 v[44:47], v[158:161], v[190:193], v[44:47]
	v_mfma_f32_16x16x32_bf16 v[36:39], v[150:153], v[198:201], v[36:39]
	v_mfma_f32_16x16x32_bf16 v[28:31], v[158:161], v[198:201], v[28:31]
	v_mfma_f32_16x16x32_bf16 v[20:23], v[150:153], v[208:211], v[20:23]
	v_mfma_f32_16x16x32_bf16 v[12:15], v[158:161], v[208:211], v[12:15]
	v_mfma_f32_16x16x32_bf16 v[48:51], v[162:165], v[178:181], v[48:51]
	v_mfma_f32_16x16x32_bf16 v[40:43], v[170:173], v[178:181], v[40:43]
	v_mfma_f32_16x16x32_bf16 v[32:35], v[162:165], v[186:189], v[32:35]
	v_mfma_f32_16x16x32_bf16 v[24:27], v[170:173], v[186:189], v[24:27]
	v_mfma_f32_16x16x32_bf16 v[16:19], v[162:165], v[194:197], v[16:19]
	v_mfma_f32_16x16x32_bf16 v[8:11], v[170:173], v[194:197], v[8:11]
	v_mfma_f32_16x16x32_bf16 v[4:7], v[162:165], v[204:207], v[4:7]
	v_mfma_f32_16x16x32_bf16 v[0:3], v[170:173], v[204:207], v[0:3]
	v_mfma_f32_16x16x32_bf16 v[48:51], v[166:169], v[182:185], v[48:51]
	v_mfma_f32_16x16x32_bf16 v[40:43], v[174:177], v[182:185], v[40:43]
	v_mfma_f32_16x16x32_bf16 v[32:35], v[166:169], v[190:193], v[32:35]
	v_mfma_f32_16x16x32_bf16 v[24:27], v[174:177], v[190:193], v[24:27]
	v_mfma_f32_16x16x32_bf16 v[16:19], v[166:169], v[198:201], v[16:19]
	v_mfma_f32_16x16x32_bf16 v[8:11], v[174:177], v[198:201], v[8:11]
	v_mfma_f32_16x16x32_bf16 v[4:7], v[166:169], v[208:211], v[4:7]
	v_mfma_f32_16x16x32_bf16 v[0:3], v[174:177], v[208:211], v[0:3]
	s_barrier
	v_add_u32_e32 v145, s74, v140
	ds_read_b128 v[146:149], v145
	ds_read_b128 v[150:153], v145 offset:1024
	ds_read_b128 v[154:157], v145 offset:2048
	ds_read_b128 v[158:161], v145 offset:3072
	v_add_u32_e32 v145, s73, v140
	ds_read_b128 v[162:165], v145
	ds_read_b128 v[166:169], v145 offset:1024
	ds_read_b128 v[170:173], v145 offset:2048
	ds_read_b128 v[174:177], v145 offset:3072
	s_mov_b32 m0, s61
	v_lshl_add_u64 v[218:219], s[46:47], 0, v[128:129]
	ds_read_b128 v[178:181], v141 offset:32768
	ds_read_b128 v[182:185], v141 offset:33792
	ds_read_b128 v[186:189], v141 offset:34816
	ds_read_b128 v[190:193], v141 offset:35840
	ds_read_b128 v[194:197], v141 offset:36864
	ds_read_b128 v[198:201], v141 offset:37888
	ds_read_b128 v[204:207], v141 offset:38912
	ds_read_b128 v[208:211], v141 offset:39936
	global_load_lds_dwordx4 v[218:219], off
	v_lshl_add_u64 v[218:219], s[46:47], 0, v[132:133]
	s_mov_b32 m0, s62
	s_nop 0
	global_load_lds_dwordx4 v[218:219], off
	s_waitcnt vmcnt(8)
	s_waitcnt lgkmcnt(0)
	s_barrier
	s_waitcnt lgkmcnt(0)
	v_mfma_f32_16x16x32_bf16 v[124:127], v[146:149], v[178:181], v[124:127]
	v_mfma_f32_16x16x32_bf16 v[120:123], v[154:157], v[178:181], v[120:123]
	v_mfma_f32_16x16x32_bf16 v[112:115], v[146:149], v[186:189], v[112:115]
	v_mfma_f32_16x16x32_bf16 v[108:111], v[154:157], v[186:189], v[108:111]
	v_mfma_f32_16x16x32_bf16 v[100:103], v[146:149], v[194:197], v[100:103]
	v_mfma_f32_16x16x32_bf16 v[92:95], v[154:157], v[194:197], v[92:95]
	v_mfma_f32_16x16x32_bf16 v[84:87], v[146:149], v[204:207], v[84:87]
	v_mfma_f32_16x16x32_bf16 v[76:79], v[154:157], v[204:207], v[76:79]
	v_mfma_f32_16x16x32_bf16 v[124:127], v[150:153], v[182:185], v[124:127]
	v_mfma_f32_16x16x32_bf16 v[120:123], v[158:161], v[182:185], v[120:123]
	v_mfma_f32_16x16x32_bf16 v[112:115], v[150:153], v[190:193], v[112:115]
	v_mfma_f32_16x16x32_bf16 v[108:111], v[158:161], v[190:193], v[108:111]
	v_mfma_f32_16x16x32_bf16 v[100:103], v[150:153], v[198:201], v[100:103]
	v_mfma_f32_16x16x32_bf16 v[92:95], v[158:161], v[198:201], v[92:95]
	v_mfma_f32_16x16x32_bf16 v[84:87], v[150:153], v[208:211], v[84:87]
	v_mfma_f32_16x16x32_bf16 v[76:79], v[158:161], v[208:211], v[76:79]
	v_mfma_f32_16x16x32_bf16 v[116:119], v[162:165], v[178:181], v[116:119]
	v_mfma_f32_16x16x32_bf16 v[104:107], v[170:173], v[178:181], v[104:107]
	v_mfma_f32_16x16x32_bf16 v[96:99], v[162:165], v[186:189], v[96:99]
	v_mfma_f32_16x16x32_bf16 v[88:91], v[170:173], v[186:189], v[88:91]
	v_mfma_f32_16x16x32_bf16 v[80:83], v[162:165], v[194:197], v[80:83]
	v_mfma_f32_16x16x32_bf16 v[72:75], v[170:173], v[194:197], v[72:75]
	v_mfma_f32_16x16x32_bf16 v[68:71], v[162:165], v[204:207], v[68:71]
	v_mfma_f32_16x16x32_bf16 v[64:67], v[170:173], v[204:207], v[64:67]
	v_mfma_f32_16x16x32_bf16 v[116:119], v[166:169], v[182:185], v[116:119]
	v_mfma_f32_16x16x32_bf16 v[104:107], v[174:177], v[182:185], v[104:107]
	v_mfma_f32_16x16x32_bf16 v[96:99], v[166:169], v[190:193], v[96:99]
	v_mfma_f32_16x16x32_bf16 v[88:91], v[174:177], v[190:193], v[88:91]
	v_mfma_f32_16x16x32_bf16 v[80:83], v[166:169], v[198:201], v[80:83]
	v_mfma_f32_16x16x32_bf16 v[72:75], v[174:177], v[198:201], v[72:75]
	v_mfma_f32_16x16x32_bf16 v[68:71], v[166:169], v[208:211], v[68:71]
	v_mfma_f32_16x16x32_bf16 v[64:67], v[174:177], v[208:211], v[64:67]
	s_barrier
; #define PG8_STAGE(bufoff, gbase, voff) do { _Pragma("unroll") for (int _i = 0; _i < 2; ++_i) \
;         __builtin_amdgcn_global_load_lds((const unsigned*)((const char*)(gbase) + (voff)[_i]), (LAS unsigned*)(lds + (bufoff) + ldsw + _i * 8192), 16, 0, 0); } while (0)
; #define PG8_LDA(dst, b, h) do { _Pragma("unroll") for (int m = 0; m < 4; ++m) _Pragma("unroll") for (int k = 0; k < 2; ++k) dst[m][k] = *(const LAS bf16x8*)(lds + PG8_SA(b, h) + aoff + m * 2048 + k * 1024); } while (0)
; #define PG8_MMA(ai, bj, At, Bt) do { __builtin_amdgcn_s_setprio(1); _Pragma("unroll") for (int m = 0; m < 4; ++m) _Pragma("unroll") for (int n = 0; n < 2; ++n) _Pragma("unroll") for (int k = 0; k < 2; ++k) \
;         acc[ai][bj][m][n] = __builtin_amdgcn_mfma_f32_16x16x32_bf16(Bt[n][k], At[m][k], acc[ai][bj][m][n], 0, 0, 0); __builtin_amdgcn_s_setprio(0); } while (0)
; #define PG8_WAIT_V(n) asm volatile("s_waitcnt vmcnt(" #n ")" ::: "memory")
; #define PG8_WAIT_L(n) asm volatile("s_waitcnt lgkmcnt(" #n ")" ::: "memory")
; #define PG8_BAR __builtin_amdgcn_s_barrier()
; #define PG8_SCHED __builtin_amdgcn_sched_barrier(0)
; template <class Epi>
; __device__ __forceinline__ void gemm_phase(LAS unsigned char* lds, const Gemm g, const Sched& S, const Epi& E) {
;     ...
;             PG8_LDA(At, 1, 1); PG8_STAGE(PG8_SB(1, 0), b3, voffB); PG8_STAGE(PG8_SB(1, 1), b3 + hstepB, voffB); PG8_STAGE(PG8_SA(1, 0), a3, voffA);
;             PG8_WAIT_V(8); PG8_WAIT_L(0); PG8_BAR; PG8_MMA(1, 0, At, B0); PG8_MMA(1, 1, At, B1); PG8_BAR; PG8_SCHED;
;         }
;         if (wr == 0) PG8_BAR;
;         if constexpr (!Epi::AFTER_DRAIN) { E(acc, cur, wr, wc, fr, fq); }
;         if (!has_next) break;
	s_mov_b32 m0, s72
	v_lshl_add_u64 v[142:143], v[142:143], 0, s[24:25]
	ds_read_b128 v[178:181], v141 offset:49152
	ds_read_b128 v[182:185], v141 offset:50176
	ds_read_b128 v[186:189], v141 offset:51200
	ds_read_b128 v[190:193], v141 offset:52224
	ds_read_b128 v[194:197], v141 offset:53248
	ds_read_b128 v[198:201], v141 offset:54272
	ds_read_b128 v[204:207], v141 offset:55296
	ds_read_b128 v[208:211], v141 offset:56320
	global_load_lds_dwordx4 v[142:143], off
	v_lshl_add_u64 v[142:143], v[212:213], 0, s[24:25]
	s_mov_b32 m0, s71
	s_nop 0
	global_load_lds_dwordx4 v[142:143], off
	v_lshl_add_u64 v[142:143], s[44:45], 0, v[130:131]
	s_mov_b32 m0, s80
	s_nop 0
	global_load_lds_dwordx4 v[142:143], off
	v_lshl_add_u64 v[142:143], s[44:45], 0, v[134:135]
	s_mov_b32 m0, s79
	s_nop 0
	global_load_lds_dwordx4 v[142:143], off
	v_lshl_add_u64 v[142:143], v[214:215], 0, s[24:25]
	s_mov_b32 m0, s64
	s_nop 0
	global_load_lds_dwordx4 v[142:143], off
	v_lshl_add_u64 v[142:143], v[216:217], 0, s[24:25]
	s_mov_b32 m0, s65
	s_nop 0
	global_load_lds_dwordx4 v[142:143], off
	s_waitcnt vmcnt(8)
	s_waitcnt lgkmcnt(0)
	s_barrier
	s_waitcnt lgkmcnt(0)
	v_mfma_f32_16x16x32_bf16 v[60:63], v[146:149], v[178:181], v[60:63]
	v_mfma_f32_16x16x32_bf16 v[56:59], v[154:157], v[178:181], v[56:59]
	v_mfma_f32_16x16x32_bf16 v[52:55], v[146:149], v[186:189], v[52:55]
	v_mfma_f32_16x16x32_bf16 v[44:47], v[154:157], v[186:189], v[44:47]
	v_mfma_f32_16x16x32_bf16 v[36:39], v[146:149], v[194:197], v[36:39]
	v_mfma_f32_16x16x32_bf16 v[28:31], v[154:157], v[194:197], v[28:31]
	v_mfma_f32_16x16x32_bf16 v[20:23], v[146:149], v[204:207], v[20:23]
	v_mfma_f32_16x16x32_bf16 v[12:15], v[154:157], v[204:207], v[12:15]
	v_mfma_f32_16x16x32_bf16 v[60:63], v[150:153], v[182:185], v[60:63]
	v_mfma_f32_16x16x32_bf16 v[56:59], v[158:161], v[182:185], v[56:59]
	v_mfma_f32_16x16x32_bf16 v[52:55], v[150:153], v[190:193], v[52:55]
	v_mfma_f32_16x16x32_bf16 v[44:47], v[158:161], v[190:193], v[44:47]
	v_mfma_f32_16x16x32_bf16 v[36:39], v[150:153], v[198:201], v[36:39]
	v_mfma_f32_16x16x32_bf16 v[28:31], v[158:161], v[198:201], v[28:31]
	v_mfma_f32_16x16x32_bf16 v[20:23], v[150:153], v[208:211], v[20:23]
	v_mfma_f32_16x16x32_bf16 v[12:15], v[158:161], v[208:211], v[12:15]
	v_mfma_f32_16x16x32_bf16 v[48:51], v[162:165], v[178:181], v[48:51]
	v_mfma_f32_16x16x32_bf16 v[40:43], v[170:173], v[178:181], v[40:43]
	v_mfma_f32_16x16x32_bf16 v[32:35], v[162:165], v[186:189], v[32:35]
	v_mfma_f32_16x16x32_bf16 v[24:27], v[170:173], v[186:189], v[24:27]
	v_mfma_f32_16x16x32_bf16 v[16:19], v[162:165], v[194:197], v[16:19]
	v_mfma_f32_16x16x32_bf16 v[8:11], v[170:173], v[194:197], v[8:11]
	v_mfma_f32_16x16x32_bf16 v[4:7], v[162:165], v[204:207], v[4:7]
	v_mfma_f32_16x16x32_bf16 v[0:3], v[170:173], v[204:207], v[0:3]
	v_mfma_f32_16x16x32_bf16 v[48:51], v[166:169], v[182:185], v[48:51]
	v_mfma_f32_16x16x32_bf16 v[40:43], v[174:177], v[182:185], v[40:43]
	v_mfma_f32_16x16x32_bf16 v[32:35], v[166:169], v[190:193], v[32:35]
	v_mfma_f32_16x16x32_bf16 v[24:27], v[174:177], v[190:193], v[24:27]
	v_mfma_f32_16x16x32_bf16 v[16:19], v[166:169], v[198:201], v[16:19]
	v_mfma_f32_16x16x32_bf16 v[8:11], v[174:177], v[198:201], v[8:11]
	v_mfma_f32_16x16x32_bf16 v[4:7], v[166:169], v[208:211], v[4:7]
	v_mfma_f32_16x16x32_bf16 v[0:3], v[174:177], v[208:211], v[0:3]
	s_barrier
	s_andn2_b64 vcc, exec, s[42:43]
	s_mov_b64 s[44:45], -1
	s_mov_b64 s[42:43], 0
	s_mov_b64 s[46:47], 0x100
	s_cbranch_vccz .LBB0_1381
	s_and_b64 vcc, exec, s[26:27]
	s_cbranch_vccnz .LBB0_1384
	s_and_b64 vcc, exec, s[4:5]
	s_mov_b32 s81, s12
	s_cbranch_vccnz .LBB0_1371
	s_branch .LBB0_1385

; #define PG8_STAGE(bufoff, gbase, voff) do { _Pragma("unroll") for (int _i = 0; _i < 2; ++_i) \
;         __builtin_amdgcn_global_load_lds((const unsigned*)((const char*)(gbase) + (voff)[_i]), (LAS unsigned*)(lds + (bufoff) + ldsw + _i * 8192), 16, 0, 0); } while (0)
; #define PG8_LDA(dst, b, h) do { _Pragma("unroll") for (int m = 0; m < 4; ++m) _Pragma("unroll") for (int k = 0; k < 2; ++k) dst[m][k] = *(const LAS bf16x8*)(lds + PG8_SA(b, h) + aoff + m * 2048 + k * 1024); } while (0)
; #define PG8_LDB(dst, b, h) do { _Pragma("unroll") for (int n = 0; n < 2; ++n) _Pragma("unroll") for (int k = 0; k < 2; ++k) dst[n][k] = *(const LAS bf16x8*)(lds + PG8_SB(b, h) + boff + n * 2048 + k * 1024); } while (0)
; #define PG8_MMA(ai, bj, At, Bt) do { __builtin_amdgcn_s_setprio(1); _Pragma("unroll") for (int m = 0; m < 4; ++m) _Pragma("unroll") for (int n = 0; n < 2; ++n) _Pragma("unroll") for (int k = 0; k < 2; ++k) \
;         acc[ai][bj][m][n] = __builtin_amdgcn_mfma_f32_16x16x32_bf16(Bt[n][k], At[m][k], acc[ai][bj][m][n], 0, 0, 0); __builtin_amdgcn_s_setprio(0); } while (0)
; #define PG8_WAIT_V(n) asm volatile("s_waitcnt vmcnt(" #n ")" ::: "memory")
; #define PG8_WAIT_L(n) asm volatile("s_waitcnt lgkmcnt(" #n ")" ::: "memory")
; #define PG8_BAR __builtin_amdgcn_s_barrier()
; #define PG8_SCHED __builtin_amdgcn_sched_barrier(0)
; template <class Epi>
; __device__ __forceinline__ void gemm_phase(LAS unsigned char* lds, const Gemm g, const Sched& S, const Epi& E) {
;     ...
;         for (int t = 0; t < nt; t += 2) {
;             const bool last = (t == nt - 2);
;             const char* a1 = cA + (size_t)(t + 1) * kstep;
;             const char* a2 = last ? nA : cA + (size_t)(t + 2) * kstep; const char* b2 = last ? nB : cB + (size_t)(t + 2) * kstep;
;             const char* a3 = a2 + kstep; const char* b3 = b2 + kstep;
;             PG8_LDB(B0, 0, 0); PG8_LDB(B1, 0, 1); PG8_SCHED; PG8_LDA(At, 0, 0); PG8_STAGE(PG8_SA(1, 1), a1 + hstepA, voffA);
;             PG8_WAIT_V(8); PG8_WAIT_L(0); PG8_BAR; PG8_MMA(0, 0, At, B0); PG8_MMA(0, 1, At, B1); PG8_BAR; PG8_SCHED;
;             PG8_LDA(At, 0, 1); PG8_STAGE(PG8_SB(0, 0), b2, voffB); PG8_STAGE(PG8_SB(0, 1), b2 + hstepB, voffB); PG8_STAGE(PG8_SA(0, 0), a2, voffA);
.LBB0_1439:
	s_add_u32 s47, s28, s46
	s_addc_u32 s52, s29, 0
	s_add_u32 s50, s47, 0x100
	s_addc_u32 s51, s52, 0
	s_and_b64 s[48:49], s[44:45], exec
	s_cselect_b32 s49, s23, s51
	s_cselect_b32 s48, s25, s50
	s_add_u32 s46, s36, s46
	s_addc_u32 s50, s37, 0
	s_add_u32 s46, s46, 0x100
	s_addc_u32 s50, s50, 0
	s_and_b64 s[44:45], s[44:45], exec
	s_cselect_b32 s51, s39, s50
	s_cselect_b32 s50, s38, s46
	s_add_u32 s54, s47, 0x40080
	ds_read_b128 v[146:149], v139
	ds_read_b128 v[150:153], v139 offset:1024
	ds_read_b128 v[154:157], v139 offset:2048
	ds_read_b128 v[158:161], v139 offset:3072
	ds_read_b128 v[162:165], v140
	ds_read_b128 v[166:169], v140 offset:1024
	ds_read_b128 v[170:173], v140 offset:2048
	ds_read_b128 v[174:177], v140 offset:3072
	s_addc_u32 s55, s52, 0
	s_add_i32 s72, s62, s10
	s_add_i32 m0, s27, 0xc000
	s_add_i32 s75, s27, 0xe000
	s_add_i32 s69, s72, 0x2000
	s_add_u32 s52, s50, 0x80000
	s_addc_u32 s53, s51, 0
	s_add_i32 s71, s63, s10
	s_add_i32 s70, s71, 0x2000
	s_add_i32 s68, 0, 0x18000
	s_add_i32 s67, 0, 0x1c000
	s_add_u32 s46, s48, 0x40000
	s_addc_u32 s47, s49, 0
	s_add_i32 s66, s68, s10
	s_add_i32 s65, s66, 0x2000
	s_add_u32 s44, s50, 0x80080
	s_addc_u32 s45, s51, 0
	s_add_i32 s74, s67, s10
	s_add_i32 s73, s74, 0x2000
	v_lshl_add_u64 v[142:143], s[54:55], 0, v[128:129]
	ds_read_b128 v[178:181], v141
	ds_read_b128 v[182:185], v141 offset:1024
	ds_read_b128 v[186:189], v141 offset:2048
	ds_read_b128 v[190:193], v141 offset:3072
	ds_read_b128 v[194:197], v141 offset:4096
	ds_read_b128 v[198:201], v141 offset:5120
	ds_read_b128 v[204:207], v141 offset:6144
	ds_read_b128 v[208:211], v141 offset:7168
	global_load_lds_dwordx4 v[142:143], off
	v_lshl_add_u64 v[142:143], s[54:55], 0, v[132:133]
	s_mov_b32 m0, s75
	s_nop 0
	global_load_lds_dwordx4 v[142:143], off
	s_waitcnt vmcnt(8)
	s_waitcnt lgkmcnt(0)
	s_barrier
	s_waitcnt lgkmcnt(0)
	v_mfma_f32_16x16x32_bf16 v[124:127], v[146:149], v[178:181], v[124:127]
	v_mfma_f32_16x16x32_bf16 v[120:123], v[154:157], v[178:181], v[120:123]
	v_mfma_f32_16x16x32_bf16 v[116:119], v[146:149], v[186:189], v[116:119]
	v_mfma_f32_16x16x32_bf16 v[112:115], v[154:157], v[186:189], v[112:115]
	v_mfma_f32_16x16x32_bf16 v[100:103], v[146:149], v[194:197], v[100:103]
	v_mfma_f32_16x16x32_bf16 v[96:99], v[154:157], v[194:197], v[96:99]
	v_mfma_f32_16x16x32_bf16 v[84:87], v[146:149], v[204:207], v[84:87]
	v_mfma_f32_16x16x32_bf16 v[80:83], v[154:157], v[204:207], v[80:83]
	v_mfma_f32_16x16x32_bf16 v[124:127], v[150:153], v[182:185], v[124:127]
	v_mfma_f32_16x16x32_bf16 v[120:123], v[158:161], v[182:185], v[120:123]
	v_mfma_f32_16x16x32_bf16 v[116:119], v[150:153], v[190:193], v[116:119]
	v_mfma_f32_16x16x32_bf16 v[112:115], v[158:161], v[190:193], v[112:115]
	v_mfma_f32_16x16x32_bf16 v[100:103], v[150:153], v[198:201], v[100:103]
	v_mfma_f32_16x16x32_bf16 v[96:99], v[158:161], v[198:201], v[96:99]
	v_mfma_f32_16x16x32_bf16 v[84:87], v[150:153], v[208:211], v[84:87]
	v_mfma_f32_16x16x32_bf16 v[80:83], v[158:161], v[208:211], v[80:83]
	v_mfma_f32_16x16x32_bf16 v[108:111], v[162:165], v[178:181], v[108:111]
	v_mfma_f32_16x16x32_bf16 v[104:107], v[170:173], v[178:181], v[104:107]
	v_mfma_f32_16x16x32_bf16 v[92:95], v[162:165], v[186:189], v[92:95]
	v_mfma_f32_16x16x32_bf16 v[88:91], v[170:173], v[186:189], v[88:91]
	v_mfma_f32_16x16x32_bf16 v[76:79], v[162:165], v[194:197], v[76:79]
	v_mfma_f32_16x16x32_bf16 v[72:75], v[170:173], v[194:197], v[72:75]
	v_mfma_f32_16x16x32_bf16 v[68:71], v[162:165], v[204:207], v[68:71]
	v_mfma_f32_16x16x32_bf16 v[64:67], v[170:173], v[204:207], v[64:67]
	v_mfma_f32_16x16x32_bf16 v[108:111], v[166:169], v[182:185], v[108:111]
	v_mfma_f32_16x16x32_bf16 v[104:107], v[174:177], v[182:185], v[104:107]
	v_mfma_f32_16x16x32_bf16 v[92:95], v[166:169], v[190:193], v[92:95]
	v_mfma_f32_16x16x32_bf16 v[88:91], v[174:177], v[190:193], v[88:91]
	v_mfma_f32_16x16x32_bf16 v[76:79], v[166:169], v[198:201], v[76:79]
	v_mfma_f32_16x16x32_bf16 v[72:75], v[174:177], v[198:201], v[72:75]
	v_mfma_f32_16x16x32_bf16 v[68:71], v[166:169], v[208:211], v[68:71]
	v_mfma_f32_16x16x32_bf16 v[64:67], v[174:177], v[208:211], v[64:67]
	s_barrier
	s_mov_b32 m0, s72
	v_lshl_add_u64 v[142:143], s[50:51], 0, v[130:131]
	ds_read_b128 v[178:181], v141 offset:16384
	ds_read_b128 v[182:185], v141 offset:17408
	ds_read_b128 v[186:189], v141 offset:18432
	ds_read_b128 v[190:193], v141 offset:19456
	ds_read_b128 v[194:197], v141 offset:20480
	ds_read_b128 v[198:201], v141 offset:21504
	ds_read_b128 v[204:207], v141 offset:22528
	ds_read_b128 v[208:211], v141 offset:23552
	global_load_lds_dwordx4 v[142:143], off
	v_lshl_add_u64 v[212:213], s[50:51], 0, v[134:135]
	s_mov_b32 m0, s69
	v_lshl_add_u64 v[214:215], s[52:53], 0, v[130:131]
	global_load_lds_dwordx4 v[212:213], off
	s_mov_b32 m0, s71
	v_lshl_add_u64 v[216:217], s[48:49], 0, v[132:133]
	global_load_lds_dwordx4 v[214:215], off
	v_lshl_add_u64 v[214:215], s[52:53], 0, v[134:135]
	s_mov_b32 m0, s70
	s_nop 0
	global_load_lds_dwordx4 v[214:215], off
	v_lshl_add_u64 v[214:215], s[48:49], 0, v[128:129]
	s_mov_b32 m0, s27
	s_nop 0
	global_load_lds_dwordx4 v[214:215], off
	s_mov_b32 m0, s56
	s_nop 0
	global_load_lds_dwordx4 v[216:217], off
	s_waitcnt vmcnt(8)
	s_waitcnt lgkmcnt(0)
	s_barrier
; #define PG8_STAGE(bufoff, gbase, voff) do { _Pragma("unroll") for (int _i = 0; _i < 2; ++_i) \
;         __builtin_amdgcn_global_load_lds((const unsigned*)((const char*)(gbase) + (voff)[_i]), (LAS unsigned*)(lds + (bufoff) + ldsw + _i * 8192), 16, 0, 0); } while (0)
; #define PG8_LDA(dst, b, h) do { _Pragma("unroll") for (int m = 0; m < 4; ++m) _Pragma("unroll") for (int k = 0; k < 2; ++k) dst[m][k] = *(const LAS bf16x8*)(lds + PG8_SA(b, h) + aoff + m * 2048 + k * 1024); } while (0)
; #define PG8_LDB(dst, b, h) do { _Pragma("unroll") for (int n = 0; n < 2; ++n) _Pragma("unroll") for (int k = 0; k < 2; ++k) dst[n][k] = *(const LAS bf16x8*)(lds + PG8_SB(b, h) + boff + n * 2048 + k * 1024); } while (0)
; #define PG8_MMA(ai, bj, At, Bt) do { __builtin_amdgcn_s_setprio(1); _Pragma("unroll") for (int m = 0; m < 4; ++m) _Pragma("unroll") for (int n = 0; n < 2; ++n) _Pragma("unroll") for (int k = 0; k < 2; ++k) \
;         acc[ai][bj][m][n] = __builtin_amdgcn_mfma_f32_16x16x32_bf16(Bt[n][k], At[m][k], acc[ai][bj][m][n], 0, 0, 0); __builtin_amdgcn_s_setprio(0); } while (0)
; #define PG8_WAIT_V(n) asm volatile("s_waitcnt vmcnt(" #n ")" ::: "memory")
; #define PG8_WAIT_L(n) asm volatile("s_waitcnt lgkmcnt(" #n ")" ::: "memory")
; #define PG8_BAR __builtin_amdgcn_s_barrier()
; #define PG8_SCHED __builtin_amdgcn_sched_barrier(0)
; template <class Epi>
; __device__ __forceinline__ void gemm_phase(LAS unsigned char* lds, const Gemm g, const Sched& S, const Epi& E) {
;     ...
;             PG8_WAIT_V(8); PG8_WAIT_L(0); PG8_BAR; PG8_MMA(1, 0, At, B0); PG8_MMA(1, 1, At, B1); PG8_BAR; PG8_SCHED;
;             PG8_LDB(B0, 1, 0); PG8_LDB(B1, 1, 1); PG8_SCHED; PG8_LDA(At, 1, 0); PG8_STAGE(PG8_SA(0, 1), a2 + hstepA, voffA);
;             PG8_WAIT_V(8); PG8_WAIT_L(0); PG8_BAR; PG8_MMA(0, 0, At, B0); PG8_MMA(0, 1, At, B1); PG8_BAR; PG8_SCHED;
	s_waitcnt lgkmcnt(0)
	v_mfma_f32_16x16x32_bf16 v[60:63], v[146:149], v[178:181], v[60:63]
	v_mfma_f32_16x16x32_bf16 v[56:59], v[154:157], v[178:181], v[56:59]
	v_mfma_f32_16x16x32_bf16 v[52:55], v[146:149], v[186:189], v[52:55]
	v_mfma_f32_16x16x32_bf16 v[48:51], v[154:157], v[186:189], v[48:51]
	v_mfma_f32_16x16x32_bf16 v[36:39], v[146:149], v[194:197], v[36:39]
	v_mfma_f32_16x16x32_bf16 v[32:35], v[154:157], v[194:197], v[32:35]
	v_mfma_f32_16x16x32_bf16 v[20:23], v[146:149], v[204:207], v[20:23]
	v_mfma_f32_16x16x32_bf16 v[16:19], v[154:157], v[204:207], v[16:19]
	v_mfma_f32_16x16x32_bf16 v[60:63], v[150:153], v[182:185], v[60:63]
	v_mfma_f32_16x16x32_bf16 v[56:59], v[158:161], v[182:185], v[56:59]
	v_mfma_f32_16x16x32_bf16 v[52:55], v[150:153], v[190:193], v[52:55]
	v_mfma_f32_16x16x32_bf16 v[48:51], v[158:161], v[190:193], v[48:51]
	v_mfma_f32_16x16x32_bf16 v[36:39], v[150:153], v[198:201], v[36:39]
	v_mfma_f32_16x16x32_bf16 v[32:35], v[158:161], v[198:201], v[32:35]
	v_mfma_f32_16x16x32_bf16 v[20:23], v[150:153], v[208:211], v[20:23]
	v_mfma_f32_16x16x32_bf16 v[16:19], v[158:161], v[208:211], v[16:19]
	v_mfma_f32_16x16x32_bf16 v[44:47], v[162:165], v[178:181], v[44:47]
	v_mfma_f32_16x16x32_bf16 v[40:43], v[170:173], v[178:181], v[40:43]
	v_mfma_f32_16x16x32_bf16 v[28:31], v[162:165], v[186:189], v[28:31]
	v_mfma_f32_16x16x32_bf16 v[24:27], v[170:173], v[186:189], v[24:27]
	v_mfma_f32_16x16x32_bf16 v[12:15], v[162:165], v[194:197], v[12:15]
	v_mfma_f32_16x16x32_bf16 v[8:11], v[170:173], v[194:197], v[8:11]
	v_mfma_f32_16x16x32_bf16 v[4:7], v[162:165], v[204:207], v[4:7]
	v_mfma_f32_16x16x32_bf16 v[0:3], v[170:173], v[204:207], v[0:3]
	v_mfma_f32_16x16x32_bf16 v[44:47], v[166:169], v[182:185], v[44:47]
	v_mfma_f32_16x16x32_bf16 v[40:43], v[174:177], v[182:185], v[40:43]
	v_mfma_f32_16x16x32_bf16 v[28:31], v[166:169], v[190:193], v[28:31]
	v_mfma_f32_16x16x32_bf16 v[24:27], v[174:177], v[190:193], v[24:27]
	v_mfma_f32_16x16x32_bf16 v[12:15], v[166:169], v[198:201], v[12:15]
	v_mfma_f32_16x16x32_bf16 v[8:11], v[174:177], v[198:201], v[8:11]
	v_mfma_f32_16x16x32_bf16 v[4:7], v[166:169], v[208:211], v[4:7]
	v_mfma_f32_16x16x32_bf16 v[0:3], v[174:177], v[208:211], v[0:3]
	s_barrier
	v_add_u32_e32 v145, s68, v137
	ds_read_b128 v[146:149], v145
	ds_read_b128 v[150:153], v145 offset:1024
	ds_read_b128 v[154:157], v145 offset:2048
	ds_read_b128 v[158:161], v145 offset:3072
	v_add_u32_e32 v145, s67, v137
	ds_read_b128 v[162:165], v145
	ds_read_b128 v[166:169], v145 offset:1024
	ds_read_b128 v[170:173], v145 offset:2048
	ds_read_b128 v[174:177], v145 offset:3072
	s_mov_b32 m0, s57
	v_lshl_add_u64 v[218:219], s[46:47], 0, v[128:129]
	ds_read_b128 v[178:181], v141 offset:32768
	ds_read_b128 v[182:185], v141 offset:33792
	ds_read_b128 v[186:189], v141 offset:34816
	ds_read_b128 v[190:193], v141 offset:35840
	ds_read_b128 v[194:197], v141 offset:36864
	ds_read_b128 v[198:201], v141 offset:37888
	ds_read_b128 v[204:207], v141 offset:38912
	ds_read_b128 v[208:211], v141 offset:39936
	global_load_lds_dwordx4 v[218:219], off
	v_lshl_add_u64 v[218:219], s[46:47], 0, v[132:133]
	s_mov_b32 m0, s58
	s_nop 0
	global_load_lds_dwordx4 v[218:219], off
	s_waitcnt vmcnt(8)
	s_waitcnt lgkmcnt(0)
	s_barrier
	s_waitcnt lgkmcnt(0)
	v_mfma_f32_16x16x32_bf16 v[124:127], v[146:149], v[178:181], v[124:127]
	v_mfma_f32_16x16x32_bf16 v[120:123], v[154:157], v[178:181], v[120:123]
	v_mfma_f32_16x16x32_bf16 v[116:119], v[146:149], v[186:189], v[116:119]
	v_mfma_f32_16x16x32_bf16 v[112:115], v[154:157], v[186:189], v[112:115]
	v_mfma_f32_16x16x32_bf16 v[100:103], v[146:149], v[194:197], v[100:103]
	v_mfma_f32_16x16x32_bf16 v[96:99], v[154:157], v[194:197], v[96:99]
	v_mfma_f32_16x16x32_bf16 v[84:87], v[146:149], v[204:207], v[84:87]
	v_mfma_f32_16x16x32_bf16 v[80:83], v[154:157], v[204:207], v[80:83]
	v_mfma_f32_16x16x32_bf16 v[124:127], v[150:153], v[182:185], v[124:127]
	v_mfma_f32_16x16x32_bf16 v[120:123], v[158:161], v[182:185], v[120:123]
	v_mfma_f32_16x16x32_bf16 v[116:119], v[150:153], v[190:193], v[116:119]
	v_mfma_f32_16x16x32_bf16 v[112:115], v[158:161], v[190:193], v[112:115]
	v_mfma_f32_16x16x32_bf16 v[100:103], v[150:153], v[198:201], v[100:103]
	v_mfma_f32_16x16x32_bf16 v[96:99], v[158:161], v[198:201], v[96:99]
	v_mfma_f32_16x16x32_bf16 v[84:87], v[150:153], v[208:211], v[84:87]
	v_mfma_f32_16x16x32_bf16 v[80:83], v[158:161], v[208:211], v[80:83]
	v_mfma_f32_16x16x32_bf16 v[108:111], v[162:165], v[178:181], v[108:111]
	v_mfma_f32_16x16x32_bf16 v[104:107], v[170:173], v[178:181], v[104:107]
	v_mfma_f32_16x16x32_bf16 v[92:95], v[162:165], v[186:189], v[92:95]
	v_mfma_f32_16x16x32_bf16 v[88:91], v[170:173], v[186:189], v[88:91]
	v_mfma_f32_16x16x32_bf16 v[76:79], v[162:165], v[194:197], v[76:79]
	v_mfma_f32_16x16x32_bf16 v[72:75], v[170:173], v[194:197], v[72:75]
	v_mfma_f32_16x16x32_bf16 v[68:71], v[162:165], v[204:207], v[68:71]
	v_mfma_f32_16x16x32_bf16 v[64:67], v[170:173], v[204:207], v[64:67]
	v_mfma_f32_16x16x32_bf16 v[108:111], v[166:169], v[182:185], v[108:111]
	v_mfma_f32_16x16x32_bf16 v[104:107], v[174:177], v[182:185], v[104:107]
	v_mfma_f32_16x16x32_bf16 v[92:95], v[166:169], v[190:193], v[92:95]
	v_mfma_f32_16x16x32_bf16 v[88:91], v[174:177], v[190:193], v[88:91]
	v_mfma_f32_16x16x32_bf16 v[76:79], v[166:169], v[198:201], v[76:79]
	v_mfma_f32_16x16x32_bf16 v[72:75], v[174:177], v[198:201], v[72:75]
	v_mfma_f32_16x16x32_bf16 v[68:71], v[166:169], v[208:211], v[68:71]
	v_mfma_f32_16x16x32_bf16 v[64:67], v[174:177], v[208:211], v[64:67]
	s_barrier
; #define PG8_STAGE(bufoff, gbase, voff) do { _Pragma("unroll") for (int _i = 0; _i < 2; ++_i) \
;         __builtin_amdgcn_global_load_lds((const unsigned*)((const char*)(gbase) + (voff)[_i]), (LAS unsigned*)(lds + (bufoff) + ldsw + _i * 8192), 16, 0, 0); } while (0)
; #define PG8_LDA(dst, b, h) do { _Pragma("unroll") for (int m = 0; m < 4; ++m) _Pragma("unroll") for (int k = 0; k < 2; ++k) dst[m][k] = *(const LAS bf16x8*)(lds + PG8_SA(b, h) + aoff + m * 2048 + k * 1024); } while (0)
; #define PG8_MMA(ai, bj, At, Bt) do { __builtin_amdgcn_s_setprio(1); _Pragma("unroll") for (int m = 0; m < 4; ++m) _Pragma("unroll") for (int n = 0; n < 2; ++n) _Pragma("unroll") for (int k = 0; k < 2; ++k) \
;         acc[ai][bj][m][n] = __builtin_amdgcn_mfma_f32_16x16x32_bf16(Bt[n][k], At[m][k], acc[ai][bj][m][n], 0, 0, 0); __builtin_amdgcn_s_setprio(0); } while (0)
; #define PG8_WAIT_V(n) asm volatile("s_waitcnt vmcnt(" #n ")" ::: "memory")
; #define PG8_WAIT_L(n) asm volatile("s_waitcnt lgkmcnt(" #n ")" ::: "memory")
; #define PG8_BAR __builtin_amdgcn_s_barrier()
; #define PG8_SCHED __builtin_amdgcn_sched_barrier(0)
; template <class Epi>
; __device__ __forceinline__ void gemm_phase(LAS unsigned char* lds, const Gemm g, const Sched& S, const Epi& E) {
;     ...
;             PG8_LDA(At, 1, 1); PG8_STAGE(PG8_SB(1, 0), b3, voffB); PG8_STAGE(PG8_SB(1, 1), b3 + hstepB, voffB); PG8_STAGE(PG8_SA(1, 0), a3, voffA);
;             PG8_WAIT_V(8); PG8_WAIT_L(0); PG8_BAR; PG8_MMA(1, 0, At, B0); PG8_MMA(1, 1, At, B1); PG8_BAR; PG8_SCHED;
;         }
;         if (wr == 0) PG8_BAR;
	s_mov_b32 m0, s66
	v_lshl_add_u64 v[142:143], v[142:143], 0, s[18:19]
	ds_read_b128 v[178:181], v141 offset:49152
	ds_read_b128 v[182:185], v141 offset:50176
	ds_read_b128 v[186:189], v141 offset:51200
	ds_read_b128 v[190:193], v141 offset:52224
	ds_read_b128 v[194:197], v141 offset:53248
	ds_read_b128 v[198:201], v141 offset:54272
	ds_read_b128 v[204:207], v141 offset:55296
	ds_read_b128 v[208:211], v141 offset:56320
	global_load_lds_dwordx4 v[142:143], off
	v_lshl_add_u64 v[142:143], v[212:213], 0, s[18:19]
	s_mov_b32 m0, s65
	s_nop 0
	global_load_lds_dwordx4 v[142:143], off
	v_lshl_add_u64 v[142:143], s[44:45], 0, v[130:131]
	s_mov_b32 m0, s74
	s_nop 0
	global_load_lds_dwordx4 v[142:143], off
	v_lshl_add_u64 v[142:143], s[44:45], 0, v[134:135]
	s_mov_b32 m0, s73
	s_nop 0
	global_load_lds_dwordx4 v[142:143], off
	v_lshl_add_u64 v[142:143], v[214:215], 0, s[18:19]
	s_mov_b32 m0, s60
	s_nop 0
	global_load_lds_dwordx4 v[142:143], off
	v_lshl_add_u64 v[142:143], v[216:217], 0, s[18:19]
	s_mov_b32 m0, s61
	s_nop 0
	global_load_lds_dwordx4 v[142:143], off
	s_waitcnt vmcnt(8)
	s_waitcnt lgkmcnt(0)
	s_barrier
	s_waitcnt lgkmcnt(0)
	v_mfma_f32_16x16x32_bf16 v[60:63], v[146:149], v[178:181], v[60:63]
	v_mfma_f32_16x16x32_bf16 v[56:59], v[154:157], v[178:181], v[56:59]
	v_mfma_f32_16x16x32_bf16 v[52:55], v[146:149], v[186:189], v[52:55]
	v_mfma_f32_16x16x32_bf16 v[48:51], v[154:157], v[186:189], v[48:51]
	v_mfma_f32_16x16x32_bf16 v[36:39], v[146:149], v[194:197], v[36:39]
	v_mfma_f32_16x16x32_bf16 v[32:35], v[154:157], v[194:197], v[32:35]
	v_mfma_f32_16x16x32_bf16 v[20:23], v[146:149], v[204:207], v[20:23]
	v_mfma_f32_16x16x32_bf16 v[16:19], v[154:157], v[204:207], v[16:19]
	v_mfma_f32_16x16x32_bf16 v[60:63], v[150:153], v[182:185], v[60:63]
	v_mfma_f32_16x16x32_bf16 v[56:59], v[158:161], v[182:185], v[56:59]
	v_mfma_f32_16x16x32_bf16 v[52:55], v[150:153], v[190:193], v[52:55]
	v_mfma_f32_16x16x32_bf16 v[48:51], v[158:161], v[190:193], v[48:51]
	v_mfma_f32_16x16x32_bf16 v[36:39], v[150:153], v[198:201], v[36:39]
	v_mfma_f32_16x16x32_bf16 v[32:35], v[158:161], v[198:201], v[32:35]
	v_mfma_f32_16x16x32_bf16 v[20:23], v[150:153], v[208:211], v[20:23]
	v_mfma_f32_16x16x32_bf16 v[16:19], v[158:161], v[208:211], v[16:19]
	v_mfma_f32_16x16x32_bf16 v[44:47], v[162:165], v[178:181], v[44:47]
	v_mfma_f32_16x16x32_bf16 v[40:43], v[170:173], v[178:181], v[40:43]
	v_mfma_f32_16x16x32_bf16 v[28:31], v[162:165], v[186:189], v[28:31]
	v_mfma_f32_16x16x32_bf16 v[24:27], v[170:173], v[186:189], v[24:27]
	v_mfma_f32_16x16x32_bf16 v[12:15], v[162:165], v[194:197], v[12:15]
	v_mfma_f32_16x16x32_bf16 v[8:11], v[170:173], v[194:197], v[8:11]
	v_mfma_f32_16x16x32_bf16 v[4:7], v[162:165], v[204:207], v[4:7]
	v_mfma_f32_16x16x32_bf16 v[0:3], v[170:173], v[204:207], v[0:3]
	v_mfma_f32_16x16x32_bf16 v[44:47], v[166:169], v[182:185], v[44:47]
	v_mfma_f32_16x16x32_bf16 v[40:43], v[174:177], v[182:185], v[40:43]
	v_mfma_f32_16x16x32_bf16 v[28:31], v[166:169], v[190:193], v[28:31]
	v_mfma_f32_16x16x32_bf16 v[24:27], v[174:177], v[190:193], v[24:27]
	v_mfma_f32_16x16x32_bf16 v[12:15], v[166:169], v[198:201], v[12:15]
	v_mfma_f32_16x16x32_bf16 v[8:11], v[174:177], v[198:201], v[8:11]
	v_mfma_f32_16x16x32_bf16 v[4:7], v[166:169], v[208:211], v[4:7]
	v_mfma_f32_16x16x32_bf16 v[0:3], v[174:177], v[208:211], v[0:3]
	s_barrier
	s_movk_i32 s46, 0x100
	s_andn2_b64 vcc, exec, s[42:43]
	s_mov_b64 s[44:45], -1
	s_mov_b64 s[42:43], 0
	s_cbranch_vccz .LBB0_1439
	s_and_b64 vcc, exec, s[20:21]
	s_cbranch_vccz .LBB0_1442
	s_barrier

; #define PG8_STAGE(bufoff, gbase, voff) do { _Pragma("unroll") for (int _i = 0; _i < 2; ++_i) \
;         __builtin_amdgcn_global_load_lds((const unsigned*)((const char*)(gbase) + (voff)[_i]), (LAS unsigned*)(lds + (bufoff) + ldsw + _i * 8192), 16, 0, 0); } while (0)
; #define PG8_LDA(dst, b, h) do { _Pragma("unroll") for (int m = 0; m < 4; ++m) _Pragma("unroll") for (int k = 0; k < 2; ++k) dst[m][k] = *(const LAS bf16x8*)(lds + PG8_SA(b, h) + aoff + m * 2048 + k * 1024); } while (0)
; #define PG8_LDB(dst, b, h) do { _Pragma("unroll") for (int n = 0; n < 2; ++n) _Pragma("unroll") for (int k = 0; k < 2; ++k) dst[n][k] = *(const LAS bf16x8*)(lds + PG8_SB(b, h) + boff + n * 2048 + k * 1024); } while (0)
; #define PG8_MMA(ai, bj, At, Bt) do { __builtin_amdgcn_s_setprio(1); _Pragma("unroll") for (int m = 0; m < 4; ++m) _Pragma("unroll") for (int n = 0; n < 2; ++n) _Pragma("unroll") for (int k = 0; k < 2; ++k) \
;         acc[ai][bj][m][n] = __builtin_amdgcn_mfma_f32_16x16x32_bf16(Bt[n][k], At[m][k], acc[ai][bj][m][n], 0, 0, 0); __builtin_amdgcn_s_setprio(0); } while (0)
; #define PG8_WAIT_V(n) asm volatile("s_waitcnt vmcnt(" #n ")" ::: "memory")
; #define PG8_WAIT_L(n) asm volatile("s_waitcnt lgkmcnt(" #n ")" ::: "memory")
; #define PG8_BAR __builtin_amdgcn_s_barrier()
; #define PG8_SCHED __builtin_amdgcn_sched_barrier(0)
; template <class Epi>
; __device__ __forceinline__ void gemm_phase(LAS unsigned char* lds, const Gemm g, const Sched& S, const Epi& E) {
;     ...
;         for (int t = 0; t < nt; t += 2) {
;             const bool last = (t == nt - 2);
;             const char* a1 = cA + (size_t)(t + 1) * kstep;
;             const char* a2 = last ? nA : cA + (size_t)(t + 2) * kstep; const char* b2 = last ? nB : cB + (size_t)(t + 2) * kstep;
;             const char* a3 = a2 + kstep; const char* b3 = b2 + kstep;
;             PG8_LDB(B0, 0, 0); PG8_LDB(B1, 0, 1); PG8_SCHED; PG8_LDA(At, 0, 0); PG8_STAGE(PG8_SA(1, 1), a1 + hstepA, voffA);
;             PG8_WAIT_V(8); PG8_WAIT_L(0); PG8_BAR; PG8_MMA(0, 0, At, B0); PG8_MMA(0, 1, At, B1); PG8_BAR; PG8_SCHED;
;             PG8_LDA(At, 0, 1); PG8_STAGE(PG8_SB(0, 0), b2, voffB); PG8_STAGE(PG8_SB(0, 1), b2 + hstepB, voffB); PG8_STAGE(PG8_SA(0, 0), a2, voffA);
.LBB0_1731:
	ds_read_b128 v[148:151], v145
	ds_read_b128 v[152:155], v145 offset:1024
	ds_read_b128 v[156:159], v145 offset:2048
	ds_read_b128 v[160:163], v145 offset:3072
	ds_read_b128 v[164:167], v146
	ds_read_b128 v[168:171], v146 offset:1024
	ds_read_b128 v[172:175], v146 offset:2048
	ds_read_b128 v[176:179], v146 offset:3072
	s_add_u32 s28, s26, 0xfffc0080
	s_addc_u32 s29, s27, -1
	s_cmp_eq_u32 s53, 12
	s_cselect_b32 s37, s17, s29
	s_cselect_b32 s36, s23, s28
	s_cselect_b32 s29, s15, s52
	s_cselect_b32 s28, s50, s51
	v_lshl_add_u64 v[140:141], s[26:27], 0, v[136:137]
	s_add_i32 m0, s25, 0xc000
	ds_read_b128 v[180:183], v147
	ds_read_b128 v[184:187], v147 offset:1024
	ds_read_b128 v[188:191], v147 offset:2048
	ds_read_b128 v[192:195], v147 offset:3072
	ds_read_b128 v[196:199], v147 offset:4096
	ds_read_b128 v[204:207], v147 offset:5120
	ds_read_b128 v[208:211], v147 offset:6144
	ds_read_b128 v[212:215], v147 offset:7168
	global_load_lds_dwordx4 v[140:141], off
	v_lshl_add_u64 v[140:141], s[26:27], 0, v[138:139]
	s_add_i32 m0, s25, 0xe000
	s_nop 0
	global_load_lds_dwordx4 v[140:141], off
	s_waitcnt vmcnt(8)
	s_waitcnt lgkmcnt(0)
	s_barrier
	s_waitcnt lgkmcnt(0)
	v_mfma_f32_16x16x32_bf16 v[116:119], v[148:151], v[180:183], v[116:119]
	v_mfma_f32_16x16x32_bf16 v[124:127], v[156:159], v[180:183], v[124:127]
	v_mfma_f32_16x16x32_bf16 v[100:103], v[148:151], v[188:191], v[100:103]
	v_mfma_f32_16x16x32_bf16 v[108:111], v[156:159], v[188:191], v[108:111]
	v_mfma_f32_16x16x32_bf16 v[84:87], v[148:151], v[196:199], v[84:87]
	v_mfma_f32_16x16x32_bf16 v[92:95], v[156:159], v[196:199], v[92:95]
	v_mfma_f32_16x16x32_bf16 v[68:71], v[148:151], v[208:211], v[68:71]
	v_mfma_f32_16x16x32_bf16 v[76:79], v[156:159], v[208:211], v[76:79]
	v_mfma_f32_16x16x32_bf16 v[116:119], v[152:155], v[184:187], v[116:119]
	v_mfma_f32_16x16x32_bf16 v[124:127], v[160:163], v[184:187], v[124:127]
	v_mfma_f32_16x16x32_bf16 v[100:103], v[152:155], v[192:195], v[100:103]
	v_mfma_f32_16x16x32_bf16 v[108:111], v[160:163], v[192:195], v[108:111]
	v_mfma_f32_16x16x32_bf16 v[84:87], v[152:155], v[204:207], v[84:87]
	v_mfma_f32_16x16x32_bf16 v[92:95], v[160:163], v[204:207], v[92:95]
	v_mfma_f32_16x16x32_bf16 v[68:71], v[152:155], v[212:215], v[68:71]
	v_mfma_f32_16x16x32_bf16 v[76:79], v[160:163], v[212:215], v[76:79]
	v_mfma_f32_16x16x32_bf16 v[112:115], v[164:167], v[180:183], v[112:115]
	v_mfma_f32_16x16x32_bf16 v[120:123], v[172:175], v[180:183], v[120:123]
	v_mfma_f32_16x16x32_bf16 v[96:99], v[164:167], v[188:191], v[96:99]
	v_mfma_f32_16x16x32_bf16 v[104:107], v[172:175], v[188:191], v[104:107]
	v_mfma_f32_16x16x32_bf16 v[80:83], v[164:167], v[196:199], v[80:83]
	v_mfma_f32_16x16x32_bf16 v[88:91], v[172:175], v[196:199], v[88:91]
	v_mfma_f32_16x16x32_bf16 v[64:67], v[164:167], v[208:211], v[64:67]
	v_mfma_f32_16x16x32_bf16 v[72:75], v[172:175], v[208:211], v[72:75]
	v_mfma_f32_16x16x32_bf16 v[112:115], v[168:171], v[184:187], v[112:115]
	v_mfma_f32_16x16x32_bf16 v[120:123], v[176:179], v[184:187], v[120:123]
	v_mfma_f32_16x16x32_bf16 v[96:99], v[168:171], v[192:195], v[96:99]
	v_mfma_f32_16x16x32_bf16 v[104:107], v[176:179], v[192:195], v[104:107]
	v_mfma_f32_16x16x32_bf16 v[80:83], v[168:171], v[204:207], v[80:83]
	v_mfma_f32_16x16x32_bf16 v[88:91], v[176:179], v[204:207], v[88:91]
	v_mfma_f32_16x16x32_bf16 v[64:67], v[168:171], v[212:215], v[64:67]
	v_mfma_f32_16x16x32_bf16 v[72:75], v[176:179], v[212:215], v[72:75]
	s_barrier
	s_add_i32 s54, s46, s39
	v_lshl_add_u64 v[140:141], s[28:29], 0, v[130:131]
	s_mov_b32 m0, s54
	ds_read_b128 v[180:183], v147 offset:16384
	ds_read_b128 v[184:187], v147 offset:17408
	ds_read_b128 v[188:191], v147 offset:18432
	ds_read_b128 v[192:195], v147 offset:19456
	ds_read_b128 v[196:199], v147 offset:20480
	ds_read_b128 v[204:207], v147 offset:21504
	ds_read_b128 v[208:211], v147 offset:22528
	ds_read_b128 v[212:215], v147 offset:23552
	global_load_lds_dwordx4 v[140:141], off
	s_add_i32 m0, s54, 0x2000
	s_add_u32 s54, s28, 0x40000
	v_lshl_add_u64 v[200:201], s[28:29], 0, v[134:135]
	s_addc_u32 s55, s29, 0
	s_add_i32 s56, s47, s39
	global_load_lds_dwordx4 v[200:201], off
	v_lshl_add_u64 v[216:217], s[54:55], 0, v[130:131]
	s_mov_b32 m0, s56
	v_lshl_add_u64 v[218:219], s[36:37], 0, v[132:133]
	global_load_lds_dwordx4 v[216:217], off
	v_lshl_add_u64 v[216:217], s[54:55], 0, v[134:135]
	s_add_i32 m0, s56, 0x2000
	s_nop 0
	global_load_lds_dwordx4 v[216:217], off
	v_lshl_add_u64 v[216:217], s[36:37], 0, v[128:129]
	s_mov_b32 m0, s25
	s_nop 0
	global_load_lds_dwordx4 v[216:217], off
	s_mov_b32 m0, s40
	s_nop 0
	global_load_lds_dwordx4 v[218:219], off
	s_waitcnt vmcnt(8)
	s_waitcnt lgkmcnt(0)
	s_barrier
; #define PG8_STAGE(bufoff, gbase, voff) do { _Pragma("unroll") for (int _i = 0; _i < 2; ++_i) \
;         __builtin_amdgcn_global_load_lds((const unsigned*)((const char*)(gbase) + (voff)[_i]), (LAS unsigned*)(lds + (bufoff) + ldsw + _i * 8192), 16, 0, 0); } while (0)
; #define PG8_LDA(dst, b, h) do { _Pragma("unroll") for (int m = 0; m < 4; ++m) _Pragma("unroll") for (int k = 0; k < 2; ++k) dst[m][k] = *(const LAS bf16x8*)(lds + PG8_SA(b, h) + aoff + m * 2048 + k * 1024); } while (0)
; #define PG8_LDB(dst, b, h) do { _Pragma("unroll") for (int n = 0; n < 2; ++n) _Pragma("unroll") for (int k = 0; k < 2; ++k) dst[n][k] = *(const LAS bf16x8*)(lds + PG8_SB(b, h) + boff + n * 2048 + k * 1024); } while (0)
; #define PG8_MMA(ai, bj, At, Bt) do { __builtin_amdgcn_s_setprio(1); _Pragma("unroll") for (int m = 0; m < 4; ++m) _Pragma("unroll") for (int n = 0; n < 2; ++n) _Pragma("unroll") for (int k = 0; k < 2; ++k) \
;         acc[ai][bj][m][n] = __builtin_amdgcn_mfma_f32_16x16x32_bf16(Bt[n][k], At[m][k], acc[ai][bj][m][n], 0, 0, 0); __builtin_amdgcn_s_setprio(0); } while (0)
; #define PG8_WAIT_V(n) asm volatile("s_waitcnt vmcnt(" #n ")" ::: "memory")
; #define PG8_WAIT_L(n) asm volatile("s_waitcnt lgkmcnt(" #n ")" ::: "memory")
; #define PG8_BAR __builtin_amdgcn_s_barrier()
; #define PG8_SCHED __builtin_amdgcn_sched_barrier(0)
; template <class Epi>
; __device__ __forceinline__ void gemm_phase(LAS unsigned char* lds, const Gemm g, const Sched& S, const Epi& E) {
;     ...
;             PG8_WAIT_V(8); PG8_WAIT_L(0); PG8_BAR; PG8_MMA(1, 0, At, B0); PG8_MMA(1, 1, At, B1); PG8_BAR; PG8_SCHED;
;             PG8_LDB(B0, 1, 0); PG8_LDB(B1, 1, 1); PG8_SCHED; PG8_LDA(At, 1, 0); PG8_STAGE(PG8_SA(0, 1), a2 + hstepA, voffA);
;             PG8_WAIT_V(8); PG8_WAIT_L(0); PG8_BAR; PG8_MMA(0, 0, At, B0); PG8_MMA(0, 1, At, B1); PG8_BAR; PG8_SCHED;
	s_waitcnt lgkmcnt(0)
	v_mfma_f32_16x16x32_bf16 v[52:55], v[148:151], v[180:183], v[52:55]
	v_mfma_f32_16x16x32_bf16 v[60:63], v[156:159], v[180:183], v[60:63]
	v_mfma_f32_16x16x32_bf16 v[36:39], v[148:151], v[188:191], v[36:39]
	v_mfma_f32_16x16x32_bf16 v[44:47], v[156:159], v[188:191], v[44:47]
	v_mfma_f32_16x16x32_bf16 v[20:23], v[148:151], v[196:199], v[20:23]
	v_mfma_f32_16x16x32_bf16 v[28:31], v[156:159], v[196:199], v[28:31]
	v_mfma_f32_16x16x32_bf16 v[4:7], v[148:151], v[208:211], v[4:7]
	v_mfma_f32_16x16x32_bf16 v[12:15], v[156:159], v[208:211], v[12:15]
	v_mfma_f32_16x16x32_bf16 v[52:55], v[152:155], v[184:187], v[52:55]
	v_mfma_f32_16x16x32_bf16 v[60:63], v[160:163], v[184:187], v[60:63]
	v_mfma_f32_16x16x32_bf16 v[36:39], v[152:155], v[192:195], v[36:39]
	v_mfma_f32_16x16x32_bf16 v[44:47], v[160:163], v[192:195], v[44:47]
	v_mfma_f32_16x16x32_bf16 v[20:23], v[152:155], v[204:207], v[20:23]
	v_mfma_f32_16x16x32_bf16 v[28:31], v[160:163], v[204:207], v[28:31]
	v_mfma_f32_16x16x32_bf16 v[4:7], v[152:155], v[212:215], v[4:7]
	v_mfma_f32_16x16x32_bf16 v[12:15], v[160:163], v[212:215], v[12:15]
	v_mfma_f32_16x16x32_bf16 v[48:51], v[164:167], v[180:183], v[48:51]
	v_mfma_f32_16x16x32_bf16 v[56:59], v[172:175], v[180:183], v[56:59]
	v_mfma_f32_16x16x32_bf16 v[32:35], v[164:167], v[188:191], v[32:35]
	v_mfma_f32_16x16x32_bf16 v[40:43], v[172:175], v[188:191], v[40:43]
	v_mfma_f32_16x16x32_bf16 v[16:19], v[164:167], v[196:199], v[16:19]
	v_mfma_f32_16x16x32_bf16 v[24:27], v[172:175], v[196:199], v[24:27]
	v_mfma_f32_16x16x32_bf16 v[0:3], v[164:167], v[208:211], v[0:3]
	v_mfma_f32_16x16x32_bf16 v[8:11], v[172:175], v[208:211], v[8:11]
	v_mfma_f32_16x16x32_bf16 v[48:51], v[168:171], v[184:187], v[48:51]
	v_mfma_f32_16x16x32_bf16 v[56:59], v[176:179], v[184:187], v[56:59]
	v_mfma_f32_16x16x32_bf16 v[32:35], v[168:171], v[192:195], v[32:35]
	v_mfma_f32_16x16x32_bf16 v[40:43], v[176:179], v[192:195], v[40:43]
	v_mfma_f32_16x16x32_bf16 v[16:19], v[168:171], v[204:207], v[16:19]
	v_mfma_f32_16x16x32_bf16 v[24:27], v[176:179], v[204:207], v[24:27]
	v_mfma_f32_16x16x32_bf16 v[0:3], v[168:171], v[212:215], v[0:3]
	v_mfma_f32_16x16x32_bf16 v[8:11], v[176:179], v[212:215], v[8:11]
	s_barrier
	s_add_i32 s54, 0, 0x18000
	s_add_i32 s55, 0, 0x1c000
	v_add_u32_e32 v160, s54, v143
	v_add_u32_e32 v176, s55, v143
	ds_read_b128 v[148:151], v160
	ds_read_b128 v[152:155], v160 offset:1024
	ds_read_b128 v[156:159], v160 offset:2048
	ds_read_b128 v[160:163], v160 offset:3072
	ds_read_b128 v[164:167], v176
	ds_read_b128 v[168:171], v176 offset:1024
	ds_read_b128 v[172:175], v176 offset:2048
	ds_read_b128 v[176:179], v176 offset:3072
	s_add_u32 s36, s36, 0x40000
	s_addc_u32 s37, s37, 0
	s_mov_b32 m0, s41
	v_lshl_add_u64 v[220:221], s[36:37], 0, v[128:129]
	ds_read_b128 v[180:183], v147 offset:32768
	ds_read_b128 v[184:187], v147 offset:33792
	ds_read_b128 v[188:191], v147 offset:34816
	ds_read_b128 v[192:195], v147 offset:35840
	ds_read_b128 v[196:199], v147 offset:36864
	ds_read_b128 v[204:207], v147 offset:37888
	ds_read_b128 v[208:211], v147 offset:38912
	ds_read_b128 v[212:215], v147 offset:39936
	global_load_lds_dwordx4 v[220:221], off
	v_lshl_add_u64 v[220:221], s[36:37], 0, v[132:133]
	s_mov_b32 m0, s42
	s_nop 0
	global_load_lds_dwordx4 v[220:221], off
	s_waitcnt vmcnt(8)
	s_waitcnt lgkmcnt(0)
	s_barrier
	s_waitcnt lgkmcnt(0)
	v_mfma_f32_16x16x32_bf16 v[116:119], v[148:151], v[180:183], v[116:119]
	v_mfma_f32_16x16x32_bf16 v[124:127], v[156:159], v[180:183], v[124:127]
	v_mfma_f32_16x16x32_bf16 v[100:103], v[148:151], v[188:191], v[100:103]
	v_mfma_f32_16x16x32_bf16 v[108:111], v[156:159], v[188:191], v[108:111]
	v_mfma_f32_16x16x32_bf16 v[84:87], v[148:151], v[196:199], v[84:87]
	v_mfma_f32_16x16x32_bf16 v[92:95], v[156:159], v[196:199], v[92:95]
	v_mfma_f32_16x16x32_bf16 v[68:71], v[148:151], v[208:211], v[68:71]
	v_mfma_f32_16x16x32_bf16 v[76:79], v[156:159], v[208:211], v[76:79]
	v_mfma_f32_16x16x32_bf16 v[116:119], v[152:155], v[184:187], v[116:119]
	v_mfma_f32_16x16x32_bf16 v[124:127], v[160:163], v[184:187], v[124:127]
	v_mfma_f32_16x16x32_bf16 v[100:103], v[152:155], v[192:195], v[100:103]
	v_mfma_f32_16x16x32_bf16 v[108:111], v[160:163], v[192:195], v[108:111]
	v_mfma_f32_16x16x32_bf16 v[84:87], v[152:155], v[204:207], v[84:87]
	v_mfma_f32_16x16x32_bf16 v[92:95], v[160:163], v[204:207], v[92:95]
	v_mfma_f32_16x16x32_bf16 v[68:71], v[152:155], v[212:215], v[68:71]
	v_mfma_f32_16x16x32_bf16 v[76:79], v[160:163], v[212:215], v[76:79]
	v_mfma_f32_16x16x32_bf16 v[112:115], v[164:167], v[180:183], v[112:115]
	v_mfma_f32_16x16x32_bf16 v[120:123], v[172:175], v[180:183], v[120:123]
	v_mfma_f32_16x16x32_bf16 v[96:99], v[164:167], v[188:191], v[96:99]
	v_mfma_f32_16x16x32_bf16 v[104:107], v[172:175], v[188:191], v[104:107]
	v_mfma_f32_16x16x32_bf16 v[80:83], v[164:167], v[196:199], v[80:83]
	v_mfma_f32_16x16x32_bf16 v[88:91], v[172:175], v[196:199], v[88:91]
	v_mfma_f32_16x16x32_bf16 v[64:67], v[164:167], v[208:211], v[64:67]
	v_mfma_f32_16x16x32_bf16 v[72:75], v[172:175], v[208:211], v[72:75]
	v_mfma_f32_16x16x32_bf16 v[112:115], v[168:171], v[184:187], v[112:115]
	v_mfma_f32_16x16x32_bf16 v[120:123], v[176:179], v[184:187], v[120:123]
	v_mfma_f32_16x16x32_bf16 v[96:99], v[168:171], v[192:195], v[96:99]
	v_mfma_f32_16x16x32_bf16 v[104:107], v[176:179], v[192:195], v[104:107]
	v_mfma_f32_16x16x32_bf16 v[80:83], v[168:171], v[204:207], v[80:83]
	v_mfma_f32_16x16x32_bf16 v[88:91], v[176:179], v[204:207], v[88:91]
	v_mfma_f32_16x16x32_bf16 v[64:67], v[168:171], v[212:215], v[64:67]
	v_mfma_f32_16x16x32_bf16 v[72:75], v[176:179], v[212:215], v[72:75]
	s_barrier
; #define PG8_STAGE(bufoff, gbase, voff) do { _Pragma("unroll") for (int _i = 0; _i < 2; ++_i) \
;         __builtin_amdgcn_global_load_lds((const unsigned*)((const char*)(gbase) + (voff)[_i]), (LAS unsigned*)(lds + (bufoff) + ldsw + _i * 8192), 16, 0, 0); } while (0)
; #define PG8_LDA(dst, b, h) do { _Pragma("unroll") for (int m = 0; m < 4; ++m) _Pragma("unroll") for (int k = 0; k < 2; ++k) dst[m][k] = *(const LAS bf16x8*)(lds + PG8_SA(b, h) + aoff + m * 2048 + k * 1024); } while (0)
; #define PG8_MMA(ai, bj, At, Bt) do { __builtin_amdgcn_s_setprio(1); _Pragma("unroll") for (int m = 0; m < 4; ++m) _Pragma("unroll") for (int n = 0; n < 2; ++n) _Pragma("unroll") for (int k = 0; k < 2; ++k) \
;         acc[ai][bj][m][n] = __builtin_amdgcn_mfma_f32_16x16x32_bf16(Bt[n][k], At[m][k], acc[ai][bj][m][n], 0, 0, 0); __builtin_amdgcn_s_setprio(0); } while (0)
; #define PG8_WAIT_V(n) asm volatile("s_waitcnt vmcnt(" #n ")" ::: "memory")
; #define PG8_WAIT_L(n) asm volatile("s_waitcnt lgkmcnt(" #n ")" ::: "memory")
; #define PG8_BAR __builtin_amdgcn_s_barrier()
; #define PG8_SCHED __builtin_amdgcn_sched_barrier(0)
; template <class Epi>
; __device__ __forceinline__ void gemm_phase(LAS unsigned char* lds, const Gemm g, const Sched& S, const Epi& E) {
;     ...
;             PG8_LDA(At, 1, 1); PG8_STAGE(PG8_SB(1, 0), b3, voffB); PG8_STAGE(PG8_SB(1, 1), b3 + hstepB, voffB); PG8_STAGE(PG8_SA(1, 0), a3, voffA);
;             PG8_WAIT_V(8); PG8_WAIT_L(0); PG8_BAR; PG8_MMA(1, 0, At, B0); PG8_MMA(1, 1, At, B1); PG8_BAR; PG8_SCHED;
;         }
;         if (wr == 0) PG8_BAR;
	s_add_i32 s36, s54, s39
	v_lshl_add_u64 v[140:141], v[140:141], 0, s[4:5]
	s_mov_b32 m0, s36
	ds_read_b128 v[180:183], v147 offset:49152
	ds_read_b128 v[184:187], v147 offset:50176
	ds_read_b128 v[188:191], v147 offset:51200
	ds_read_b128 v[192:195], v147 offset:52224
	ds_read_b128 v[196:199], v147 offset:53248
	ds_read_b128 v[204:207], v147 offset:54272
	ds_read_b128 v[208:211], v147 offset:55296
	ds_read_b128 v[212:215], v147 offset:56320
	global_load_lds_dwordx4 v[140:141], off
	s_add_i32 m0, s36, 0x2000
	s_add_u32 s28, s28, 0x40080
	v_lshl_add_u64 v[140:141], v[200:201], 0, s[4:5]
	s_addc_u32 s29, s29, 0
	s_add_i32 s36, s55, s39
	global_load_lds_dwordx4 v[140:141], off
	v_lshl_add_u64 v[140:141], s[28:29], 0, v[130:131]
	s_mov_b32 m0, s36
	s_nop 0
	global_load_lds_dwordx4 v[140:141], off
	v_lshl_add_u64 v[140:141], s[28:29], 0, v[134:135]
	s_add_i32 m0, s36, 0x2000
	s_nop 0
	global_load_lds_dwordx4 v[140:141], off
	v_lshl_add_u64 v[140:141], v[216:217], 0, s[4:5]
	s_mov_b32 m0, s44
	s_nop 0
	global_load_lds_dwordx4 v[140:141], off
	v_lshl_add_u64 v[140:141], v[218:219], 0, s[4:5]
	s_mov_b32 m0, s45
	s_nop 0
	global_load_lds_dwordx4 v[140:141], off
	s_waitcnt vmcnt(8)
	s_waitcnt lgkmcnt(0)
	s_barrier
	s_waitcnt lgkmcnt(0)
	v_mfma_f32_16x16x32_bf16 v[52:55], v[148:151], v[180:183], v[52:55]
	v_mfma_f32_16x16x32_bf16 v[60:63], v[156:159], v[180:183], v[60:63]
	v_mfma_f32_16x16x32_bf16 v[36:39], v[148:151], v[188:191], v[36:39]
	v_mfma_f32_16x16x32_bf16 v[44:47], v[156:159], v[188:191], v[44:47]
	v_mfma_f32_16x16x32_bf16 v[20:23], v[148:151], v[196:199], v[20:23]
	v_mfma_f32_16x16x32_bf16 v[28:31], v[156:159], v[196:199], v[28:31]
	v_mfma_f32_16x16x32_bf16 v[4:7], v[148:151], v[208:211], v[4:7]
	v_mfma_f32_16x16x32_bf16 v[12:15], v[156:159], v[208:211], v[12:15]
	v_mfma_f32_16x16x32_bf16 v[52:55], v[152:155], v[184:187], v[52:55]
	v_mfma_f32_16x16x32_bf16 v[60:63], v[160:163], v[184:187], v[60:63]
	v_mfma_f32_16x16x32_bf16 v[36:39], v[152:155], v[192:195], v[36:39]
	v_mfma_f32_16x16x32_bf16 v[44:47], v[160:163], v[192:195], v[44:47]
	v_mfma_f32_16x16x32_bf16 v[20:23], v[152:155], v[204:207], v[20:23]
	v_mfma_f32_16x16x32_bf16 v[28:31], v[160:163], v[204:207], v[28:31]
	v_mfma_f32_16x16x32_bf16 v[4:7], v[152:155], v[212:215], v[4:7]
	v_mfma_f32_16x16x32_bf16 v[12:15], v[160:163], v[212:215], v[12:15]
	v_mfma_f32_16x16x32_bf16 v[48:51], v[164:167], v[180:183], v[48:51]
	v_mfma_f32_16x16x32_bf16 v[56:59], v[172:175], v[180:183], v[56:59]
	v_mfma_f32_16x16x32_bf16 v[32:35], v[164:167], v[188:191], v[32:35]
	v_mfma_f32_16x16x32_bf16 v[40:43], v[172:175], v[188:191], v[40:43]
	v_mfma_f32_16x16x32_bf16 v[16:19], v[164:167], v[196:199], v[16:19]
	v_mfma_f32_16x16x32_bf16 v[24:27], v[172:175], v[196:199], v[24:27]
	v_mfma_f32_16x16x32_bf16 v[0:3], v[164:167], v[208:211], v[0:3]
	v_mfma_f32_16x16x32_bf16 v[8:11], v[172:175], v[208:211], v[8:11]
	v_mfma_f32_16x16x32_bf16 v[48:51], v[168:171], v[184:187], v[48:51]
	v_mfma_f32_16x16x32_bf16 v[56:59], v[176:179], v[184:187], v[56:59]
	v_mfma_f32_16x16x32_bf16 v[32:35], v[168:171], v[192:195], v[32:35]
	v_mfma_f32_16x16x32_bf16 v[40:43], v[176:179], v[192:195], v[40:43]
	v_mfma_f32_16x16x32_bf16 v[16:19], v[168:171], v[204:207], v[16:19]
	v_mfma_f32_16x16x32_bf16 v[24:27], v[176:179], v[204:207], v[24:27]
	v_mfma_f32_16x16x32_bf16 v[0:3], v[168:171], v[212:215], v[0:3]
	v_mfma_f32_16x16x32_bf16 v[8:11], v[176:179], v[212:215], v[8:11]
	s_barrier
	s_add_i32 s53, s53, 2
	s_add_u32 s26, s26, 0x100
	s_addc_u32 s27, s27, 0
	s_add_u32 s51, s51, 0x100
	s_addc_u32 s52, s52, 0
	s_cmp_gt_u32 s53, 13
	s_cbranch_scc0 .LBB0_1731
	s_and_b64 vcc, exec, s[6:7]
	s_cbranch_vccz .LBB0_1734
	s_barrier

; #define PG8_STAGE(bufoff, gbase, voff) do { _Pragma("unroll") for (int _i = 0; _i < 2; ++_i) \
;         __builtin_amdgcn_global_load_lds((const unsigned*)((const char*)(gbase) + (voff)[_i]), (LAS unsigned*)(lds + (bufoff) + ldsw + _i * 8192), 16, 0, 0); } while (0)
; #define PG8_LDA(dst, b, h) do { _Pragma("unroll") for (int m = 0; m < 4; ++m) _Pragma("unroll") for (int k = 0; k < 2; ++k) dst[m][k] = *(const LAS bf16x8*)(lds + PG8_SA(b, h) + aoff + m * 2048 + k * 1024); } while (0)
; #define PG8_LDB(dst, b, h) do { _Pragma("unroll") for (int n = 0; n < 2; ++n) _Pragma("unroll") for (int k = 0; k < 2; ++k) dst[n][k] = *(const LAS bf16x8*)(lds + PG8_SB(b, h) + boff + n * 2048 + k * 1024); } while (0)
; #define PG8_MMA(ai, bj, At, Bt) do { __builtin_amdgcn_s_setprio(1); _Pragma("unroll") for (int m = 0; m < 4; ++m) _Pragma("unroll") for (int n = 0; n < 2; ++n) _Pragma("unroll") for (int k = 0; k < 2; ++k) \
;         acc[ai][bj][m][n] = __builtin_amdgcn_mfma_f32_16x16x32_bf16(Bt[n][k], At[m][k], acc[ai][bj][m][n], 0, 0, 0); __builtin_amdgcn_s_setprio(0); } while (0)
; #define PG8_WAIT_V(n) asm volatile("s_waitcnt vmcnt(" #n ")" ::: "memory")
; #define PG8_WAIT_L(n) asm volatile("s_waitcnt lgkmcnt(" #n ")" ::: "memory")
; #define PG8_BAR __builtin_amdgcn_s_barrier()
; #define PG8_SCHED __builtin_amdgcn_sched_barrier(0)
; template <class Epi>
; __device__ __forceinline__ void gemm_phase(LAS unsigned char* lds, const Gemm g, const Sched& S, const Epi& E) {
;     ...
;         for (int t = 0; t < nt; t += 2) {
;             const bool last = (t == nt - 2);
;             const char* a1 = cA + (size_t)(t + 1) * kstep;
;             const char* a2 = last ? nA : cA + (size_t)(t + 2) * kstep; const char* b2 = last ? nB : cB + (size_t)(t + 2) * kstep;
;             const char* a3 = a2 + kstep; const char* b3 = b2 + kstep;
;             PG8_LDB(B0, 0, 0); PG8_LDB(B1, 0, 1); PG8_SCHED; PG8_LDA(At, 0, 0); PG8_STAGE(PG8_SA(1, 1), a1 + hstepA, voffA);
;             PG8_WAIT_V(8); PG8_WAIT_L(0); PG8_BAR; PG8_MMA(0, 0, At, B0); PG8_MMA(0, 1, At, B1); PG8_BAR; PG8_SCHED;
;             PG8_LDA(At, 0, 1); PG8_STAGE(PG8_SB(0, 0), b2, voffB); PG8_STAGE(PG8_SB(0, 1), b2 + hstepB, voffB); PG8_STAGE(PG8_SA(0, 0), a2, voffA);
.LBB0_1827:
	v_add_u32_e32 v158, s54, v144
	v_add_u32_e32 v174, s55, v144
	s_add_u32 s36, s26, s28
	ds_read_b128 v[146:149], v158
	ds_read_b128 v[150:153], v158 offset:1024
	ds_read_b128 v[154:157], v158 offset:2048
	ds_read_b128 v[158:161], v158 offset:3072
	ds_read_b128 v[162:165], v174
	ds_read_b128 v[166:169], v174 offset:1024
	ds_read_b128 v[170:173], v174 offset:2048
	ds_read_b128 v[174:177], v174 offset:3072
	s_addc_u32 s37, s27, s29
	s_add_u32 s36, s36, 0x100
	s_addc_u32 s37, s37, 0
	s_add_u32 s66, s63, s28
	s_addc_u32 s67, s64, s29
	s_cmpk_eq_i32 s28, 0x1500
	s_cselect_b32 s39, s23, s37
	s_cselect_b32 s38, s22, s36
	s_cselect_b32 s37, s25, s67
	s_cselect_b32 s36, s24, s66
	s_mov_b32 m0, s56
	v_lshl_add_u64 v[214:215], v[140:141], 0, s[28:29]
	ds_read_b128 v[178:181], v145
	ds_read_b128 v[182:185], v145 offset:1024
	ds_read_b128 v[186:189], v145 offset:2048
	ds_read_b128 v[190:193], v145 offset:3072
	ds_read_b128 v[194:197], v145 offset:4096
	ds_read_b128 v[198:201], v145 offset:5120
	ds_read_b128 v[206:209], v145 offset:6144
	ds_read_b128 v[210:213], v145 offset:7168
	global_load_lds_dwordx4 v[214:215], off
	v_lshl_add_u64 v[214:215], v[142:143], 0, s[28:29]
	s_mov_b32 m0, s57
	s_nop 0
	global_load_lds_dwordx4 v[214:215], off
	s_waitcnt vmcnt(8)
	s_waitcnt lgkmcnt(0)
	s_barrier
	s_waitcnt lgkmcnt(0)
	v_mfma_f32_16x16x32_bf16 v[124:127], v[146:149], v[178:181], v[124:127]
	v_mfma_f32_16x16x32_bf16 v[120:123], v[154:157], v[178:181], v[120:123]
	v_mfma_f32_16x16x32_bf16 v[108:111], v[146:149], v[186:189], v[108:111]
	v_mfma_f32_16x16x32_bf16 v[104:107], v[154:157], v[186:189], v[104:107]
	v_mfma_f32_16x16x32_bf16 v[92:95], v[146:149], v[194:197], v[92:95]
	v_mfma_f32_16x16x32_bf16 v[88:91], v[154:157], v[194:197], v[88:91]
	v_mfma_f32_16x16x32_bf16 v[76:79], v[146:149], v[206:209], v[76:79]
	v_mfma_f32_16x16x32_bf16 v[72:75], v[154:157], v[206:209], v[72:75]
	v_mfma_f32_16x16x32_bf16 v[124:127], v[150:153], v[182:185], v[124:127]
	v_mfma_f32_16x16x32_bf16 v[120:123], v[158:161], v[182:185], v[120:123]
	v_mfma_f32_16x16x32_bf16 v[108:111], v[150:153], v[190:193], v[108:111]
	v_mfma_f32_16x16x32_bf16 v[104:107], v[158:161], v[190:193], v[104:107]
	v_mfma_f32_16x16x32_bf16 v[92:95], v[150:153], v[198:201], v[92:95]
	v_mfma_f32_16x16x32_bf16 v[88:91], v[158:161], v[198:201], v[88:91]
	v_mfma_f32_16x16x32_bf16 v[76:79], v[150:153], v[210:213], v[76:79]
	v_mfma_f32_16x16x32_bf16 v[72:75], v[158:161], v[210:213], v[72:75]
	v_mfma_f32_16x16x32_bf16 v[116:119], v[162:165], v[178:181], v[116:119]
	v_mfma_f32_16x16x32_bf16 v[112:115], v[170:173], v[178:181], v[112:115]
	v_mfma_f32_16x16x32_bf16 v[100:103], v[162:165], v[186:189], v[100:103]
	v_mfma_f32_16x16x32_bf16 v[96:99], v[170:173], v[186:189], v[96:99]
	v_mfma_f32_16x16x32_bf16 v[84:87], v[162:165], v[194:197], v[84:87]
	v_mfma_f32_16x16x32_bf16 v[80:83], v[170:173], v[194:197], v[80:83]
	v_mfma_f32_16x16x32_bf16 v[68:71], v[162:165], v[206:209], v[68:71]
	v_mfma_f32_16x16x32_bf16 v[64:67], v[170:173], v[206:209], v[64:67]
	v_mfma_f32_16x16x32_bf16 v[116:119], v[166:169], v[182:185], v[116:119]
	v_mfma_f32_16x16x32_bf16 v[112:115], v[174:177], v[182:185], v[112:115]
	v_mfma_f32_16x16x32_bf16 v[100:103], v[166:169], v[190:193], v[100:103]
	v_mfma_f32_16x16x32_bf16 v[96:99], v[174:177], v[190:193], v[96:99]
	v_mfma_f32_16x16x32_bf16 v[84:87], v[166:169], v[198:201], v[84:87]
	v_mfma_f32_16x16x32_bf16 v[80:83], v[174:177], v[198:201], v[80:83]
	v_mfma_f32_16x16x32_bf16 v[68:71], v[166:169], v[210:213], v[68:71]
	v_mfma_f32_16x16x32_bf16 v[64:67], v[174:177], v[210:213], v[64:67]
	s_barrier
	s_mov_b32 m0, s58
	v_lshl_add_u64 v[214:215], s[36:37], 0, v[130:131]
	ds_read_b128 v[178:181], v145 offset:16384
	ds_read_b128 v[182:185], v145 offset:17408
	ds_read_b128 v[186:189], v145 offset:18432
	ds_read_b128 v[190:193], v145 offset:19456
	ds_read_b128 v[194:197], v145 offset:20480
	ds_read_b128 v[198:201], v145 offset:21504
	ds_read_b128 v[206:209], v145 offset:22528
	ds_read_b128 v[210:213], v145 offset:23552
	global_load_lds_dwordx4 v[214:215], off
	s_add_i32 m0, s58, 0x2000
	s_add_u32 s66, s36, 0xb0000
	v_lshl_add_u64 v[216:217], s[36:37], 0, v[134:135]
	s_addc_u32 s67, s37, 0
	s_add_i32 s68, s55, s46
	global_load_lds_dwordx4 v[216:217], off
	v_lshl_add_u64 v[218:219], s[66:67], 0, v[130:131]
	s_mov_b32 m0, s68
	v_lshl_add_u64 v[220:221], s[38:39], 0, v[132:133]
	global_load_lds_dwordx4 v[218:219], off
	v_lshl_add_u64 v[218:219], s[66:67], 0, v[134:135]
	s_add_i32 m0, s68, 0x2000
	s_nop 0
	global_load_lds_dwordx4 v[218:219], off
	v_lshl_add_u64 v[218:219], s[38:39], 0, v[128:129]
	s_mov_b32 m0, s47
	s_nop 0
	global_load_lds_dwordx4 v[218:219], off
	s_mov_b32 m0, s48
	s_nop 0
	global_load_lds_dwordx4 v[220:221], off
	s_waitcnt vmcnt(8)
	s_waitcnt lgkmcnt(0)
	s_barrier
; #define PG8_STAGE(bufoff, gbase, voff) do { _Pragma("unroll") for (int _i = 0; _i < 2; ++_i) \
;         __builtin_amdgcn_global_load_lds((const unsigned*)((const char*)(gbase) + (voff)[_i]), (LAS unsigned*)(lds + (bufoff) + ldsw + _i * 8192), 16, 0, 0); } while (0)
; #define PG8_LDA(dst, b, h) do { _Pragma("unroll") for (int m = 0; m < 4; ++m) _Pragma("unroll") for (int k = 0; k < 2; ++k) dst[m][k] = *(const LAS bf16x8*)(lds + PG8_SA(b, h) + aoff + m * 2048 + k * 1024); } while (0)
; #define PG8_LDB(dst, b, h) do { _Pragma("unroll") for (int n = 0; n < 2; ++n) _Pragma("unroll") for (int k = 0; k < 2; ++k) dst[n][k] = *(const LAS bf16x8*)(lds + PG8_SB(b, h) + boff + n * 2048 + k * 1024); } while (0)
; #define PG8_MMA(ai, bj, At, Bt) do { __builtin_amdgcn_s_setprio(1); _Pragma("unroll") for (int m = 0; m < 4; ++m) _Pragma("unroll") for (int n = 0; n < 2; ++n) _Pragma("unroll") for (int k = 0; k < 2; ++k) \
;         acc[ai][bj][m][n] = __builtin_amdgcn_mfma_f32_16x16x32_bf16(Bt[n][k], At[m][k], acc[ai][bj][m][n], 0, 0, 0); __builtin_amdgcn_s_setprio(0); } while (0)
; #define PG8_WAIT_V(n) asm volatile("s_waitcnt vmcnt(" #n ")" ::: "memory")
; #define PG8_WAIT_L(n) asm volatile("s_waitcnt lgkmcnt(" #n ")" ::: "memory")
; #define PG8_BAR __builtin_amdgcn_s_barrier()
; #define PG8_SCHED __builtin_amdgcn_sched_barrier(0)
; template <class Epi>
; __device__ __forceinline__ void gemm_phase(LAS unsigned char* lds, const Gemm g, const Sched& S, const Epi& E) {
;     ...
;             PG8_WAIT_V(8); PG8_WAIT_L(0); PG8_BAR; PG8_MMA(1, 0, At, B0); PG8_MMA(1, 1, At, B1); PG8_BAR; PG8_SCHED;
;             PG8_LDB(B0, 1, 0); PG8_LDB(B1, 1, 1); PG8_SCHED; PG8_LDA(At, 1, 0); PG8_STAGE(PG8_SA(0, 1), a2 + hstepA, voffA);
;             PG8_WAIT_V(8); PG8_WAIT_L(0); PG8_BAR; PG8_MMA(0, 0, At, B0); PG8_MMA(0, 1, At, B1); PG8_BAR; PG8_SCHED;
	s_waitcnt lgkmcnt(0)
	v_mfma_f32_16x16x32_bf16 v[60:63], v[146:149], v[178:181], v[60:63]
	v_mfma_f32_16x16x32_bf16 v[56:59], v[154:157], v[178:181], v[56:59]
	v_mfma_f32_16x16x32_bf16 v[44:47], v[146:149], v[186:189], v[44:47]
	v_mfma_f32_16x16x32_bf16 v[40:43], v[154:157], v[186:189], v[40:43]
	v_mfma_f32_16x16x32_bf16 v[28:31], v[146:149], v[194:197], v[28:31]
	v_mfma_f32_16x16x32_bf16 v[24:27], v[154:157], v[194:197], v[24:27]
	v_mfma_f32_16x16x32_bf16 v[12:15], v[146:149], v[206:209], v[12:15]
	v_mfma_f32_16x16x32_bf16 v[8:11], v[154:157], v[206:209], v[8:11]
	v_mfma_f32_16x16x32_bf16 v[60:63], v[150:153], v[182:185], v[60:63]
	v_mfma_f32_16x16x32_bf16 v[56:59], v[158:161], v[182:185], v[56:59]
	v_mfma_f32_16x16x32_bf16 v[44:47], v[150:153], v[190:193], v[44:47]
	v_mfma_f32_16x16x32_bf16 v[40:43], v[158:161], v[190:193], v[40:43]
	v_mfma_f32_16x16x32_bf16 v[28:31], v[150:153], v[198:201], v[28:31]
	v_mfma_f32_16x16x32_bf16 v[24:27], v[158:161], v[198:201], v[24:27]
	v_mfma_f32_16x16x32_bf16 v[12:15], v[150:153], v[210:213], v[12:15]
	v_mfma_f32_16x16x32_bf16 v[8:11], v[158:161], v[210:213], v[8:11]
	v_mfma_f32_16x16x32_bf16 v[52:55], v[162:165], v[178:181], v[52:55]
	v_mfma_f32_16x16x32_bf16 v[48:51], v[170:173], v[178:181], v[48:51]
	v_mfma_f32_16x16x32_bf16 v[36:39], v[162:165], v[186:189], v[36:39]
	v_mfma_f32_16x16x32_bf16 v[32:35], v[170:173], v[186:189], v[32:35]
	v_mfma_f32_16x16x32_bf16 v[20:23], v[162:165], v[194:197], v[20:23]
	v_mfma_f32_16x16x32_bf16 v[16:19], v[170:173], v[194:197], v[16:19]
	v_mfma_f32_16x16x32_bf16 v[4:7], v[162:165], v[206:209], v[4:7]
	v_mfma_f32_16x16x32_bf16 v[0:3], v[170:173], v[206:209], v[0:3]
	v_mfma_f32_16x16x32_bf16 v[52:55], v[166:169], v[182:185], v[52:55]
	v_mfma_f32_16x16x32_bf16 v[48:51], v[174:177], v[182:185], v[48:51]
	v_mfma_f32_16x16x32_bf16 v[36:39], v[166:169], v[190:193], v[36:39]
	v_mfma_f32_16x16x32_bf16 v[32:35], v[174:177], v[190:193], v[32:35]
	v_mfma_f32_16x16x32_bf16 v[20:23], v[166:169], v[198:201], v[20:23]
	v_mfma_f32_16x16x32_bf16 v[16:19], v[174:177], v[198:201], v[16:19]
	v_mfma_f32_16x16x32_bf16 v[4:7], v[166:169], v[210:213], v[4:7]
	v_mfma_f32_16x16x32_bf16 v[0:3], v[174:177], v[210:213], v[0:3]
	s_barrier
	s_add_i32 s66, 0, 0x18000
	s_add_i32 s67, 0, 0x1c000
	v_add_u32_e32 v158, s66, v144
	v_add_u32_e32 v174, s67, v144
	ds_read_b128 v[146:149], v158
	ds_read_b128 v[150:153], v158 offset:1024
	ds_read_b128 v[154:157], v158 offset:2048
	ds_read_b128 v[158:161], v158 offset:3072
	ds_read_b128 v[162:165], v174
	ds_read_b128 v[166:169], v174 offset:1024
	ds_read_b128 v[170:173], v174 offset:2048
	ds_read_b128 v[174:177], v174 offset:3072
	s_add_u32 s38, s38, 0xb0000
	s_addc_u32 s39, s39, 0
	s_mov_b32 m0, s49
	v_lshl_add_u64 v[222:223], s[38:39], 0, v[128:129]
	ds_read_b128 v[178:181], v145 offset:32768
	ds_read_b128 v[182:185], v145 offset:33792
	ds_read_b128 v[186:189], v145 offset:34816
	ds_read_b128 v[190:193], v145 offset:35840
	ds_read_b128 v[194:197], v145 offset:36864
	ds_read_b128 v[198:201], v145 offset:37888
	ds_read_b128 v[206:209], v145 offset:38912
	ds_read_b128 v[210:213], v145 offset:39936
	global_load_lds_dwordx4 v[222:223], off
	v_lshl_add_u64 v[222:223], s[38:39], 0, v[132:133]
	s_mov_b32 m0, s50
	s_nop 0
	global_load_lds_dwordx4 v[222:223], off
	s_waitcnt vmcnt(8)
	s_waitcnt lgkmcnt(0)
	s_barrier
	s_waitcnt lgkmcnt(0)
	v_mfma_f32_16x16x32_bf16 v[124:127], v[146:149], v[178:181], v[124:127]
	v_mfma_f32_16x16x32_bf16 v[120:123], v[154:157], v[178:181], v[120:123]
	v_mfma_f32_16x16x32_bf16 v[108:111], v[146:149], v[186:189], v[108:111]
	v_mfma_f32_16x16x32_bf16 v[104:107], v[154:157], v[186:189], v[104:107]
	v_mfma_f32_16x16x32_bf16 v[92:95], v[146:149], v[194:197], v[92:95]
	v_mfma_f32_16x16x32_bf16 v[88:91], v[154:157], v[194:197], v[88:91]
	v_mfma_f32_16x16x32_bf16 v[76:79], v[146:149], v[206:209], v[76:79]
	v_mfma_f32_16x16x32_bf16 v[72:75], v[154:157], v[206:209], v[72:75]
	v_mfma_f32_16x16x32_bf16 v[124:127], v[150:153], v[182:185], v[124:127]
	v_mfma_f32_16x16x32_bf16 v[120:123], v[158:161], v[182:185], v[120:123]
	v_mfma_f32_16x16x32_bf16 v[108:111], v[150:153], v[190:193], v[108:111]
	v_mfma_f32_16x16x32_bf16 v[104:107], v[158:161], v[190:193], v[104:107]
	v_mfma_f32_16x16x32_bf16 v[92:95], v[150:153], v[198:201], v[92:95]
	v_mfma_f32_16x16x32_bf16 v[88:91], v[158:161], v[198:201], v[88:91]
	v_mfma_f32_16x16x32_bf16 v[76:79], v[150:153], v[210:213], v[76:79]
	v_mfma_f32_16x16x32_bf16 v[72:75], v[158:161], v[210:213], v[72:75]
	v_mfma_f32_16x16x32_bf16 v[116:119], v[162:165], v[178:181], v[116:119]
	v_mfma_f32_16x16x32_bf16 v[112:115], v[170:173], v[178:181], v[112:115]
	v_mfma_f32_16x16x32_bf16 v[100:103], v[162:165], v[186:189], v[100:103]
	v_mfma_f32_16x16x32_bf16 v[96:99], v[170:173], v[186:189], v[96:99]
	v_mfma_f32_16x16x32_bf16 v[84:87], v[162:165], v[194:197], v[84:87]
	v_mfma_f32_16x16x32_bf16 v[80:83], v[170:173], v[194:197], v[80:83]
	v_mfma_f32_16x16x32_bf16 v[68:71], v[162:165], v[206:209], v[68:71]
	v_mfma_f32_16x16x32_bf16 v[64:67], v[170:173], v[206:209], v[64:67]
	v_mfma_f32_16x16x32_bf16 v[116:119], v[166:169], v[182:185], v[116:119]
	v_mfma_f32_16x16x32_bf16 v[112:115], v[174:177], v[182:185], v[112:115]
	v_mfma_f32_16x16x32_bf16 v[100:103], v[166:169], v[190:193], v[100:103]
	v_mfma_f32_16x16x32_bf16 v[96:99], v[174:177], v[190:193], v[96:99]
	v_mfma_f32_16x16x32_bf16 v[84:87], v[166:169], v[198:201], v[84:87]
	v_mfma_f32_16x16x32_bf16 v[80:83], v[174:177], v[198:201], v[80:83]
	v_mfma_f32_16x16x32_bf16 v[68:71], v[166:169], v[210:213], v[68:71]
	v_mfma_f32_16x16x32_bf16 v[64:67], v[174:177], v[210:213], v[64:67]
	s_barrier
; #define PG8_STAGE(bufoff, gbase, voff) do { _Pragma("unroll") for (int _i = 0; _i < 2; ++_i) \
;         __builtin_amdgcn_global_load_lds((const unsigned*)((const char*)(gbase) + (voff)[_i]), (LAS unsigned*)(lds + (bufoff) + ldsw + _i * 8192), 16, 0, 0); } while (0)
; #define PG8_LDA(dst, b, h) do { _Pragma("unroll") for (int m = 0; m < 4; ++m) _Pragma("unroll") for (int k = 0; k < 2; ++k) dst[m][k] = *(const LAS bf16x8*)(lds + PG8_SA(b, h) + aoff + m * 2048 + k * 1024); } while (0)
; #define PG8_MMA(ai, bj, At, Bt) do { __builtin_amdgcn_s_setprio(1); _Pragma("unroll") for (int m = 0; m < 4; ++m) _Pragma("unroll") for (int n = 0; n < 2; ++n) _Pragma("unroll") for (int k = 0; k < 2; ++k) \
;         acc[ai][bj][m][n] = __builtin_amdgcn_mfma_f32_16x16x32_bf16(Bt[n][k], At[m][k], acc[ai][bj][m][n], 0, 0, 0); __builtin_amdgcn_s_setprio(0); } while (0)
; #define PG8_WAIT_V(n) asm volatile("s_waitcnt vmcnt(" #n ")" ::: "memory")
; #define PG8_WAIT_L(n) asm volatile("s_waitcnt lgkmcnt(" #n ")" ::: "memory")
; #define PG8_BAR __builtin_amdgcn_s_barrier()
; #define PG8_SCHED __builtin_amdgcn_sched_barrier(0)
; template <class Epi>
; __device__ __forceinline__ void gemm_phase(LAS unsigned char* lds, const Gemm g, const Sched& S, const Epi& E) {
;     ...
;             PG8_LDA(At, 1, 1); PG8_STAGE(PG8_SB(1, 0), b3, voffB); PG8_STAGE(PG8_SB(1, 1), b3 + hstepB, voffB); PG8_STAGE(PG8_SA(1, 0), a3, voffA);
;             PG8_WAIT_V(8); PG8_WAIT_L(0); PG8_BAR; PG8_MMA(1, 0, At, B0); PG8_MMA(1, 1, At, B1); PG8_BAR; PG8_SCHED;
;         }
;         if (wr == 0) PG8_BAR;
	s_add_i32 s38, s66, s46
	v_lshl_add_u64 v[214:215], v[214:215], 0, s[16:17]
	s_mov_b32 m0, s38
	ds_read_b128 v[178:181], v145 offset:49152
	ds_read_b128 v[182:185], v145 offset:50176
	ds_read_b128 v[186:189], v145 offset:51200
	ds_read_b128 v[190:193], v145 offset:52224
	ds_read_b128 v[194:197], v145 offset:53248
	ds_read_b128 v[198:201], v145 offset:54272
	ds_read_b128 v[206:209], v145 offset:55296
	ds_read_b128 v[210:213], v145 offset:56320
	global_load_lds_dwordx4 v[214:215], off
	s_add_i32 m0, s38, 0x2000
	s_add_u32 s36, s36, 0xb0080
	v_lshl_add_u64 v[214:215], v[216:217], 0, s[16:17]
	s_addc_u32 s37, s37, 0
	s_add_i32 s38, s67, s46
	global_load_lds_dwordx4 v[214:215], off
	v_lshl_add_u64 v[214:215], s[36:37], 0, v[130:131]
	s_mov_b32 m0, s38
	s_nop 0
	global_load_lds_dwordx4 v[214:215], off
	v_lshl_add_u64 v[214:215], s[36:37], 0, v[134:135]
	s_add_i32 m0, s38, 0x2000
	s_nop 0
	global_load_lds_dwordx4 v[214:215], off
	v_lshl_add_u64 v[214:215], v[218:219], 0, s[16:17]
	s_mov_b32 m0, s52
	s_nop 0
	global_load_lds_dwordx4 v[214:215], off
	v_lshl_add_u64 v[214:215], v[220:221], 0, s[16:17]
	s_mov_b32 m0, s53
	s_nop 0
	global_load_lds_dwordx4 v[214:215], off
	s_waitcnt vmcnt(8)
	s_waitcnt lgkmcnt(0)
	s_barrier
	s_waitcnt lgkmcnt(0)
	v_mfma_f32_16x16x32_bf16 v[60:63], v[146:149], v[178:181], v[60:63]
	v_mfma_f32_16x16x32_bf16 v[56:59], v[154:157], v[178:181], v[56:59]
	v_mfma_f32_16x16x32_bf16 v[44:47], v[146:149], v[186:189], v[44:47]
	v_mfma_f32_16x16x32_bf16 v[40:43], v[154:157], v[186:189], v[40:43]
	v_mfma_f32_16x16x32_bf16 v[28:31], v[146:149], v[194:197], v[28:31]
	v_mfma_f32_16x16x32_bf16 v[24:27], v[154:157], v[194:197], v[24:27]
	v_mfma_f32_16x16x32_bf16 v[12:15], v[146:149], v[206:209], v[12:15]
	v_mfma_f32_16x16x32_bf16 v[8:11], v[154:157], v[206:209], v[8:11]
	v_mfma_f32_16x16x32_bf16 v[60:63], v[150:153], v[182:185], v[60:63]
	v_mfma_f32_16x16x32_bf16 v[56:59], v[158:161], v[182:185], v[56:59]
	v_mfma_f32_16x16x32_bf16 v[44:47], v[150:153], v[190:193], v[44:47]
	v_mfma_f32_16x16x32_bf16 v[40:43], v[158:161], v[190:193], v[40:43]
	v_mfma_f32_16x16x32_bf16 v[28:31], v[150:153], v[198:201], v[28:31]
	v_mfma_f32_16x16x32_bf16 v[24:27], v[158:161], v[198:201], v[24:27]
	v_mfma_f32_16x16x32_bf16 v[12:15], v[150:153], v[210:213], v[12:15]
	v_mfma_f32_16x16x32_bf16 v[8:11], v[158:161], v[210:213], v[8:11]
	v_mfma_f32_16x16x32_bf16 v[52:55], v[162:165], v[178:181], v[52:55]
	v_mfma_f32_16x16x32_bf16 v[48:51], v[170:173], v[178:181], v[48:51]
	v_mfma_f32_16x16x32_bf16 v[36:39], v[162:165], v[186:189], v[36:39]
	v_mfma_f32_16x16x32_bf16 v[32:35], v[170:173], v[186:189], v[32:35]
	v_mfma_f32_16x16x32_bf16 v[20:23], v[162:165], v[194:197], v[20:23]
	v_mfma_f32_16x16x32_bf16 v[16:19], v[170:173], v[194:197], v[16:19]
	v_mfma_f32_16x16x32_bf16 v[4:7], v[162:165], v[206:209], v[4:7]
	v_mfma_f32_16x16x32_bf16 v[0:3], v[170:173], v[206:209], v[0:3]
	v_mfma_f32_16x16x32_bf16 v[52:55], v[166:169], v[182:185], v[52:55]
	v_mfma_f32_16x16x32_bf16 v[48:51], v[174:177], v[182:185], v[48:51]
	v_mfma_f32_16x16x32_bf16 v[36:39], v[166:169], v[190:193], v[36:39]
	v_mfma_f32_16x16x32_bf16 v[32:35], v[174:177], v[190:193], v[32:35]
	v_mfma_f32_16x16x32_bf16 v[20:23], v[166:169], v[198:201], v[20:23]
	v_mfma_f32_16x16x32_bf16 v[16:19], v[174:177], v[198:201], v[16:19]
	v_mfma_f32_16x16x32_bf16 v[4:7], v[166:169], v[210:213], v[4:7]
	v_mfma_f32_16x16x32_bf16 v[0:3], v[174:177], v[210:213], v[0:3]
	s_barrier
	s_add_i32 s65, s65, 2
	s_add_u32 s28, s28, 0x100
	s_addc_u32 s29, s29, 0
	s_cmp_gt_u32 s65, 41
	s_cbranch_scc0 .LBB0_1827
	s_and_b64 vcc, exec, s[18:19]
	s_cbranch_vccz .LBB0_1830
	s_barrier
